# f32 IEEE division expansions in gate-sigmoid epilogues and mix-GEMM gate-ratio hook replaced by v_rcp_f32 (still f32); dead div chains removed
# speedup vs baseline: 1.0216x; 1.0130x over previous
; #define LAS __attribute__((address_space(3)))
; template <bool PASS2>
; __device__ __forceinline__ void lru_item(const Frame& F, const Args& a, int item) {
;     ...
;     for (int idx = F.tid; idx < 259 * 16; idx += 512) { const int row = idx >> 4, ch = idx & 15; const int t = t0 - 1 + row; u32x4 v = (u32x4){0u, 0u, 0u, 0u};
;         if (t >= 0 && t < SEQ) v = *(const u32x4*)(proj + (rowbase + t) * NIN + C_XB + n * 128 + 8 * ch);
;         *(LAS u32x4*)(R0 + row * AT_PITCH + 16 * ch) = v; }
.Lstg_p1a_0:
	s_or_b64 exec, exec, s[10:11]
	v_add_u32_e32 v8, 32, v8
	v_mov_b32_e32 v198, 0
	v_mov_b32_e32 v199, 0
	v_mov_b32_e32 v200, 0
	v_mov_b32_e32 v201, 0
	v_cmp_gt_u32_e32 vcc, s46, v8
	s_and_saveexec_b64 s[10:11], vcc
	v_or_b32_e32 v6, s6, v8
	v_mov_b64_e32 v[4:5], s[22:23]
	v_mad_u64_u32 v[4:5], s[14:15], v6, s47, v[4:5]
	v_mad_i32_i24 v5, s7, v118, v5
	v_lshl_add_u64 v[4:5], s[4:5], 1, v[4:5]
	v_lshl_add_u64 v[4:5], v[4:5], 0, v[94:95]
	v_add_co_u32_e32 v4, vcc, 0xe402000, v4
	s_nop 1
	v_addc_co_u32_e32 v5, vcc, 0, v5, vcc
	global_load_dwordx4 v[198:201], v[4:5], off offset:1024
	s_or_b64 exec, exec, s[10:11]
	v_add_u32_e32 v8, 32, v8
	v_mov_b32_e32 v202, 0
	v_mov_b32_e32 v203, 0
	v_mov_b32_e32 v204, 0
	v_mov_b32_e32 v205, 0
	v_cmp_gt_u32_e32 vcc, s46, v8
	s_and_saveexec_b64 s[10:11], vcc
	v_or_b32_e32 v6, s6, v8
	v_mov_b64_e32 v[4:5], s[22:23]
	v_mad_u64_u32 v[4:5], s[14:15], v6, s47, v[4:5]
	v_mad_i32_i24 v5, s7, v118, v5
	v_lshl_add_u64 v[4:5], s[4:5], 1, v[4:5]
	v_lshl_add_u64 v[4:5], v[4:5], 0, v[94:95]
	v_add_co_u32_e32 v4, vcc, 0xe402000, v4
	s_nop 1
	v_addc_co_u32_e32 v5, vcc, 0, v5, vcc
	global_load_dwordx4 v[202:205], v[4:5], off offset:1024
	s_or_b64 exec, exec, s[10:11]
	v_add_u32_e32 v8, 32, v8
	v_mov_b32_e32 v206, 0
	v_mov_b32_e32 v207, 0
	v_mov_b32_e32 v208, 0
	v_mov_b32_e32 v209, 0
	v_cmp_gt_u32_e32 vcc, s46, v8
	s_and_saveexec_b64 s[10:11], vcc
	v_or_b32_e32 v6, s6, v8
	v_mov_b64_e32 v[4:5], s[22:23]
	v_mad_u64_u32 v[4:5], s[14:15], v6, s47, v[4:5]
	v_mad_i32_i24 v5, s7, v118, v5
	v_lshl_add_u64 v[4:5], s[4:5], 1, v[4:5]
	v_lshl_add_u64 v[4:5], v[4:5], 0, v[94:95]
	v_add_co_u32_e32 v4, vcc, 0xe402000, v4
	s_nop 1
	v_addc_co_u32_e32 v5, vcc, 0, v5, vcc
	global_load_dwordx4 v[206:209], v[4:5], off offset:1024
	s_or_b64 exec, exec, s[10:11]
	v_add_u32_e32 v8, 32, v8
	v_mov_b32_e32 v210, 0
	v_mov_b32_e32 v211, 0
	v_mov_b32_e32 v212, 0
	v_mov_b32_e32 v213, 0
	v_cmp_gt_u32_e32 vcc, s46, v8
	s_and_saveexec_b64 s[10:11], vcc
	v_or_b32_e32 v6, s6, v8
	v_mov_b64_e32 v[4:5], s[22:23]
	v_mad_u64_u32 v[4:5], s[14:15], v6, s47, v[4:5]
	v_mad_i32_i24 v5, s7, v118, v5
	v_lshl_add_u64 v[4:5], s[4:5], 1, v[4:5]
	v_lshl_add_u64 v[4:5], v[4:5], 0, v[94:95]
	v_add_co_u32_e32 v4, vcc, 0xe402000, v4
	s_nop 1
	v_addc_co_u32_e32 v5, vcc, 0, v5, vcc
	global_load_dwordx4 v[210:213], v[4:5], off offset:1024
	s_or_b64 exec, exec, s[10:11]
	v_add_u32_e32 v8, 32, v8
	v_mov_b32_e32 v214, 0
	v_mov_b32_e32 v215, 0
	v_mov_b32_e32 v216, 0
	v_mov_b32_e32 v217, 0
	v_cmp_gt_u32_e32 vcc, s46, v8
	s_and_saveexec_b64 s[10:11], vcc
	v_or_b32_e32 v6, s6, v8
	v_mov_b64_e32 v[4:5], s[22:23]
	v_mad_u64_u32 v[4:5], s[14:15], v6, s47, v[4:5]
	v_mad_i32_i24 v5, s7, v118, v5
	v_lshl_add_u64 v[4:5], s[4:5], 1, v[4:5]
	v_lshl_add_u64 v[4:5], v[4:5], 0, v[94:95]
	v_add_co_u32_e32 v4, vcc, 0xe402000, v4
	s_nop 1
	v_addc_co_u32_e32 v5, vcc, 0, v5, vcc
	global_load_dwordx4 v[214:217], v[4:5], off offset:1024
	s_or_b64 exec, exec, s[10:11]
	v_add_u32_e32 v8, 32, v8
	v_mov_b32_e32 v218, 0
	v_mov_b32_e32 v219, 0
	v_mov_b32_e32 v220, 0
	v_mov_b32_e32 v221, 0
	v_cmp_gt_u32_e32 vcc, s46, v8
	s_and_saveexec_b64 s[10:11], vcc
	v_or_b32_e32 v6, s6, v8
	v_mov_b64_e32 v[4:5], s[22:23]
	v_mad_u64_u32 v[4:5], s[14:15], v6, s47, v[4:5]
	v_mad_i32_i24 v5, s7, v118, v5
	v_lshl_add_u64 v[4:5], s[4:5], 1, v[4:5]
	v_lshl_add_u64 v[4:5], v[4:5], 0, v[94:95]
	v_add_co_u32_e32 v4, vcc, 0xe402000, v4
	s_nop 1
	v_addc_co_u32_e32 v5, vcc, 0, v5, vcc
	global_load_dwordx4 v[218:221], v[4:5], off offset:1024
	s_or_b64 exec, exec, s[10:11]
	v_add_u32_e32 v8, 32, v8
	v_mov_b32_e32 v222, 0
	v_mov_b32_e32 v223, 0
	v_mov_b32_e32 v224, 0
	v_mov_b32_e32 v225, 0
	v_cmp_gt_u32_e32 vcc, s46, v8
	s_and_saveexec_b64 s[10:11], vcc
	v_or_b32_e32 v6, s6, v8
	v_mov_b64_e32 v[4:5], s[22:23]
	v_mad_u64_u32 v[4:5], s[14:15], v6, s47, v[4:5]
; #define LAS __attribute__((address_space(3)))
; template <bool PASS2>
; __device__ __forceinline__ void lru_item(const Frame& F, const Args& a, int item) {
;     ...
;     for (int idx = F.tid; idx < 259 * 16; idx += 512) { const int row = idx >> 4, ch = idx & 15; const int t = t0 - 1 + row; u32x4 v = (u32x4){0u, 0u, 0u, 0u};
;         if (t >= 0 && t < SEQ) v = *(const u32x4*)(proj + (rowbase + t) * NIN + C_XB + n * 128 + 8 * ch);
;         *(LAS u32x4*)(R0 + row * AT_PITCH + 16 * ch) = v; }
;     {
;         f32x4 cw[4][2], cbv[2];
; #pragma unroll
;         for (int j = 0; j < 4; ++j) { cw[j][0] = *(const f32x4*)(a.conv_w + j * 1536 + n * 128 + 8 * cch); cw[j][1] = *(const f32x4*)(a.conv_w + j * 1536 + n * 128 + 8 * cch + 4); }
;         cbv[0] = *(const f32x4*)(a.conv_b + n * 128 + 8 * cch); cbv[1] = *(const f32x4*)(a.conv_b + n * 128 + 8 * cch + 4);
;         u32x4 ybv[8];
;         if (PASS2) {
; #pragma unroll
;             for (int it = 0; it < 8; ++it) ybv[it] = *(const u32x4*)(proj + (rowbase + t0 + r0 + 32 * it) * NIN + C_YB + n * 128 + 8 * cch);
;         }
;         __syncthreads();
;     ...
;         const bf16_t* wt = (const bf16_t*)(a.ws + WS_WLRU) + (size_t)((dir * 12 + n) * 2) * 16384 + (size_t)c * 128 + 8 * fq;
;         bf16x8 wrf[4], wif[4];
; #pragma unroll
;         for (int ks = 0; ks < 4; ++ks) { wrf[ks] = *(const bf16x8*)(wt + 32 * ks); wif[ks] = *(const bf16x8*)(wt + 16384 + 32 * ks); }
;         const float ba = a.lru_ba[dir * 1536 + cg_], bi = a.lru_bi[dir * 1536 + cg_];
;         const float lam = a.lru_lambda[dir * 1536 + cg_];
	v_mad_i32_i24 v5, s7, v118, v5
	v_lshl_add_u64 v[4:5], s[4:5], 1, v[4:5]
	v_lshl_add_u64 v[4:5], v[4:5], 0, v[94:95]
	v_add_co_u32_e32 v4, vcc, 0xe402000, v4
	s_nop 1
	v_addc_co_u32_e32 v5, vcc, 0, v5, vcc
	global_load_dwordx4 v[222:225], v[4:5], off offset:1024
	s_or_b64 exec, exec, s[10:11]
	s_lshl_b64 s[6:7], s[4:5], 2
	v_lshl_add_u64 v[16:17], v[96:97], 0, s[6:7]
	v_add_co_u32_e32 v4, vcc, 0x1000, v16
	v_lshl_add_u64 v[8:9], v[16:17], 0, s[30:31]
	s_nop 0
	v_addc_co_u32_e32 v5, vcc, 0, v17, vcc
	v_add_co_u32_e32 v14, vcc, 0x3000, v16
	v_lshl_add_u64 v[12:13], v[16:17], 0, s[34:35]
	s_nop 0
	v_addc_co_u32_e32 v15, vcc, 0, v17, vcc
	global_load_dwordx4 v[36:39], v[16:17], off
	global_load_dwordx4 v[32:35], v[16:17], off offset:16
	s_nop 0
	global_load_dwordx4 v[4:7], v[4:5], off offset:2048
	s_nop 0
	global_load_dwordx4 v[8:11], v[8:9], off offset:16
	s_nop 0
	global_load_dwordx4 v[46:49], v[14:15], off
	global_load_dwordx4 v[40:43], v[12:13], off offset:16
	v_lshl_add_u64 v[12:13], v[16:17], 0, s[36:37]
	v_add_co_u32_e32 v16, vcc, 0x4000, v16
	global_load_dwordx4 v[12:15], v[12:13], off offset:16
	s_nop 0
	v_addc_co_u32_e32 v17, vcc, 0, v17, vcc
	global_load_dwordx4 v[16:19], v[16:17], off offset:2048
	v_lshl_add_u64 v[24:25], v[98:99], 0, s[6:7]
	global_load_dwordx4 v[20:23], v[24:25], off
	s_nop 0
	global_load_dwordx4 v[24:27], v[24:25], off offset:16
	s_mov_b32 s5, 0
	v_mov_b32_e32 v44, v115
	v_mov_b32_e32 v45, v108
	v_readlane_b32 s98, v242, 17
	v_readlane_b32 s99, v242, 18
	v_add_u32_e32 v248, s4, v92
	v_ashrrev_i32_e32 v249, 31, v248
	v_lshlrev_b64 v[248:249], 2, v[248:249]
	s_nop 1
	v_lshl_add_u64 v[250:251], s[98:99], 0, v[248:249]
	global_load_dword v178, v[250:251], off
	s_add_u32 s98, s98, 0x1800
	s_addc_u32 s99, s99, 0
	v_lshl_add_u64 v[250:251], s[98:99], 0, v[248:249]
	global_load_dword v142, v[250:251], off
	s_lshl_b32 s100, s13, 16
	s_mov_b32 s101, 0
	v_lshl_add_u64 v[250:251], v[102:103], 0, s[100:101]
	global_load_dwordx4 v[146:149], v[250:251], off
	global_load_dwordx4 v[150:153], v[250:251], off offset:64
	global_load_dwordx4 v[154:157], v[250:251], off offset:128
	global_load_dwordx4 v[158:161], v[250:251], off offset:192
	v_lshl_add_u64 v[252:253], s[86:87], 0, v[248:249]
	v_lshl_add_u64 v[254:255], s[90:91], 0, v[248:249]
	global_load_dword v179, v[252:253], off
	global_load_dword v180, v[254:255], off
	s_add_u32 s100, s100, 0x8000
	v_lshl_add_u64 v[250:251], v[102:103], 0, s[100:101]
	global_load_dwordx4 v[162:165], v[250:251], off
	global_load_dwordx4 v[166:169], v[250:251], off offset:64
	global_load_dwordx4 v[170:173], v[250:251], off offset:128
	global_load_dwordx4 v[174:177], v[250:251], off offset:192
	s_add_u32 s100, s100, 0xb8000
	v_lshl_add_u64 v[250:251], v[102:103], 0, s[100:101]
	global_load_dwordx4 v[182:185], v[250:251], off
	global_load_dwordx4 v[186:189], v[250:251], off offset:64
	global_load_dwordx4 v[230:233], v[250:251], off offset:128
	global_load_dwordx4 v[234:237], v[250:251], off offset:192
	s_add_u32 s98, s86, 0x1800
	s_addc_u32 s99, s87, 0
	v_lshl_add_u64 v[252:253], s[98:99], 0, v[248:249]
	s_add_u32 s98, s90, 0x1800
	s_addc_u32 s99, s91, 0
	v_lshl_add_u64 v[254:255], s[98:99], 0, v[248:249]
	global_load_dword v143, v[252:253], off
	global_load_dword v145, v[254:255], off
	s_add_u32 s100, s100, 0x8000
	v_lshl_add_u64 v[250:251], v[102:103], 0, s[100:101]
	global_load_dwordx4 v[238:241], v[250:251], off
	global_load_dwordx4 v[134:137], v[250:251], off offset:64
	global_load_dwordx4 v[138:141], v[250:251], off offset:128
	global_load_dwordx4 v[244:247], v[250:251], off offset:192
	v_cmp_gt_u32_e64 s[98:99], 48, v144
	v_add_u32_e32 v193, 0x2200, v113
	s_waitcnt vmcnt(38)
	s_and_saveexec_b64 s[100:101], s[98:99]
	s_cbranch_execz .Lstg_p1a_w8
	ds_write_b128 v193, v[226:229] offset:60928

; __device__ __forceinline__ float sigmoidf_(float x) { return 1.0f / (1.0f + __expf(-x)); }
;     __device__ __forceinline__ void operator()(const f32x4 (&acc)[2][2][4][2], const Unit& u, int wr, int wc, int fr, int fq) const {
;         const int row0 = u.pm * BM + wr * 64 + fr; const int col0 = u.pn * BM + wc * 32 + 8 * fq;
;         f32x4 bv[2][2];
; #pragma unroll
;         for (int bj = 0; bj < 2; ++bj)
; #pragma unroll
;             for (int n = 0; n < 2; ++n) bv[bj][n] = *(const f32x4*)(bias + col0 + bj * HALF + 4 * n);
; #pragma unroll
;         for (int ai = 0; ai < 2; ++ai)
; #pragma unroll
;             for (int m = 0; m < 4; ++m) { unsigned char* rowp = O + (size_t)(row0 + ai * HALF + m * 16) * GP8 + col0;
; #pragma unroll
;                 for (int bj = 0; bj < 2; ++bj) { const f32x4 v0 = acc[ai][bj][m][0] + bv[bj][0], v1 = acc[ai][bj][m][1] + bv[bj][1];
;                     unsigned q[8];
; #pragma unroll
;                     for (int j = 0; j < 4; ++j) { q[j] = (unsigned)fmaxf(__builtin_rintf(sigmoidf_(v0[j]) * 255.f), 1.f); q[4 + j] = (unsigned)fmaxf(__builtin_rintf(sigmoidf_(v1[j]) * 255.f), 1.f); }
;                     u32x2 w; w.x = q[0] | (q[1] << 8) | (q[2] << 16) | (q[3] << 24); w.y = q[4] | (q[5] << 8) | (q[6] << 16) | (q[7] << 24);
;                     *(u32x2*)(rowp + bj * HALF) = w; } }
.LBB0_793:
	v_lshl_or_b32 v162, s9, 8, v169
	v_ashrrev_i32_e32 v163, 31, v162
	v_lshl_add_u64 v[36:37], v[162:163], 2, s[78:79]
	global_load_dwordx4 v[52:55], v[36:37], off
	global_load_dwordx4 v[48:51], v[36:37], off offset:16
	v_lshl_add_u32 v173, s8, 8, v145
	v_mov_b64_e32 v[164:165], s[12:13]
	v_mad_i64_i32 v[32:33], s[2:3], v173, s55, v[164:165]
	v_lshl_add_u64 v[166:167], v[32:33], 0, v[162:163]
	global_load_dwordx4 v[32:35], v[36:37], off offset:528
	s_nop 0
	global_load_dwordx4 v[36:39], v[36:37], off offset:512
	s_waitcnt vmcnt(0)
	v_add_f32_e32 v140, v140, v52
	v_add_f32_e32 v136, v136, v48
	v_mul_f32_e32 v140, 0xbfb8aa3b, v140
	v_add_f32_e32 v141, v141, v53
	v_add_f32_e32 v142, v142, v54
	v_mul_f32_e32 v136, 0xbfb8aa3b, v136
	v_exp_f32_e32 v140, v140
	v_mul_f32_e32 v141, 0xbfb8aa3b, v141
	v_mul_f32_e32 v142, 0xbfb8aa3b, v142
	v_exp_f32_e32 v136, v136
	v_exp_f32_e32 v141, v141
	v_exp_f32_e32 v142, v142
	v_add_f32_e32 v137, v137, v49
	v_mul_f32_e32 v137, 0xbfb8aa3b, v137
	v_add_f32_e32 v140, 1.0, v140
	v_exp_f32_e32 v137, v137
	v_add_f32_e32 v136, 1.0, v136
	v_add_f32_e32 v141, 1.0, v141
	v_add_f32_e32 v142, 1.0, v142
	v_add_f32_e32 v137, 1.0, v137
	v_rcp_f32_e32 v140, v140
	v_rcp_f32_e32 v136, v136
	s_nop 0
	v_mul_f32_e32 v136, 0x437f0000, v136
	v_rcp_f32_e32 v141, v141
	v_rndne_f32_e32 v136, v136
	v_mul_f32_e32 v141, 0x437f0000, v141
	v_max_f32_e32 v136, 1.0, v136
	v_rndne_f32_e32 v141, v141
	v_add_f32_e32 v138, v138, v50
	v_rcp_f32_e32 v137, v137
	v_cvt_u32_f32_e32 v174, v136
	v_max_f32_e32 v136, 1.0, v141
	v_mul_f32_e32 v138, 0xbfb8aa3b, v138
	v_exp_f32_e32 v138, v138
	s_nop 0
	v_add_f32_e32 v138, 1.0, v138
	v_rcp_f32_e32 v141, v142
	v_add_f32_e32 v143, v143, v55
	v_mul_f32_e32 v143, 0xbfb8aa3b, v143
	v_exp_f32_e32 v143, v143
	v_rcp_f32_e32 v138, v138
	v_add_f32_e32 v142, 1.0, v143
	v_add_f32_e32 v139, v139, v51
	v_mul_f32_e32 v139, 0xbfb8aa3b, v139
	v_exp_f32_e32 v139, v139
	s_nop 0
	v_add_f32_e32 v139, 1.0, v139
	v_rcp_f32_e32 v142, v142
	v_mul_f32_e32 v140, 0x437f0000, v140
	v_add_f32_e32 v132, v132, v36
	v_rndne_f32_e32 v140, v140
	v_mul_f32_e32 v141, 0x437f0000, v141
	v_mul_f32_e32 v142, 0x437f0000, v142
	v_mul_f32_e32 v132, 0xbfb8aa3b, v132
	v_max_f32_e32 v140, 1.0, v140
	v_rndne_f32_e32 v141, v141
	v_rndne_f32_e32 v142, v142
	v_exp_f32_e32 v132, v132
	v_cvt_u32_f32_e32 v140, v140
	v_mul_f32_e32 v137, 0x437f0000, v137
	v_cvt_u32_f32_e32 v136, v136
	v_max_f32_e32 v141, 1.0, v141
	v_max_f32_e32 v142, 1.0, v142
	v_rcp_f32_e32 v139, v139
	v_rndne_f32_e32 v137, v137
	v_cvt_u32_f32_sdwa v141, v141 dst_sel:WORD_1 dst_unused:UNUSED_PAD src0_sel:DWORD
	v_mul_f32_e32 v138, 0x437f0000, v138
	v_cvt_u32_f32_sdwa v142, v142 dst_sel:BYTE_3 dst_unused:UNUSED_PAD src0_sel:DWORD
	v_mul_f32_e32 v139, 0x437f0000, v139
	v_max_f32_e32 v137, 1.0, v137
	v_rndne_f32_e32 v138, v138
	v_rndne_f32_e32 v139, v139
	v_cvt_u32_f32_e32 v137, v137
	v_max_f32_e32 v138, 1.0, v138
	v_max_f32_e32 v139, 1.0, v139
	v_add_f32_e32 v132, 1.0, v132
	v_cvt_u32_f32_sdwa v138, v138 dst_sel:WORD_1 dst_unused:UNUSED_PAD src0_sel:DWORD
	v_cvt_u32_f32_sdwa v139, v139 dst_sel:BYTE_3 dst_unused:UNUSED_PAD src0_sel:DWORD
	v_lshl_or_b32 v136, v136, 8, v140
	v_or3_b32 v136, v136, v141, v142
	v_lshl_or_b32 v137, v137, 8, v174
	v_or3_b32 v137, v137, v138, v139
	global_store_dwordx2 v[166:167], v[136:137], off
	v_add_f32_e32 v128, v128, v32
	v_mul_f32_e32 v128, 0xbfb8aa3b, v128
	v_exp_f32_e32 v128, v128
	s_nop 0
	v_add_f32_e32 v128, 1.0, v128
	v_rcp_f32_e32 v132, v132
	v_add_f32_e32 v133, v133, v37
	v_mul_f32_e32 v133, 0xbfb8aa3b, v133
	v_exp_f32_e32 v133, v133
	s_nop 0
	v_add_f32_e32 v133, 1.0, v133
	v_rcp_f32_e32 v128, v128
	s_nop 0
	v_mul_f32_e32 v128, 0x437f0000, v128
	v_rndne_f32_e32 v128, v128
	v_max_f32_e32 v128, 1.0, v128
	v_cvt_u32_f32_e32 v138, v128
	v_add_f32_e32 v129, v129, v33
	v_mul_f32_e32 v129, 0xbfb8aa3b, v129
	v_exp_f32_e32 v129, v129
	s_nop 0
	v_add_f32_e32 v129, 1.0, v129
	v_rcp_f32_e32 v128, v133
	v_add_f32_e32 v134, v134, v38
	v_mul_f32_e32 v134, 0xbfb8aa3b, v134
	v_exp_f32_e32 v134, v134
	v_rcp_f32_e32 v129, v129
	v_add_f32_e32 v133, 1.0, v134
	v_add_f32_e32 v130, v130, v34
	v_mul_f32_e32 v130, 0xbfb8aa3b, v130
	v_exp_f32_e32 v130, v130
	s_nop 0
	v_add_f32_e32 v130, 1.0, v130
	v_rcp_f32_e32 v133, v133
	v_add_f32_e32 v135, v135, v39
	v_mul_f32_e32 v135, 0xbfb8aa3b, v135
	v_exp_f32_e32 v135, v135
	v_rcp_f32_e32 v130, v130
	v_add_f32_e32 v134, 1.0, v135
	v_add_f32_e32 v131, v131, v35
	v_mul_f32_e32 v131, 0xbfb8aa3b, v131
	v_exp_f32_e32 v131, v131
	s_nop 0
	v_add_f32_e32 v131, 1.0, v131
	v_rcp_f32_e32 v134, v134
	v_mul_f32_e32 v129, 0x437f0000, v129
	v_rndne_f32_e32 v129, v129
	v_mul_f32_e32 v130, 0x437f0000, v130
	v_rcp_f32_e32 v131, v131
	s_nop 0
	v_mul_f32_e32 v131, 0x437f0000, v131
	v_add_f32_e32 v124, v124, v52
	v_max_f32_e32 v129, 1.0, v129
	v_rndne_f32_e32 v130, v130
	v_rndne_f32_e32 v131, v131
	v_mul_f32_e32 v124, 0xbfb8aa3b, v124
	v_cvt_u32_f32_e32 v129, v129
	v_max_f32_e32 v130, 1.0, v130
	v_max_f32_e32 v131, 1.0, v131
	v_exp_f32_e32 v124, v124
	v_cvt_u32_f32_sdwa v130, v130 dst_sel:WORD_1 dst_unused:UNUSED_PAD src0_sel:DWORD
	v_cvt_u32_f32_sdwa v131, v131 dst_sel:BYTE_3 dst_unused:UNUSED_PAD src0_sel:DWORD
	v_mul_f32_e32 v132, 0x437f0000, v132
	v_mul_f32_e32 v128, 0x437f0000, v128
	v_rndne_f32_e32 v132, v132
	v_rndne_f32_e32 v128, v128
	v_lshl_or_b32 v129, v129, 8, v138
	v_add_f32_e32 v124, 1.0, v124
	v_max_f32_e32 v132, 1.0, v132
	v_max_f32_e32 v128, 1.0, v128
	v_mul_f32_e32 v133, 0x437f0000, v133
	v_mul_f32_e32 v134, 0x437f0000, v134
	v_or3_b32 v129, v129, v130, v131
	v_cvt_u32_f32_e32 v132, v132
	v_cvt_u32_f32_e32 v128, v128
	v_rndne_f32_e32 v133, v133
; __device__ __forceinline__ float sigmoidf_(float x) { return 1.0f / (1.0f + __expf(-x)); }
;     __device__ __forceinline__ void operator()(const f32x4 (&acc)[2][2][4][2], const Unit& u, int wr, int wc, int fr, int fq) const {
;     ...
;                 for (int bj = 0; bj < 2; ++bj) { const f32x4 v0 = acc[ai][bj][m][0] + bv[bj][0], v1 = acc[ai][bj][m][1] + bv[bj][1];
;                     unsigned q[8];
; #pragma unroll
;                     for (int j = 0; j < 4; ++j) { q[j] = (unsigned)fmaxf(__builtin_rintf(sigmoidf_(v0[j]) * 255.f), 1.f); q[4 + j] = (unsigned)fmaxf(__builtin_rintf(sigmoidf_(v1[j]) * 255.f), 1.f); }
;                     u32x2 w; w.x = q[0] | (q[1] << 8) | (q[2] << 16) | (q[3] << 24); w.y = q[4] | (q[5] << 8) | (q[6] << 16) | (q[7] << 24);
;                     *(u32x2*)(rowp + bj * HALF) = w; } }
	v_rndne_f32_e32 v134, v134
	v_max_f32_e32 v133, 1.0, v133
	v_max_f32_e32 v134, 1.0, v134
	v_cvt_u32_f32_sdwa v133, v133 dst_sel:WORD_1 dst_unused:UNUSED_PAD src0_sel:DWORD
	v_cvt_u32_f32_sdwa v134, v134 dst_sel:BYTE_3 dst_unused:UNUSED_PAD src0_sel:DWORD
	v_lshl_or_b32 v128, v128, 8, v132
	v_add_f32_e32 v120, v120, v48
	v_mul_f32_e32 v120, 0xbfb8aa3b, v120
	v_or3_b32 v128, v128, v133, v134
	v_exp_f32_e32 v120, v120
	s_nop 0
	v_add_f32_e32 v120, 1.0, v120
	v_rcp_f32_e32 v124, v124
	v_add_f32_e32 v125, v125, v53
	v_mul_f32_e32 v125, 0xbfb8aa3b, v125
	v_exp_f32_e32 v125, v125
	s_nop 0
	v_add_f32_e32 v125, 1.0, v125
	v_rcp_f32_e32 v120, v120
	s_nop 0
	v_mul_f32_e32 v120, 0x437f0000, v120
	v_rndne_f32_e32 v120, v120
	v_max_f32_e32 v120, 1.0, v120
	v_cvt_u32_f32_e32 v132, v120
	v_add_f32_e32 v121, v121, v49
	v_mul_f32_e32 v121, 0xbfb8aa3b, v121
	v_exp_f32_e32 v121, v121
	s_nop 0
	v_add_f32_e32 v121, 1.0, v121
	v_rcp_f32_e32 v120, v125
	v_add_f32_e32 v126, v126, v54
	v_mul_f32_e32 v126, 0xbfb8aa3b, v126
	v_exp_f32_e32 v126, v126
	v_rcp_f32_e32 v121, v121
	v_add_f32_e32 v125, 1.0, v126
	v_add_f32_e32 v122, v122, v50
	v_mul_f32_e32 v122, 0xbfb8aa3b, v122
	v_exp_f32_e32 v122, v122
	s_nop 0
	v_add_f32_e32 v122, 1.0, v122
	v_rcp_f32_e32 v125, v125
	v_add_f32_e32 v127, v127, v55
	v_mul_f32_e32 v127, 0xbfb8aa3b, v127
	v_exp_f32_e32 v127, v127
	v_rcp_f32_e32 v122, v122
	v_add_f32_e32 v126, 1.0, v127
	v_add_f32_e32 v123, v123, v51
	v_mul_f32_e32 v123, 0xbfb8aa3b, v123
	v_exp_f32_e32 v123, v123
	s_nop 0
	v_add_f32_e32 v123, 1.0, v123
	v_rcp_f32_e32 v126, v126
	v_mul_f32_e32 v124, 0x437f0000, v124
	v_mul_f32_e32 v120, 0x437f0000, v120
	v_add_f32_e32 v116, v116, v36
	v_rndne_f32_e32 v124, v124
	v_rndne_f32_e32 v120, v120
	v_mul_f32_e32 v125, 0x437f0000, v125
	v_mul_f32_e32 v126, 0x437f0000, v126
	v_mul_f32_e32 v116, 0xbfb8aa3b, v116
	v_max_f32_e32 v124, 1.0, v124
	v_max_f32_e32 v120, 1.0, v120
	v_rndne_f32_e32 v125, v125
	v_rndne_f32_e32 v126, v126
	v_exp_f32_e32 v116, v116
	v_cvt_u32_f32_e32 v124, v124
	v_cvt_u32_f32_e32 v120, v120
	v_mul_f32_e32 v121, 0x437f0000, v121
	v_max_f32_e32 v125, 1.0, v125
	v_max_f32_e32 v126, 1.0, v126
	v_rcp_f32_e32 v123, v123
	v_rndne_f32_e32 v121, v121
	v_cvt_u32_f32_sdwa v125, v125 dst_sel:WORD_1 dst_unused:UNUSED_PAD src0_sel:DWORD
	v_mul_f32_e32 v122, 0x437f0000, v122
	v_cvt_u32_f32_sdwa v126, v126 dst_sel:BYTE_3 dst_unused:UNUSED_PAD src0_sel:DWORD
	v_mul_f32_e32 v123, 0x437f0000, v123
	v_max_f32_e32 v121, 1.0, v121
	v_rndne_f32_e32 v122, v122
	v_rndne_f32_e32 v123, v123
	v_cvt_u32_f32_e32 v121, v121
	v_max_f32_e32 v122, 1.0, v122
	v_max_f32_e32 v123, 1.0, v123
	v_add_f32_e32 v116, 1.0, v116
	v_cvt_u32_f32_sdwa v122, v122 dst_sel:WORD_1 dst_unused:UNUSED_PAD src0_sel:DWORD
	v_cvt_u32_f32_sdwa v123, v123 dst_sel:BYTE_3 dst_unused:UNUSED_PAD src0_sel:DWORD
	v_lshl_or_b32 v120, v120, 8, v124
	v_or3_b32 v120, v120, v125, v126
	global_store_dwordx2 v[166:167], v[128:129], off offset:128
	v_or_b32_e32 v128, 16, v173
	v_mad_i64_i32 v[128:129], s[2:3], v128, s55, v[164:165]
	v_lshl_or_b32 v121, v121, 8, v132
	v_lshl_add_u64 v[128:129], v[128:129], 0, v[162:163]
	v_or3_b32 v121, v121, v122, v123
	global_store_dwordx2 v[128:129], v[120:121], off
	v_add_f32_e32 v112, v112, v32
	v_mul_f32_e32 v112, 0xbfb8aa3b, v112
	v_exp_f32_e32 v112, v112
	s_nop 0
	v_add_f32_e32 v112, 1.0, v112
	v_rcp_f32_e32 v116, v116
	v_add_f32_e32 v117, v117, v37
	v_mul_f32_e32 v117, 0xbfb8aa3b, v117
	v_exp_f32_e32 v117, v117
	s_nop 0
	v_add_f32_e32 v117, 1.0, v117
	v_rcp_f32_e32 v112, v112
	s_nop 0
	v_mul_f32_e32 v112, 0x437f0000, v112
	v_rndne_f32_e32 v112, v112
	v_max_f32_e32 v112, 1.0, v112
	v_cvt_u32_f32_e32 v122, v112
	v_add_f32_e32 v113, v113, v33
	v_mul_f32_e32 v113, 0xbfb8aa3b, v113
	v_exp_f32_e32 v113, v113
	s_nop 0
	v_add_f32_e32 v113, 1.0, v113
	v_rcp_f32_e32 v112, v117
	v_add_f32_e32 v118, v118, v38
	v_mul_f32_e32 v118, 0xbfb8aa3b, v118
	v_exp_f32_e32 v118, v118
	v_rcp_f32_e32 v113, v113
	v_add_f32_e32 v117, 1.0, v118
	v_add_f32_e32 v114, v114, v34
	v_mul_f32_e32 v114, 0xbfb8aa3b, v114
	v_exp_f32_e32 v114, v114
	s_nop 0
	v_add_f32_e32 v114, 1.0, v114
	v_rcp_f32_e32 v117, v117
	v_add_f32_e32 v119, v119, v39
	v_mul_f32_e32 v119, 0xbfb8aa3b, v119
	v_exp_f32_e32 v119, v119
	v_rcp_f32_e32 v114, v114
	v_add_f32_e32 v118, 1.0, v119
	v_add_f32_e32 v115, v115, v35
	v_mul_f32_e32 v115, 0xbfb8aa3b, v115
	v_exp_f32_e32 v115, v115
	s_nop 0
	v_add_f32_e32 v115, 1.0, v115
	v_rcp_f32_e32 v118, v118
	v_mul_f32_e32 v113, 0x437f0000, v113
	v_rndne_f32_e32 v113, v113
	v_mul_f32_e32 v114, 0x437f0000, v114
	v_rcp_f32_e32 v115, v115
	s_nop 0
	v_mul_f32_e32 v115, 0x437f0000, v115
	v_add_f32_e32 v108, v108, v52
	v_max_f32_e32 v113, 1.0, v113
	v_rndne_f32_e32 v114, v114
	v_rndne_f32_e32 v115, v115
	v_mul_f32_e32 v108, 0xbfb8aa3b, v108
	v_cvt_u32_f32_e32 v113, v113
	v_max_f32_e32 v114, 1.0, v114
	v_max_f32_e32 v115, 1.0, v115
	v_exp_f32_e32 v108, v108
	v_cvt_u32_f32_sdwa v114, v114 dst_sel:WORD_1 dst_unused:UNUSED_PAD src0_sel:DWORD
	v_cvt_u32_f32_sdwa v115, v115 dst_sel:BYTE_3 dst_unused:UNUSED_PAD src0_sel:DWORD
	v_mul_f32_e32 v116, 0x437f0000, v116
	v_mul_f32_e32 v112, 0x437f0000, v112
	v_rndne_f32_e32 v116, v116
	v_rndne_f32_e32 v112, v112
	v_lshl_or_b32 v113, v113, 8, v122
	v_add_f32_e32 v108, 1.0, v108
	v_max_f32_e32 v116, 1.0, v116
	v_max_f32_e32 v112, 1.0, v112
	v_mul_f32_e32 v117, 0x437f0000, v117
	v_mul_f32_e32 v118, 0x437f0000, v118
	v_or3_b32 v113, v113, v114, v115
	v_cvt_u32_f32_e32 v116, v116
	v_cvt_u32_f32_e32 v112, v112
	v_rndne_f32_e32 v117, v117
	v_rndne_f32_e32 v118, v118
	v_max_f32_e32 v117, 1.0, v117
	v_max_f32_e32 v118, 1.0, v118
; __device__ __forceinline__ float sigmoidf_(float x) { return 1.0f / (1.0f + __expf(-x)); }
;     __device__ __forceinline__ void operator()(const f32x4 (&acc)[2][2][4][2], const Unit& u, int wr, int wc, int fr, int fq) const {
;     ...
;             for (int m = 0; m < 4; ++m) { unsigned char* rowp = O + (size_t)(row0 + ai * HALF + m * 16) * GP8 + col0;
; #pragma unroll
;                 for (int bj = 0; bj < 2; ++bj) { const f32x4 v0 = acc[ai][bj][m][0] + bv[bj][0], v1 = acc[ai][bj][m][1] + bv[bj][1];
;                     unsigned q[8];
; #pragma unroll
;                     for (int j = 0; j < 4; ++j) { q[j] = (unsigned)fmaxf(__builtin_rintf(sigmoidf_(v0[j]) * 255.f), 1.f); q[4 + j] = (unsigned)fmaxf(__builtin_rintf(sigmoidf_(v1[j]) * 255.f), 1.f); }
;                     u32x2 w; w.x = q[0] | (q[1] << 8) | (q[2] << 16) | (q[3] << 24); w.y = q[4] | (q[5] << 8) | (q[6] << 16) | (q[7] << 24);
;                     *(u32x2*)(rowp + bj * HALF) = w; } }
	v_cvt_u32_f32_sdwa v117, v117 dst_sel:WORD_1 dst_unused:UNUSED_PAD src0_sel:DWORD
	v_cvt_u32_f32_sdwa v118, v118 dst_sel:BYTE_3 dst_unused:UNUSED_PAD src0_sel:DWORD
	v_lshl_or_b32 v112, v112, 8, v116
	v_add_f32_e32 v104, v104, v48
	v_mul_f32_e32 v104, 0xbfb8aa3b, v104
	v_or3_b32 v112, v112, v117, v118
	v_exp_f32_e32 v104, v104
	s_nop 0
	v_add_f32_e32 v104, 1.0, v104
	v_rcp_f32_e32 v108, v108
	v_add_f32_e32 v109, v109, v53
	v_mul_f32_e32 v109, 0xbfb8aa3b, v109
	v_exp_f32_e32 v109, v109
	s_nop 0
	v_add_f32_e32 v109, 1.0, v109
	v_rcp_f32_e32 v104, v104
	s_nop 0
	v_mul_f32_e32 v104, 0x437f0000, v104
	v_rndne_f32_e32 v104, v104
	v_max_f32_e32 v104, 1.0, v104
	v_cvt_u32_f32_e32 v116, v104
	v_add_f32_e32 v105, v105, v49
	v_mul_f32_e32 v105, 0xbfb8aa3b, v105
	v_exp_f32_e32 v105, v105
	s_nop 0
	v_add_f32_e32 v105, 1.0, v105
	v_rcp_f32_e32 v104, v109
	v_add_f32_e32 v110, v110, v54
	v_mul_f32_e32 v110, 0xbfb8aa3b, v110
	v_exp_f32_e32 v110, v110
	v_rcp_f32_e32 v105, v105
	v_add_f32_e32 v109, 1.0, v110
	v_add_f32_e32 v106, v106, v50
	v_mul_f32_e32 v106, 0xbfb8aa3b, v106
	v_exp_f32_e32 v106, v106
	s_nop 0
	v_add_f32_e32 v106, 1.0, v106
	v_rcp_f32_e32 v109, v109
	v_add_f32_e32 v111, v111, v55
	v_mul_f32_e32 v111, 0xbfb8aa3b, v111
	v_exp_f32_e32 v111, v111
	v_rcp_f32_e32 v106, v106
	v_add_f32_e32 v110, 1.0, v111
	v_add_f32_e32 v107, v107, v51
	v_mul_f32_e32 v107, 0xbfb8aa3b, v107
	v_exp_f32_e32 v107, v107
	s_nop 0
	v_add_f32_e32 v107, 1.0, v107
	v_rcp_f32_e32 v110, v110
	v_mul_f32_e32 v108, 0x437f0000, v108
	v_mul_f32_e32 v104, 0x437f0000, v104
	v_add_f32_e32 v100, v100, v36
	v_rndne_f32_e32 v108, v108
	v_rndne_f32_e32 v104, v104
	v_mul_f32_e32 v109, 0x437f0000, v109
	v_mul_f32_e32 v110, 0x437f0000, v110
	v_mul_f32_e32 v100, 0xbfb8aa3b, v100
	v_max_f32_e32 v108, 1.0, v108
	v_max_f32_e32 v104, 1.0, v104
	v_rndne_f32_e32 v109, v109
	v_rndne_f32_e32 v110, v110
	v_exp_f32_e32 v100, v100
	v_cvt_u32_f32_e32 v108, v108
	v_cvt_u32_f32_e32 v104, v104
	v_mul_f32_e32 v105, 0x437f0000, v105
	v_max_f32_e32 v109, 1.0, v109
	v_max_f32_e32 v110, 1.0, v110
	v_rcp_f32_e32 v107, v107
	v_rndne_f32_e32 v105, v105
	v_cvt_u32_f32_sdwa v109, v109 dst_sel:WORD_1 dst_unused:UNUSED_PAD src0_sel:DWORD
	v_mul_f32_e32 v106, 0x437f0000, v106
	v_cvt_u32_f32_sdwa v110, v110 dst_sel:BYTE_3 dst_unused:UNUSED_PAD src0_sel:DWORD
	v_mul_f32_e32 v107, 0x437f0000, v107
	v_max_f32_e32 v105, 1.0, v105
	v_rndne_f32_e32 v106, v106
	v_rndne_f32_e32 v107, v107
	v_cvt_u32_f32_e32 v105, v105
	v_max_f32_e32 v106, 1.0, v106
	v_max_f32_e32 v107, 1.0, v107
	v_add_f32_e32 v100, 1.0, v100
	v_cvt_u32_f32_sdwa v106, v106 dst_sel:WORD_1 dst_unused:UNUSED_PAD src0_sel:DWORD
	v_cvt_u32_f32_sdwa v107, v107 dst_sel:BYTE_3 dst_unused:UNUSED_PAD src0_sel:DWORD
	v_lshl_or_b32 v104, v104, 8, v108
	v_or3_b32 v104, v104, v109, v110
	global_store_dwordx2 v[128:129], v[112:113], off offset:128
	v_or_b32_e32 v112, 32, v173
	v_mad_i64_i32 v[112:113], s[2:3], v112, s55, v[164:165]
	v_lshl_or_b32 v105, v105, 8, v116
	v_lshl_add_u64 v[112:113], v[112:113], 0, v[162:163]
	v_or3_b32 v105, v105, v106, v107
	global_store_dwordx2 v[112:113], v[104:105], off
	v_add_f32_e32 v96, v96, v32
	v_mul_f32_e32 v96, 0xbfb8aa3b, v96
	v_exp_f32_e32 v96, v96
	s_nop 0
	v_add_f32_e32 v96, 1.0, v96
	v_rcp_f32_e32 v100, v100
	v_add_f32_e32 v101, v101, v37
	v_mul_f32_e32 v101, 0xbfb8aa3b, v101
	v_exp_f32_e32 v101, v101
	s_nop 0
	v_add_f32_e32 v101, 1.0, v101
	v_rcp_f32_e32 v96, v96
	s_nop 0
	v_mul_f32_e32 v96, 0x437f0000, v96
	v_rndne_f32_e32 v96, v96
	v_max_f32_e32 v96, 1.0, v96
	v_cvt_u32_f32_e32 v106, v96
	v_add_f32_e32 v97, v97, v33
	v_mul_f32_e32 v97, 0xbfb8aa3b, v97
	v_exp_f32_e32 v97, v97
	s_nop 0
	v_add_f32_e32 v97, 1.0, v97
	v_rcp_f32_e32 v96, v101
	v_add_f32_e32 v102, v102, v38
	v_mul_f32_e32 v102, 0xbfb8aa3b, v102
	v_exp_f32_e32 v102, v102
	v_rcp_f32_e32 v97, v97
	v_add_f32_e32 v101, 1.0, v102
	v_add_f32_e32 v98, v98, v34
	v_mul_f32_e32 v98, 0xbfb8aa3b, v98
	v_exp_f32_e32 v98, v98
	s_nop 0
	v_add_f32_e32 v98, 1.0, v98
	v_rcp_f32_e32 v101, v101
	v_add_f32_e32 v103, v103, v39
	v_mul_f32_e32 v103, 0xbfb8aa3b, v103
	v_exp_f32_e32 v103, v103
	v_rcp_f32_e32 v98, v98
	v_add_f32_e32 v102, 1.0, v103
	v_add_f32_e32 v99, v99, v35
	v_mul_f32_e32 v99, 0xbfb8aa3b, v99
	v_exp_f32_e32 v99, v99
	s_nop 0
	v_add_f32_e32 v99, 1.0, v99
	v_rcp_f32_e32 v102, v102
	v_mul_f32_e32 v97, 0x437f0000, v97
	v_rndne_f32_e32 v97, v97
	v_mul_f32_e32 v98, 0x437f0000, v98
	v_rcp_f32_e32 v99, v99
	s_nop 0
	v_mul_f32_e32 v99, 0x437f0000, v99
	v_add_f32_e32 v92, v92, v52
	v_max_f32_e32 v97, 1.0, v97
	v_rndne_f32_e32 v98, v98
	v_rndne_f32_e32 v99, v99
	v_mul_f32_e32 v92, 0xbfb8aa3b, v92
	v_cvt_u32_f32_e32 v97, v97
	v_max_f32_e32 v98, 1.0, v98
	v_max_f32_e32 v99, 1.0, v99
	v_exp_f32_e32 v92, v92
	v_cvt_u32_f32_sdwa v98, v98 dst_sel:WORD_1 dst_unused:UNUSED_PAD src0_sel:DWORD
	v_cvt_u32_f32_sdwa v99, v99 dst_sel:BYTE_3 dst_unused:UNUSED_PAD src0_sel:DWORD
	v_mul_f32_e32 v100, 0x437f0000, v100
	v_mul_f32_e32 v96, 0x437f0000, v96
	v_rndne_f32_e32 v100, v100
	v_rndne_f32_e32 v96, v96
	v_lshl_or_b32 v97, v97, 8, v106
	v_add_f32_e32 v92, 1.0, v92
	v_max_f32_e32 v100, 1.0, v100
	v_max_f32_e32 v96, 1.0, v96
	v_mul_f32_e32 v101, 0x437f0000, v101
	v_mul_f32_e32 v102, 0x437f0000, v102
	v_or3_b32 v97, v97, v98, v99
	v_cvt_u32_f32_e32 v100, v100
	v_cvt_u32_f32_e32 v96, v96
	v_rndne_f32_e32 v101, v101
	v_rndne_f32_e32 v102, v102
	v_max_f32_e32 v101, 1.0, v101
	v_max_f32_e32 v102, 1.0, v102
	v_cvt_u32_f32_sdwa v101, v101 dst_sel:WORD_1 dst_unused:UNUSED_PAD src0_sel:DWORD
	v_cvt_u32_f32_sdwa v102, v102 dst_sel:BYTE_3 dst_unused:UNUSED_PAD src0_sel:DWORD
	v_lshl_or_b32 v96, v96, 8, v100
; __device__ __forceinline__ float sigmoidf_(float x) { return 1.0f / (1.0f + __expf(-x)); }
;     __device__ __forceinline__ void operator()(const f32x4 (&acc)[2][2][4][2], const Unit& u, int wr, int wc, int fr, int fq) const {
;     ...
;             for (int m = 0; m < 4; ++m) { unsigned char* rowp = O + (size_t)(row0 + ai * HALF + m * 16) * GP8 + col0;
; #pragma unroll
;                 for (int bj = 0; bj < 2; ++bj) { const f32x4 v0 = acc[ai][bj][m][0] + bv[bj][0], v1 = acc[ai][bj][m][1] + bv[bj][1];
;                     unsigned q[8];
; #pragma unroll
;                     for (int j = 0; j < 4; ++j) { q[j] = (unsigned)fmaxf(__builtin_rintf(sigmoidf_(v0[j]) * 255.f), 1.f); q[4 + j] = (unsigned)fmaxf(__builtin_rintf(sigmoidf_(v1[j]) * 255.f), 1.f); }
;                     u32x2 w; w.x = q[0] | (q[1] << 8) | (q[2] << 16) | (q[3] << 24); w.y = q[4] | (q[5] << 8) | (q[6] << 16) | (q[7] << 24);
;                     *(u32x2*)(rowp + bj * HALF) = w; } }
	v_add_f32_e32 v88, v88, v48
	v_mul_f32_e32 v88, 0xbfb8aa3b, v88
	v_or3_b32 v96, v96, v101, v102
	v_exp_f32_e32 v88, v88
	s_nop 0
	v_add_f32_e32 v88, 1.0, v88
	v_rcp_f32_e32 v92, v92
	v_add_f32_e32 v93, v93, v53
	v_mul_f32_e32 v93, 0xbfb8aa3b, v93
	v_exp_f32_e32 v93, v93
	s_nop 0
	v_add_f32_e32 v93, 1.0, v93
	v_rcp_f32_e32 v88, v88
	s_nop 0
	v_mul_f32_e32 v88, 0x437f0000, v88
	v_rndne_f32_e32 v88, v88
	v_max_f32_e32 v88, 1.0, v88
	v_cvt_u32_f32_e32 v100, v88
	v_add_f32_e32 v89, v89, v49
	v_mul_f32_e32 v89, 0xbfb8aa3b, v89
	v_exp_f32_e32 v89, v89
	s_nop 0
	v_add_f32_e32 v89, 1.0, v89
	v_rcp_f32_e32 v88, v93
	v_add_f32_e32 v94, v94, v54
	v_mul_f32_e32 v94, 0xbfb8aa3b, v94
	v_exp_f32_e32 v94, v94
	v_rcp_f32_e32 v89, v89
	v_add_f32_e32 v93, 1.0, v94
	v_add_f32_e32 v90, v90, v50
	v_mul_f32_e32 v90, 0xbfb8aa3b, v90
	v_exp_f32_e32 v90, v90
	s_nop 0
	v_add_f32_e32 v90, 1.0, v90
	v_rcp_f32_e32 v93, v93
	v_add_f32_e32 v95, v95, v55
	v_mul_f32_e32 v95, 0xbfb8aa3b, v95
	v_exp_f32_e32 v95, v95
	v_rcp_f32_e32 v90, v90
	v_add_f32_e32 v94, 1.0, v95
	v_add_f32_e32 v91, v91, v51
	v_mul_f32_e32 v91, 0xbfb8aa3b, v91
	v_exp_f32_e32 v91, v91
	s_nop 0
	v_add_f32_e32 v91, 1.0, v91
	v_rcp_f32_e32 v94, v94
	v_mul_f32_e32 v92, 0x437f0000, v92
	v_mul_f32_e32 v88, 0x437f0000, v88
	v_add_f32_e32 v84, v84, v36
	v_rndne_f32_e32 v92, v92
	v_rndne_f32_e32 v88, v88
	v_mul_f32_e32 v93, 0x437f0000, v93
	v_mul_f32_e32 v94, 0x437f0000, v94
	v_mul_f32_e32 v84, 0xbfb8aa3b, v84
	v_max_f32_e32 v92, 1.0, v92
	v_max_f32_e32 v88, 1.0, v88
	v_rndne_f32_e32 v93, v93
	v_rndne_f32_e32 v94, v94
	v_exp_f32_e32 v84, v84
	v_cvt_u32_f32_e32 v92, v92
	v_cvt_u32_f32_e32 v88, v88
	v_mul_f32_e32 v89, 0x437f0000, v89
	v_max_f32_e32 v93, 1.0, v93
	v_max_f32_e32 v94, 1.0, v94
	v_rcp_f32_e32 v91, v91
	v_rndne_f32_e32 v89, v89
	v_cvt_u32_f32_sdwa v93, v93 dst_sel:WORD_1 dst_unused:UNUSED_PAD src0_sel:DWORD
	v_mul_f32_e32 v90, 0x437f0000, v90
	v_cvt_u32_f32_sdwa v94, v94 dst_sel:BYTE_3 dst_unused:UNUSED_PAD src0_sel:DWORD
	v_mul_f32_e32 v91, 0x437f0000, v91
	v_max_f32_e32 v89, 1.0, v89
	v_rndne_f32_e32 v90, v90
	v_rndne_f32_e32 v91, v91
	v_cvt_u32_f32_e32 v89, v89
	v_max_f32_e32 v90, 1.0, v90
	v_max_f32_e32 v91, 1.0, v91
	v_add_f32_e32 v84, 1.0, v84
	v_cvt_u32_f32_sdwa v90, v90 dst_sel:WORD_1 dst_unused:UNUSED_PAD src0_sel:DWORD
	v_cvt_u32_f32_sdwa v91, v91 dst_sel:BYTE_3 dst_unused:UNUSED_PAD src0_sel:DWORD
	v_lshl_or_b32 v88, v88, 8, v92
	v_or3_b32 v88, v88, v93, v94
	global_store_dwordx2 v[112:113], v[96:97], off offset:128
	v_or_b32_e32 v96, 48, v173
	v_mad_i64_i32 v[96:97], s[2:3], v96, s55, v[164:165]
	v_lshl_or_b32 v89, v89, 8, v100
	v_lshl_add_u64 v[96:97], v[96:97], 0, v[162:163]
	v_or3_b32 v89, v89, v90, v91
	global_store_dwordx2 v[96:97], v[88:89], off
	v_add_f32_e32 v80, v80, v32
	v_mul_f32_e32 v80, 0xbfb8aa3b, v80
	v_exp_f32_e32 v80, v80
	s_nop 0
	v_add_f32_e32 v80, 1.0, v80
	v_rcp_f32_e32 v84, v84
	v_add_f32_e32 v85, v85, v37
	v_mul_f32_e32 v85, 0xbfb8aa3b, v85
	v_exp_f32_e32 v85, v85
	s_nop 0
	v_add_f32_e32 v85, 1.0, v85
	v_rcp_f32_e32 v80, v80
	s_nop 0
	v_mul_f32_e32 v80, 0x437f0000, v80
	v_rndne_f32_e32 v80, v80
	v_max_f32_e32 v80, 1.0, v80
	v_cvt_u32_f32_e32 v90, v80
	v_add_f32_e32 v81, v81, v33
	v_mul_f32_e32 v81, 0xbfb8aa3b, v81
	v_exp_f32_e32 v81, v81
	s_nop 0
	v_add_f32_e32 v81, 1.0, v81
	v_rcp_f32_e32 v80, v85
	v_add_f32_e32 v86, v86, v38
	v_mul_f32_e32 v86, 0xbfb8aa3b, v86
	v_exp_f32_e32 v86, v86
	v_rcp_f32_e32 v81, v81
	v_add_f32_e32 v85, 1.0, v86
	v_add_f32_e32 v82, v82, v34
	v_mul_f32_e32 v82, 0xbfb8aa3b, v82
	v_exp_f32_e32 v82, v82
	s_nop 0
	v_add_f32_e32 v82, 1.0, v82
	v_rcp_f32_e32 v85, v85
	v_add_f32_e32 v87, v87, v39
	v_mul_f32_e32 v87, 0xbfb8aa3b, v87
	v_exp_f32_e32 v87, v87
	v_rcp_f32_e32 v82, v82
	v_add_f32_e32 v86, 1.0, v87
	v_add_f32_e32 v83, v83, v35
	v_mul_f32_e32 v83, 0xbfb8aa3b, v83
	v_exp_f32_e32 v83, v83
	s_nop 0
	v_add_f32_e32 v83, 1.0, v83
	v_rcp_f32_e32 v86, v86
	v_mul_f32_e32 v81, 0x437f0000, v81
	v_rndne_f32_e32 v81, v81
	v_mul_f32_e32 v82, 0x437f0000, v82
	v_rcp_f32_e32 v83, v83
	s_nop 0
	v_mul_f32_e32 v83, 0x437f0000, v83
	v_add_f32_e32 v76, v76, v52
	v_max_f32_e32 v81, 1.0, v81
	v_rndne_f32_e32 v82, v82
	v_rndne_f32_e32 v83, v83
	v_mul_f32_e32 v76, 0xbfb8aa3b, v76
	v_cvt_u32_f32_e32 v81, v81
	v_max_f32_e32 v82, 1.0, v82
	v_max_f32_e32 v83, 1.0, v83
	v_exp_f32_e32 v76, v76
	v_cvt_u32_f32_sdwa v82, v82 dst_sel:WORD_1 dst_unused:UNUSED_PAD src0_sel:DWORD
	v_cvt_u32_f32_sdwa v83, v83 dst_sel:BYTE_3 dst_unused:UNUSED_PAD src0_sel:DWORD
	v_mul_f32_e32 v84, 0x437f0000, v84
	v_mul_f32_e32 v80, 0x437f0000, v80
	v_rndne_f32_e32 v84, v84
	v_rndne_f32_e32 v80, v80
	v_lshl_or_b32 v81, v81, 8, v90
	v_add_f32_e32 v76, 1.0, v76
	v_max_f32_e32 v84, 1.0, v84
	v_max_f32_e32 v80, 1.0, v80
	v_mul_f32_e32 v85, 0x437f0000, v85
	v_mul_f32_e32 v86, 0x437f0000, v86
	v_or3_b32 v81, v81, v82, v83
	v_cvt_u32_f32_e32 v84, v84
	v_cvt_u32_f32_e32 v80, v80
	v_rndne_f32_e32 v85, v85
	v_rndne_f32_e32 v86, v86
	v_max_f32_e32 v85, 1.0, v85
	v_max_f32_e32 v86, 1.0, v86
	v_cvt_u32_f32_sdwa v85, v85 dst_sel:WORD_1 dst_unused:UNUSED_PAD src0_sel:DWORD
	v_cvt_u32_f32_sdwa v86, v86 dst_sel:BYTE_3 dst_unused:UNUSED_PAD src0_sel:DWORD
	v_lshl_or_b32 v80, v80, 8, v84
	v_add_f32_e32 v72, v72, v48
	v_mul_f32_e32 v72, 0xbfb8aa3b, v72
	v_or3_b32 v80, v80, v85, v86
	v_exp_f32_e32 v72, v72
	s_nop 0
	v_add_f32_e32 v72, 1.0, v72
	v_rcp_f32_e32 v76, v76
	v_add_f32_e32 v77, v77, v53
	v_mul_f32_e32 v77, 0xbfb8aa3b, v77
	v_exp_f32_e32 v77, v77
	s_nop 0
	v_add_f32_e32 v77, 1.0, v77
	v_rcp_f32_e32 v72, v72
	s_nop 0
	v_mul_f32_e32 v72, 0x437f0000, v72
	v_rndne_f32_e32 v72, v72
	v_max_f32_e32 v72, 1.0, v72
; __device__ __forceinline__ float sigmoidf_(float x) { return 1.0f / (1.0f + __expf(-x)); }
;     __device__ __forceinline__ void operator()(const f32x4 (&acc)[2][2][4][2], const Unit& u, int wr, int wc, int fr, int fq) const {
;     ...
;             for (int m = 0; m < 4; ++m) { unsigned char* rowp = O + (size_t)(row0 + ai * HALF + m * 16) * GP8 + col0;
; #pragma unroll
;                 for (int bj = 0; bj < 2; ++bj) { const f32x4 v0 = acc[ai][bj][m][0] + bv[bj][0], v1 = acc[ai][bj][m][1] + bv[bj][1];
;                     unsigned q[8];
; #pragma unroll
;                     for (int j = 0; j < 4; ++j) { q[j] = (unsigned)fmaxf(__builtin_rintf(sigmoidf_(v0[j]) * 255.f), 1.f); q[4 + j] = (unsigned)fmaxf(__builtin_rintf(sigmoidf_(v1[j]) * 255.f), 1.f); }
;                     u32x2 w; w.x = q[0] | (q[1] << 8) | (q[2] << 16) | (q[3] << 24); w.y = q[4] | (q[5] << 8) | (q[6] << 16) | (q[7] << 24);
;                     *(u32x2*)(rowp + bj * HALF) = w; } }
	v_cvt_u32_f32_e32 v84, v72
	v_add_f32_e32 v73, v73, v49
	v_mul_f32_e32 v73, 0xbfb8aa3b, v73
	v_exp_f32_e32 v73, v73
	s_nop 0
	v_add_f32_e32 v73, 1.0, v73
	v_rcp_f32_e32 v72, v77
	v_add_f32_e32 v78, v78, v54
	v_mul_f32_e32 v78, 0xbfb8aa3b, v78
	v_exp_f32_e32 v78, v78
	v_rcp_f32_e32 v73, v73
	v_add_f32_e32 v77, 1.0, v78
	v_add_f32_e32 v74, v74, v50
	v_mul_f32_e32 v74, 0xbfb8aa3b, v74
	v_exp_f32_e32 v74, v74
	s_nop 0
	v_add_f32_e32 v74, 1.0, v74
	v_rcp_f32_e32 v77, v77
	v_add_f32_e32 v79, v79, v55
	v_mul_f32_e32 v79, 0xbfb8aa3b, v79
	v_exp_f32_e32 v79, v79
	v_rcp_f32_e32 v74, v74
	v_add_f32_e32 v78, 1.0, v79
	v_add_f32_e32 v75, v75, v51
	v_mul_f32_e32 v75, 0xbfb8aa3b, v75
	v_exp_f32_e32 v75, v75
	s_nop 0
	v_add_f32_e32 v75, 1.0, v75
	v_rcp_f32_e32 v78, v78
	v_mul_f32_e32 v76, 0x437f0000, v76
	v_mul_f32_e32 v72, 0x437f0000, v72
	v_add_f32_e32 v68, v68, v36
	v_rndne_f32_e32 v76, v76
	v_rndne_f32_e32 v72, v72
	v_mul_f32_e32 v77, 0x437f0000, v77
	v_mul_f32_e32 v78, 0x437f0000, v78
	v_mul_f32_e32 v68, 0xbfb8aa3b, v68
	v_max_f32_e32 v76, 1.0, v76
	v_max_f32_e32 v72, 1.0, v72
	v_rndne_f32_e32 v77, v77
	v_rndne_f32_e32 v78, v78
	v_exp_f32_e32 v68, v68
	v_cvt_u32_f32_e32 v76, v76
	v_cvt_u32_f32_e32 v72, v72
	v_mul_f32_e32 v73, 0x437f0000, v73
	v_max_f32_e32 v77, 1.0, v77
	v_max_f32_e32 v78, 1.0, v78
	v_rcp_f32_e32 v75, v75
	v_rndne_f32_e32 v73, v73
	v_cvt_u32_f32_sdwa v77, v77 dst_sel:WORD_1 dst_unused:UNUSED_PAD src0_sel:DWORD
	v_mul_f32_e32 v74, 0x437f0000, v74
	v_cvt_u32_f32_sdwa v78, v78 dst_sel:BYTE_3 dst_unused:UNUSED_PAD src0_sel:DWORD
	v_mul_f32_e32 v75, 0x437f0000, v75
	v_max_f32_e32 v73, 1.0, v73
	v_rndne_f32_e32 v74, v74
	v_rndne_f32_e32 v75, v75
	v_cvt_u32_f32_e32 v73, v73
	v_max_f32_e32 v74, 1.0, v74
	v_max_f32_e32 v75, 1.0, v75
	v_add_f32_e32 v68, 1.0, v68
	v_cvt_u32_f32_sdwa v74, v74 dst_sel:WORD_1 dst_unused:UNUSED_PAD src0_sel:DWORD
	v_cvt_u32_f32_sdwa v75, v75 dst_sel:BYTE_3 dst_unused:UNUSED_PAD src0_sel:DWORD
	v_lshl_or_b32 v72, v72, 8, v76
	v_or3_b32 v72, v72, v77, v78
	global_store_dwordx2 v[96:97], v[80:81], off offset:128
	v_add_u32_e32 v80, 0x80, v173
	v_mad_i64_i32 v[80:81], s[2:3], v80, s55, v[164:165]
	v_lshl_or_b32 v73, v73, 8, v84
	v_lshl_add_u64 v[80:81], v[80:81], 0, v[162:163]
	v_or3_b32 v73, v73, v74, v75
	global_store_dwordx2 v[80:81], v[72:73], off
	v_add_f32_e32 v64, v64, v32
	v_mul_f32_e32 v64, 0xbfb8aa3b, v64
	v_exp_f32_e32 v64, v64
	s_nop 0
	v_add_f32_e32 v64, 1.0, v64
	v_rcp_f32_e32 v68, v68
	v_add_f32_e32 v69, v69, v37
	v_mul_f32_e32 v69, 0xbfb8aa3b, v69
	v_exp_f32_e32 v69, v69
	s_nop 0
	v_add_f32_e32 v69, 1.0, v69
	v_rcp_f32_e32 v64, v64
	s_nop 0
	v_mul_f32_e32 v64, 0x437f0000, v64
	v_rndne_f32_e32 v64, v64
	v_max_f32_e32 v64, 1.0, v64
	v_cvt_u32_f32_e32 v74, v64
	v_add_f32_e32 v65, v65, v33
	v_mul_f32_e32 v65, 0xbfb8aa3b, v65
	v_exp_f32_e32 v65, v65
	s_nop 0
	v_add_f32_e32 v65, 1.0, v65
	v_rcp_f32_e32 v64, v69
	v_add_f32_e32 v70, v70, v38
	v_mul_f32_e32 v70, 0xbfb8aa3b, v70
	v_exp_f32_e32 v70, v70
	v_rcp_f32_e32 v65, v65
	v_add_f32_e32 v69, 1.0, v70
	v_add_f32_e32 v66, v66, v34
	v_mul_f32_e32 v66, 0xbfb8aa3b, v66
	v_exp_f32_e32 v66, v66
	s_nop 0
	v_add_f32_e32 v66, 1.0, v66
	v_rcp_f32_e32 v69, v69
	v_add_f32_e32 v71, v71, v39
	v_mul_f32_e32 v71, 0xbfb8aa3b, v71
	v_exp_f32_e32 v71, v71
	v_rcp_f32_e32 v66, v66
	v_add_f32_e32 v70, 1.0, v71
	v_add_f32_e32 v67, v67, v35
	v_mul_f32_e32 v67, 0xbfb8aa3b, v67
	v_exp_f32_e32 v67, v67
	s_nop 0
	v_add_f32_e32 v67, 1.0, v67
	v_rcp_f32_e32 v70, v70
	v_mul_f32_e32 v65, 0x437f0000, v65
	v_rndne_f32_e32 v65, v65
	v_mul_f32_e32 v66, 0x437f0000, v66
	v_rcp_f32_e32 v67, v67
	s_nop 0
	v_mul_f32_e32 v67, 0x437f0000, v67
	v_add_f32_e32 v60, v60, v52
	v_max_f32_e32 v65, 1.0, v65
	v_rndne_f32_e32 v66, v66
	v_rndne_f32_e32 v67, v67
	v_mul_f32_e32 v60, 0xbfb8aa3b, v60
	v_cvt_u32_f32_e32 v65, v65
	v_max_f32_e32 v66, 1.0, v66
	v_max_f32_e32 v67, 1.0, v67
	v_exp_f32_e32 v60, v60
	v_cvt_u32_f32_sdwa v66, v66 dst_sel:WORD_1 dst_unused:UNUSED_PAD src0_sel:DWORD
	v_cvt_u32_f32_sdwa v67, v67 dst_sel:BYTE_3 dst_unused:UNUSED_PAD src0_sel:DWORD
	v_mul_f32_e32 v68, 0x437f0000, v68
	v_mul_f32_e32 v64, 0x437f0000, v64
	v_rndne_f32_e32 v68, v68
	v_rndne_f32_e32 v64, v64
	v_lshl_or_b32 v65, v65, 8, v74
	v_add_f32_e32 v60, 1.0, v60
	v_max_f32_e32 v68, 1.0, v68
	v_max_f32_e32 v64, 1.0, v64
	v_mul_f32_e32 v69, 0x437f0000, v69
	v_mul_f32_e32 v70, 0x437f0000, v70
	v_or3_b32 v65, v65, v66, v67
	v_cvt_u32_f32_e32 v68, v68
	v_cvt_u32_f32_e32 v64, v64
	v_rndne_f32_e32 v69, v69
	v_rndne_f32_e32 v70, v70
	v_max_f32_e32 v69, 1.0, v69
	v_max_f32_e32 v70, 1.0, v70
	v_cvt_u32_f32_sdwa v69, v69 dst_sel:WORD_1 dst_unused:UNUSED_PAD src0_sel:DWORD
	v_cvt_u32_f32_sdwa v70, v70 dst_sel:BYTE_3 dst_unused:UNUSED_PAD src0_sel:DWORD
	v_lshl_or_b32 v64, v64, 8, v68
	v_add_f32_e32 v56, v56, v48
	v_mul_f32_e32 v56, 0xbfb8aa3b, v56
	v_or3_b32 v64, v64, v69, v70
	v_exp_f32_e32 v56, v56
	s_nop 0
	v_add_f32_e32 v56, 1.0, v56
	v_rcp_f32_e32 v60, v60
	v_add_f32_e32 v61, v61, v53
	v_mul_f32_e32 v61, 0xbfb8aa3b, v61
	v_exp_f32_e32 v61, v61
	s_nop 0
	v_add_f32_e32 v61, 1.0, v61
	v_rcp_f32_e32 v56, v56
	s_nop 0
	v_mul_f32_e32 v56, 0x437f0000, v56
	v_rndne_f32_e32 v56, v56
	v_max_f32_e32 v56, 1.0, v56
	v_cvt_u32_f32_e32 v68, v56
	v_add_f32_e32 v57, v57, v49
	v_mul_f32_e32 v57, 0xbfb8aa3b, v57
	v_exp_f32_e32 v57, v57
	s_nop 0
	v_add_f32_e32 v57, 1.0, v57
	v_rcp_f32_e32 v56, v61
	v_add_f32_e32 v62, v62, v54
	v_mul_f32_e32 v62, 0xbfb8aa3b, v62
	v_exp_f32_e32 v62, v62
	v_rcp_f32_e32 v57, v57
	v_add_f32_e32 v61, 1.0, v62
	v_add_f32_e32 v58, v58, v50
	v_mul_f32_e32 v58, 0xbfb8aa3b, v58
	v_exp_f32_e32 v58, v58
	s_nop 0
	v_add_f32_e32 v58, 1.0, v58
; __device__ __forceinline__ float sigmoidf_(float x) { return 1.0f / (1.0f + __expf(-x)); }
;     __device__ __forceinline__ void operator()(const f32x4 (&acc)[2][2][4][2], const Unit& u, int wr, int wc, int fr, int fq) const {
;     ...
;             for (int m = 0; m < 4; ++m) { unsigned char* rowp = O + (size_t)(row0 + ai * HALF + m * 16) * GP8 + col0;
; #pragma unroll
;                 for (int bj = 0; bj < 2; ++bj) { const f32x4 v0 = acc[ai][bj][m][0] + bv[bj][0], v1 = acc[ai][bj][m][1] + bv[bj][1];
;                     unsigned q[8];
; #pragma unroll
;                     for (int j = 0; j < 4; ++j) { q[j] = (unsigned)fmaxf(__builtin_rintf(sigmoidf_(v0[j]) * 255.f), 1.f); q[4 + j] = (unsigned)fmaxf(__builtin_rintf(sigmoidf_(v1[j]) * 255.f), 1.f); }
;                     u32x2 w; w.x = q[0] | (q[1] << 8) | (q[2] << 16) | (q[3] << 24); w.y = q[4] | (q[5] << 8) | (q[6] << 16) | (q[7] << 24);
;                     *(u32x2*)(rowp + bj * HALF) = w; } }
	v_rcp_f32_e32 v61, v61
	v_add_f32_e32 v63, v63, v55
	v_mul_f32_e32 v63, 0xbfb8aa3b, v63
	v_exp_f32_e32 v63, v63
	v_rcp_f32_e32 v58, v58
	v_add_f32_e32 v62, 1.0, v63
	v_add_f32_e32 v59, v59, v51
	v_mul_f32_e32 v59, 0xbfb8aa3b, v59
	v_exp_f32_e32 v59, v59
	s_nop 0
	v_add_f32_e32 v59, 1.0, v59
	v_rcp_f32_e32 v62, v62
	v_mul_f32_e32 v60, 0x437f0000, v60
	v_mul_f32_e32 v56, 0x437f0000, v56
	v_add_f32_e32 v44, v44, v36
	v_rndne_f32_e32 v60, v60
	v_rndne_f32_e32 v56, v56
	v_mul_f32_e32 v61, 0x437f0000, v61
	v_mul_f32_e32 v62, 0x437f0000, v62
	v_mul_f32_e32 v44, 0xbfb8aa3b, v44
	v_max_f32_e32 v60, 1.0, v60
	v_max_f32_e32 v56, 1.0, v56
	v_rndne_f32_e32 v61, v61
	v_rndne_f32_e32 v62, v62
	v_exp_f32_e32 v44, v44
	v_cvt_u32_f32_e32 v60, v60
	v_cvt_u32_f32_e32 v56, v56
	v_mul_f32_e32 v57, 0x437f0000, v57
	v_max_f32_e32 v61, 1.0, v61
	v_max_f32_e32 v62, 1.0, v62
	v_rcp_f32_e32 v59, v59
	v_rndne_f32_e32 v57, v57
	v_cvt_u32_f32_sdwa v61, v61 dst_sel:WORD_1 dst_unused:UNUSED_PAD src0_sel:DWORD
	v_mul_f32_e32 v58, 0x437f0000, v58
	v_cvt_u32_f32_sdwa v62, v62 dst_sel:BYTE_3 dst_unused:UNUSED_PAD src0_sel:DWORD
	v_mul_f32_e32 v59, 0x437f0000, v59
	v_max_f32_e32 v57, 1.0, v57
	v_rndne_f32_e32 v58, v58
	v_rndne_f32_e32 v59, v59
	v_cvt_u32_f32_e32 v57, v57
	v_max_f32_e32 v58, 1.0, v58
	v_max_f32_e32 v59, 1.0, v59
	v_add_f32_e32 v44, 1.0, v44
	v_cvt_u32_f32_sdwa v58, v58 dst_sel:WORD_1 dst_unused:UNUSED_PAD src0_sel:DWORD
	v_cvt_u32_f32_sdwa v59, v59 dst_sel:BYTE_3 dst_unused:UNUSED_PAD src0_sel:DWORD
	v_lshl_or_b32 v56, v56, 8, v60
	v_or3_b32 v56, v56, v61, v62
	global_store_dwordx2 v[80:81], v[64:65], off offset:128
	v_add_u32_e32 v64, 0x90, v173
	v_mad_i64_i32 v[64:65], s[2:3], v64, s55, v[164:165]
	v_lshl_or_b32 v57, v57, 8, v68
	v_lshl_add_u64 v[64:65], v[64:65], 0, v[162:163]
	v_or3_b32 v57, v57, v58, v59
	global_store_dwordx2 v[64:65], v[56:57], off
	v_add_f32_e32 v40, v40, v32
	v_mul_f32_e32 v40, 0xbfb8aa3b, v40
	v_exp_f32_e32 v40, v40
	s_nop 0
	v_add_f32_e32 v40, 1.0, v40
	v_rcp_f32_e32 v44, v44
	v_add_f32_e32 v45, v45, v37
	v_mul_f32_e32 v45, 0xbfb8aa3b, v45
	v_exp_f32_e32 v45, v45
	s_nop 0
	v_add_f32_e32 v45, 1.0, v45
	v_rcp_f32_e32 v40, v40
	s_nop 0
	v_mul_f32_e32 v40, 0x437f0000, v40
	v_rndne_f32_e32 v40, v40
	v_max_f32_e32 v40, 1.0, v40
	v_cvt_u32_f32_e32 v58, v40
	v_add_f32_e32 v41, v41, v33
	v_mul_f32_e32 v41, 0xbfb8aa3b, v41
	v_exp_f32_e32 v41, v41
	s_nop 0
	v_add_f32_e32 v41, 1.0, v41
	v_rcp_f32_e32 v40, v45
	v_add_f32_e32 v46, v46, v38
	v_mul_f32_e32 v46, 0xbfb8aa3b, v46
	v_exp_f32_e32 v46, v46
	v_rcp_f32_e32 v41, v41
	v_add_f32_e32 v45, 1.0, v46
	v_add_f32_e32 v42, v42, v34
	v_mul_f32_e32 v42, 0xbfb8aa3b, v42
	v_exp_f32_e32 v42, v42
	s_nop 0
	v_add_f32_e32 v42, 1.0, v42
	v_rcp_f32_e32 v45, v45
	v_add_f32_e32 v47, v47, v39
	v_mul_f32_e32 v47, 0xbfb8aa3b, v47
	v_exp_f32_e32 v47, v47
	v_rcp_f32_e32 v42, v42
	v_add_f32_e32 v46, 1.0, v47
	v_add_f32_e32 v43, v43, v35
	v_mul_f32_e32 v43, 0xbfb8aa3b, v43
	v_exp_f32_e32 v43, v43
	s_nop 0
	v_add_f32_e32 v43, 1.0, v43
	v_rcp_f32_e32 v46, v46
	v_mul_f32_e32 v41, 0x437f0000, v41
	v_rndne_f32_e32 v41, v41
	v_mul_f32_e32 v42, 0x437f0000, v42
	v_rcp_f32_e32 v43, v43
	s_nop 0
	v_mul_f32_e32 v43, 0x437f0000, v43
	v_add_f32_e32 v28, v28, v52
	v_max_f32_e32 v41, 1.0, v41
	v_rndne_f32_e32 v42, v42
	v_rndne_f32_e32 v43, v43
	v_mul_f32_e32 v28, 0xbfb8aa3b, v28
	v_cvt_u32_f32_e32 v41, v41
	v_max_f32_e32 v42, 1.0, v42
	v_max_f32_e32 v43, 1.0, v43
	v_exp_f32_e32 v28, v28
	v_cvt_u32_f32_sdwa v42, v42 dst_sel:WORD_1 dst_unused:UNUSED_PAD src0_sel:DWORD
	v_cvt_u32_f32_sdwa v43, v43 dst_sel:BYTE_3 dst_unused:UNUSED_PAD src0_sel:DWORD
	v_mul_f32_e32 v44, 0x437f0000, v44
	v_mul_f32_e32 v40, 0x437f0000, v40
	v_rndne_f32_e32 v44, v44
	v_rndne_f32_e32 v40, v40
	v_lshl_or_b32 v41, v41, 8, v58
	v_add_f32_e32 v28, 1.0, v28
	v_max_f32_e32 v44, 1.0, v44
	v_max_f32_e32 v40, 1.0, v40
	v_mul_f32_e32 v45, 0x437f0000, v45
	v_mul_f32_e32 v46, 0x437f0000, v46
	v_or3_b32 v41, v41, v42, v43
	v_cvt_u32_f32_e32 v44, v44
	v_cvt_u32_f32_e32 v40, v40
	v_rndne_f32_e32 v45, v45
	v_rndne_f32_e32 v46, v46
	v_max_f32_e32 v45, 1.0, v45
	v_max_f32_e32 v46, 1.0, v46
	v_cvt_u32_f32_sdwa v45, v45 dst_sel:WORD_1 dst_unused:UNUSED_PAD src0_sel:DWORD
	v_cvt_u32_f32_sdwa v46, v46 dst_sel:BYTE_3 dst_unused:UNUSED_PAD src0_sel:DWORD
	v_lshl_or_b32 v40, v40, 8, v44
	v_add_f32_e32 v24, v24, v48
	v_mul_f32_e32 v24, 0xbfb8aa3b, v24
	v_or3_b32 v40, v40, v45, v46
	v_exp_f32_e32 v24, v24
	s_nop 0
	v_add_f32_e32 v24, 1.0, v24
	v_rcp_f32_e32 v28, v28
	v_add_f32_e32 v29, v29, v53
	v_mul_f32_e32 v29, 0xbfb8aa3b, v29
	v_exp_f32_e32 v29, v29
	s_nop 0
	v_add_f32_e32 v29, 1.0, v29
	v_rcp_f32_e32 v24, v24
	s_nop 0
	v_mul_f32_e32 v24, 0x437f0000, v24
	v_rndne_f32_e32 v24, v24
	v_max_f32_e32 v24, 1.0, v24
	v_cvt_u32_f32_e32 v44, v24
	v_add_f32_e32 v25, v25, v49
	v_mul_f32_e32 v25, 0xbfb8aa3b, v25
	v_exp_f32_e32 v25, v25
	s_nop 0
	v_add_f32_e32 v25, 1.0, v25
	v_rcp_f32_e32 v24, v29
	v_add_f32_e32 v30, v30, v54
	v_mul_f32_e32 v30, 0xbfb8aa3b, v30
	v_exp_f32_e32 v30, v30
	v_rcp_f32_e32 v25, v25
	v_add_f32_e32 v29, 1.0, v30
	v_add_f32_e32 v26, v26, v50
	v_mul_f32_e32 v26, 0xbfb8aa3b, v26
	v_exp_f32_e32 v26, v26
	s_nop 0
	v_add_f32_e32 v26, 1.0, v26
	v_rcp_f32_e32 v29, v29
	v_add_f32_e32 v31, v31, v55
	v_mul_f32_e32 v31, 0xbfb8aa3b, v31
	v_exp_f32_e32 v31, v31
	v_rcp_f32_e32 v26, v26
	v_add_f32_e32 v30, 1.0, v31
	v_add_f32_e32 v27, v27, v51
	v_mul_f32_e32 v27, 0xbfb8aa3b, v27
	v_exp_f32_e32 v27, v27
	s_nop 0
	v_add_f32_e32 v27, 1.0, v27
	v_rcp_f32_e32 v30, v30
	v_mul_f32_e32 v28, 0x437f0000, v28
	v_mul_f32_e32 v24, 0x437f0000, v24
	v_add_f32_e32 v20, v20, v36
	v_rndne_f32_e32 v28, v28
; __device__ __forceinline__ float sigmoidf_(float x) { return 1.0f / (1.0f + __expf(-x)); }
;     __device__ __forceinline__ void operator()(const f32x4 (&acc)[2][2][4][2], const Unit& u, int wr, int wc, int fr, int fq) const {
;     ...
;             for (int m = 0; m < 4; ++m) { unsigned char* rowp = O + (size_t)(row0 + ai * HALF + m * 16) * GP8 + col0;
; #pragma unroll
;                 for (int bj = 0; bj < 2; ++bj) { const f32x4 v0 = acc[ai][bj][m][0] + bv[bj][0], v1 = acc[ai][bj][m][1] + bv[bj][1];
;                     unsigned q[8];
; #pragma unroll
;                     for (int j = 0; j < 4; ++j) { q[j] = (unsigned)fmaxf(__builtin_rintf(sigmoidf_(v0[j]) * 255.f), 1.f); q[4 + j] = (unsigned)fmaxf(__builtin_rintf(sigmoidf_(v1[j]) * 255.f), 1.f); }
;                     u32x2 w; w.x = q[0] | (q[1] << 8) | (q[2] << 16) | (q[3] << 24); w.y = q[4] | (q[5] << 8) | (q[6] << 16) | (q[7] << 24);
;                     *(u32x2*)(rowp + bj * HALF) = w; } }
	v_rndne_f32_e32 v24, v24
	v_mul_f32_e32 v29, 0x437f0000, v29
	v_mul_f32_e32 v30, 0x437f0000, v30
	v_mul_f32_e32 v20, 0xbfb8aa3b, v20
	v_max_f32_e32 v28, 1.0, v28
	v_max_f32_e32 v24, 1.0, v24
	v_rndne_f32_e32 v29, v29
	v_rndne_f32_e32 v30, v30
	v_exp_f32_e32 v20, v20
	v_cvt_u32_f32_e32 v28, v28
	v_cvt_u32_f32_e32 v24, v24
	v_mul_f32_e32 v25, 0x437f0000, v25
	v_max_f32_e32 v29, 1.0, v29
	v_max_f32_e32 v30, 1.0, v30
	v_rcp_f32_e32 v27, v27
	v_rndne_f32_e32 v25, v25
	v_cvt_u32_f32_sdwa v29, v29 dst_sel:WORD_1 dst_unused:UNUSED_PAD src0_sel:DWORD
	v_mul_f32_e32 v26, 0x437f0000, v26
	v_cvt_u32_f32_sdwa v30, v30 dst_sel:BYTE_3 dst_unused:UNUSED_PAD src0_sel:DWORD
	v_mul_f32_e32 v27, 0x437f0000, v27
	v_max_f32_e32 v25, 1.0, v25
	v_rndne_f32_e32 v26, v26
	v_rndne_f32_e32 v27, v27
	v_cvt_u32_f32_e32 v25, v25
	v_max_f32_e32 v26, 1.0, v26
	v_max_f32_e32 v27, 1.0, v27
	v_add_f32_e32 v20, 1.0, v20
	v_cvt_u32_f32_sdwa v26, v26 dst_sel:WORD_1 dst_unused:UNUSED_PAD src0_sel:DWORD
	v_cvt_u32_f32_sdwa v27, v27 dst_sel:BYTE_3 dst_unused:UNUSED_PAD src0_sel:DWORD
	v_lshl_or_b32 v24, v24, 8, v28
	v_or3_b32 v24, v24, v29, v30
	global_store_dwordx2 v[64:65], v[40:41], off offset:128
	v_add_u32_e32 v40, 0xa0, v173
	v_mad_i64_i32 v[40:41], s[2:3], v40, s55, v[164:165]
	v_lshl_or_b32 v25, v25, 8, v44
	v_lshl_add_u64 v[40:41], v[40:41], 0, v[162:163]
	v_or3_b32 v25, v25, v26, v27
	global_store_dwordx2 v[40:41], v[24:25], off
	v_add_f32_e32 v16, v16, v32
	v_mul_f32_e32 v16, 0xbfb8aa3b, v16
	v_exp_f32_e32 v16, v16
	s_nop 0
	v_add_f32_e32 v16, 1.0, v16
	v_rcp_f32_e32 v20, v20
	v_add_f32_e32 v21, v21, v37
	v_mul_f32_e32 v21, 0xbfb8aa3b, v21
	v_exp_f32_e32 v21, v21
	s_nop 0
	v_add_f32_e32 v21, 1.0, v21
	v_rcp_f32_e32 v16, v16
	s_nop 0
	v_mul_f32_e32 v16, 0x437f0000, v16
	v_rndne_f32_e32 v16, v16
	v_max_f32_e32 v16, 1.0, v16
	v_cvt_u32_f32_e32 v26, v16
	v_add_f32_e32 v17, v17, v33
	v_mul_f32_e32 v17, 0xbfb8aa3b, v17
	v_exp_f32_e32 v17, v17
	s_nop 0
	v_add_f32_e32 v17, 1.0, v17
	v_rcp_f32_e32 v16, v21
	v_add_f32_e32 v22, v22, v38
	v_mul_f32_e32 v22, 0xbfb8aa3b, v22
	v_exp_f32_e32 v22, v22
	v_rcp_f32_e32 v17, v17
	v_add_f32_e32 v21, 1.0, v22
	v_add_f32_e32 v18, v18, v34
	v_mul_f32_e32 v18, 0xbfb8aa3b, v18
	v_exp_f32_e32 v18, v18
	s_nop 0
	v_add_f32_e32 v18, 1.0, v18
	v_rcp_f32_e32 v21, v21
	v_add_f32_e32 v23, v23, v39
	v_mul_f32_e32 v23, 0xbfb8aa3b, v23
	v_exp_f32_e32 v23, v23
	v_rcp_f32_e32 v18, v18
	v_add_f32_e32 v22, 1.0, v23
	v_add_f32_e32 v19, v19, v35
	v_mul_f32_e32 v19, 0xbfb8aa3b, v19
	v_exp_f32_e32 v19, v19
	s_nop 0
	v_add_f32_e32 v19, 1.0, v19
	v_rcp_f32_e32 v22, v22
	v_mul_f32_e32 v17, 0x437f0000, v17
	v_rndne_f32_e32 v17, v17
	v_mul_f32_e32 v18, 0x437f0000, v18
	v_rcp_f32_e32 v19, v19
	s_nop 0
	v_mul_f32_e32 v19, 0x437f0000, v19
	v_add_f32_e32 v12, v12, v52
	v_max_f32_e32 v17, 1.0, v17
	v_rndne_f32_e32 v18, v18
	v_rndne_f32_e32 v19, v19
	v_mul_f32_e32 v12, 0xbfb8aa3b, v12
	v_cvt_u32_f32_e32 v17, v17
	v_max_f32_e32 v18, 1.0, v18
	v_max_f32_e32 v19, 1.0, v19
	v_exp_f32_e32 v12, v12
	v_cvt_u32_f32_sdwa v18, v18 dst_sel:WORD_1 dst_unused:UNUSED_PAD src0_sel:DWORD
	v_cvt_u32_f32_sdwa v19, v19 dst_sel:BYTE_3 dst_unused:UNUSED_PAD src0_sel:DWORD
	v_mul_f32_e32 v20, 0x437f0000, v20
	v_mul_f32_e32 v16, 0x437f0000, v16
	v_rndne_f32_e32 v20, v20
	v_rndne_f32_e32 v16, v16
	v_lshl_or_b32 v17, v17, 8, v26
	v_add_f32_e32 v12, 1.0, v12
	v_max_f32_e32 v20, 1.0, v20
	v_max_f32_e32 v16, 1.0, v16
	v_mul_f32_e32 v21, 0x437f0000, v21
	v_mul_f32_e32 v22, 0x437f0000, v22
	v_or3_b32 v17, v17, v18, v19
	v_cvt_u32_f32_e32 v20, v20
	v_cvt_u32_f32_e32 v16, v16
	v_rndne_f32_e32 v21, v21
	v_rndne_f32_e32 v22, v22
	v_max_f32_e32 v21, 1.0, v21
	v_max_f32_e32 v22, 1.0, v22
	v_cvt_u32_f32_sdwa v21, v21 dst_sel:WORD_1 dst_unused:UNUSED_PAD src0_sel:DWORD
	v_cvt_u32_f32_sdwa v22, v22 dst_sel:BYTE_3 dst_unused:UNUSED_PAD src0_sel:DWORD
	v_lshl_or_b32 v16, v16, 8, v20
	v_add_f32_e32 v8, v8, v48
	v_mul_f32_e32 v8, 0xbfb8aa3b, v8
	v_or3_b32 v16, v16, v21, v22
	v_exp_f32_e32 v8, v8
	s_nop 0
	v_add_f32_e32 v8, 1.0, v8
	v_rcp_f32_e32 v12, v12
	v_add_f32_e32 v13, v13, v53
	v_mul_f32_e32 v13, 0xbfb8aa3b, v13
	v_exp_f32_e32 v13, v13
	s_nop 0
	v_add_f32_e32 v13, 1.0, v13
	v_rcp_f32_e32 v8, v8
	s_nop 0
	v_mul_f32_e32 v8, 0x437f0000, v8
	v_rndne_f32_e32 v8, v8
	v_max_f32_e32 v8, 1.0, v8
	v_cvt_u32_f32_e32 v20, v8
	v_add_f32_e32 v9, v9, v49
	v_mul_f32_e32 v9, 0xbfb8aa3b, v9
	v_exp_f32_e32 v9, v9
	s_nop 0
	v_add_f32_e32 v9, 1.0, v9
	v_rcp_f32_e32 v8, v13
	v_add_f32_e32 v14, v14, v54
; __device__ __forceinline__ float sigmoidf_(float x) { return 1.0f / (1.0f + __expf(-x)); }
; #define PG8_BAR __builtin_amdgcn_s_barrier()
;     __device__ __forceinline__ void operator()(const f32x4 (&acc)[2][2][4][2], const Unit& u, int wr, int wc, int fr, int fq) const {
;     ...
;             for (int m = 0; m < 4; ++m) { unsigned char* rowp = O + (size_t)(row0 + ai * HALF + m * 16) * GP8 + col0;
; #pragma unroll
;                 for (int bj = 0; bj < 2; ++bj) { const f32x4 v0 = acc[ai][bj][m][0] + bv[bj][0], v1 = acc[ai][bj][m][1] + bv[bj][1];
;                     unsigned q[8];
; #pragma unroll
;                     for (int j = 0; j < 4; ++j) { q[j] = (unsigned)fmaxf(__builtin_rintf(sigmoidf_(v0[j]) * 255.f), 1.f); q[4 + j] = (unsigned)fmaxf(__builtin_rintf(sigmoidf_(v1[j]) * 255.f), 1.f); }
;                     u32x2 w; w.x = q[0] | (q[1] << 8) | (q[2] << 16) | (q[3] << 24); w.y = q[4] | (q[5] << 8) | (q[6] << 16) | (q[7] << 24);
;                     *(u32x2*)(rowp + bj * HALF) = w; } }
; template <class Epi, class Sched, bool ALIGN_EPI = true>
; __device__ __forceinline__ void gemm_phase(LAS unsigned char* lds, const Gemm g, const Sched& S, const Epi& E) {
;     ...
;         if constexpr (ALIGN_EPI) { if (wr == 0) PG8_BAR; }
;         E(acc, cur, wr, wc, fr, fq);
;         if (!has_next) break;
; #pragma unroll
;         for (int a = 0; a < 2; ++a)
; #pragma unroll
;             for (int b = 0; b < 2; ++b)
; #pragma unroll
;                 for (int m = 0; m < 4; ++m)
; #pragma unroll
;                     for (int n = 0; n < 2; ++n) acc[a][b][m][n] = (f32x4){0.f, 0.f, 0.f, 0.f};
;         cur = nxt; cA = nA; cB = nB; ++ui;
;         if constexpr (ALIGN_EPI) { if (wr == 1) PG8_BAR; }
	v_mul_f32_e32 v14, 0xbfb8aa3b, v14
	v_exp_f32_e32 v14, v14
	v_rcp_f32_e32 v9, v9
	v_add_f32_e32 v13, 1.0, v14
	v_add_f32_e32 v10, v10, v50
	v_mul_f32_e32 v10, 0xbfb8aa3b, v10
	v_exp_f32_e32 v10, v10
	s_nop 0
	v_add_f32_e32 v10, 1.0, v10
	v_rcp_f32_e32 v13, v13
	v_add_f32_e32 v15, v15, v55
	v_mul_f32_e32 v15, 0xbfb8aa3b, v15
	v_exp_f32_e32 v15, v15
	v_rcp_f32_e32 v10, v10
	v_add_f32_e32 v14, 1.0, v15
	v_add_f32_e32 v11, v11, v51
	v_mul_f32_e32 v11, 0xbfb8aa3b, v11
	v_exp_f32_e32 v11, v11
	s_nop 0
	v_add_f32_e32 v11, 1.0, v11
	v_rcp_f32_e32 v14, v14
	v_mul_f32_e32 v12, 0x437f0000, v12
	v_mul_f32_e32 v8, 0x437f0000, v8
	v_add_f32_e32 v4, v4, v36
	v_rndne_f32_e32 v12, v12
	v_rndne_f32_e32 v8, v8
	v_mul_f32_e32 v13, 0x437f0000, v13
	v_mul_f32_e32 v14, 0x437f0000, v14
	v_mul_f32_e32 v4, 0xbfb8aa3b, v4
	v_max_f32_e32 v12, 1.0, v12
	v_max_f32_e32 v8, 1.0, v8
	v_rndne_f32_e32 v13, v13
	v_rndne_f32_e32 v14, v14
	v_exp_f32_e32 v4, v4
	v_cvt_u32_f32_e32 v12, v12
	v_cvt_u32_f32_e32 v8, v8
	v_mul_f32_e32 v9, 0x437f0000, v9
	v_max_f32_e32 v13, 1.0, v13
	v_max_f32_e32 v14, 1.0, v14
	v_rcp_f32_e32 v11, v11
	v_rndne_f32_e32 v9, v9
	v_cvt_u32_f32_sdwa v13, v13 dst_sel:WORD_1 dst_unused:UNUSED_PAD src0_sel:DWORD
	v_mul_f32_e32 v10, 0x437f0000, v10
	v_cvt_u32_f32_sdwa v14, v14 dst_sel:BYTE_3 dst_unused:UNUSED_PAD src0_sel:DWORD
	v_mul_f32_e32 v11, 0x437f0000, v11
	v_max_f32_e32 v9, 1.0, v9
	v_rndne_f32_e32 v10, v10
	v_rndne_f32_e32 v11, v11
	v_cvt_u32_f32_e32 v9, v9
	v_max_f32_e32 v10, 1.0, v10
	v_max_f32_e32 v11, 1.0, v11
	v_add_f32_e32 v4, 1.0, v4
	v_cvt_u32_f32_sdwa v10, v10 dst_sel:WORD_1 dst_unused:UNUSED_PAD src0_sel:DWORD
	v_cvt_u32_f32_sdwa v11, v11 dst_sel:BYTE_3 dst_unused:UNUSED_PAD src0_sel:DWORD
	v_lshl_or_b32 v8, v8, 8, v12
	v_or3_b32 v8, v8, v13, v14
	global_store_dwordx2 v[40:41], v[16:17], off offset:128
	v_add_u32_e32 v16, 0xb0, v173
	v_mad_i64_i32 v[16:17], s[2:3], v16, s55, v[164:165]
	v_lshl_or_b32 v9, v9, 8, v20
	v_lshl_add_u64 v[16:17], v[16:17], 0, v[162:163]
	v_or3_b32 v9, v9, v10, v11
	global_store_dwordx2 v[16:17], v[8:9], off
	v_add_f32_e32 v0, v0, v32
	v_mul_f32_e32 v0, 0xbfb8aa3b, v0
	v_exp_f32_e32 v0, v0
	s_nop 0
	v_add_f32_e32 v0, 1.0, v0
	v_rcp_f32_e32 v4, v4
	v_add_f32_e32 v5, v5, v37
	v_mul_f32_e32 v5, 0xbfb8aa3b, v5
	v_exp_f32_e32 v5, v5
	s_nop 0
	v_add_f32_e32 v5, 1.0, v5
	v_rcp_f32_e32 v0, v0
	s_nop 0
	v_mul_f32_e32 v0, 0x437f0000, v0
	v_rndne_f32_e32 v0, v0
	v_max_f32_e32 v0, 1.0, v0
	v_cvt_u32_f32_e32 v10, v0
	v_add_f32_e32 v1, v1, v33
	v_mul_f32_e32 v1, 0xbfb8aa3b, v1
	v_exp_f32_e32 v1, v1
	s_nop 0
	v_add_f32_e32 v1, 1.0, v1
	v_rcp_f32_e32 v0, v5
	v_add_f32_e32 v6, v6, v38
	v_mul_f32_e32 v6, 0xbfb8aa3b, v6
	v_exp_f32_e32 v6, v6
	v_rcp_f32_e32 v1, v1
	v_add_f32_e32 v5, 1.0, v6
	v_add_f32_e32 v2, v2, v34
	v_mul_f32_e32 v2, 0xbfb8aa3b, v2
	v_exp_f32_e32 v2, v2
	s_nop 0
	v_add_f32_e32 v2, 1.0, v2
	v_rcp_f32_e32 v5, v5
	v_add_f32_e32 v7, v7, v39
	v_mul_f32_e32 v7, 0xbfb8aa3b, v7
	v_exp_f32_e32 v7, v7
	v_rcp_f32_e32 v2, v2
	v_add_f32_e32 v6, 1.0, v7
	v_add_f32_e32 v3, v3, v35
	v_mul_f32_e32 v3, 0xbfb8aa3b, v3
	v_exp_f32_e32 v3, v3
	s_nop 0
	v_add_f32_e32 v3, 1.0, v3
	v_rcp_f32_e32 v6, v6
	v_mul_f32_e32 v4, 0x437f0000, v4
	v_mul_f32_e32 v0, 0x437f0000, v0
	v_mul_f32_e32 v1, 0x437f0000, v1
	v_rcp_f32_e32 v3, v3
	v_rndne_f32_e32 v4, v4
	v_rndne_f32_e32 v0, v0
	v_rndne_f32_e32 v1, v1
	v_mul_f32_e32 v5, 0x437f0000, v5
	v_mul_f32_e32 v2, 0x437f0000, v2
	v_mul_f32_e32 v6, 0x437f0000, v6
	v_mul_f32_e32 v3, 0x437f0000, v3
	v_max_f32_e32 v4, 1.0, v4
	v_max_f32_e32 v0, 1.0, v0
	v_max_f32_e32 v1, 1.0, v1
	v_rndne_f32_e32 v5, v5
	v_rndne_f32_e32 v2, v2
	v_rndne_f32_e32 v6, v6
	v_rndne_f32_e32 v3, v3
	v_cvt_u32_f32_e32 v4, v4
	v_cvt_u32_f32_e32 v0, v0
	v_cvt_u32_f32_e32 v1, v1
	v_max_f32_e32 v5, 1.0, v5
	v_max_f32_e32 v2, 1.0, v2
	v_max_f32_e32 v6, 1.0, v6
	v_max_f32_e32 v3, 1.0, v3
	v_cvt_u32_f32_sdwa v5, v5 dst_sel:WORD_1 dst_unused:UNUSED_PAD src0_sel:DWORD
	v_cvt_u32_f32_sdwa v2, v2 dst_sel:WORD_1 dst_unused:UNUSED_PAD src0_sel:DWORD
	v_cvt_u32_f32_sdwa v6, v6 dst_sel:BYTE_3 dst_unused:UNUSED_PAD src0_sel:DWORD
	v_cvt_u32_f32_sdwa v3, v3 dst_sel:BYTE_3 dst_unused:UNUSED_PAD src0_sel:DWORD
	v_lshl_or_b32 v0, v0, 8, v4
	v_lshl_or_b32 v1, v1, 8, v10
	v_or3_b32 v0, v0, v5, v6
	v_or3_b32 v1, v1, v2, v3
	s_andn2_b64 vcc, exec, s[0:1]
	s_mov_b64 s[0:1], -1
	global_store_dwordx2 v[16:17], v[0:1], off offset:128
	s_cbranch_vccnz .LBB0_786
	s_andn2_b64 vcc, exec, s[10:11]
	s_cbranch_vccnz .LBB0_785
	s_barrier
	s_branch .LBB0_785

; __device__ __forceinline__ float sigmoidf_(float x) { return 1.0f / (1.0f + __expf(-x)); }
;     __device__ __forceinline__ void operator()(const f32x4 (&acc)[2][2][4][2], const Unit& u, int wr, int wc, int fr, int fq) const {
;         const int row0 = u.pm * BM + wr * 64 + fr; const int col0 = u.pn * BM + wc * 32 + 8 * fq;
;         f32x4 bv[2][2];
; #pragma unroll
;         for (int bj = 0; bj < 2; ++bj)
; #pragma unroll
;             for (int n = 0; n < 2; ++n) bv[bj][n] = *(const f32x4*)(bias + col0 + bj * HALF + 4 * n);
; #pragma unroll
;         for (int ai = 0; ai < 2; ++ai)
; #pragma unroll
;             for (int m = 0; m < 4; ++m) { unsigned char* rowp = O + (size_t)(row0 + ai * HALF + m * 16) * GP8 + col0;
; #pragma unroll
;                 for (int bj = 0; bj < 2; ++bj) { const f32x4 v0 = acc[ai][bj][m][0] + bv[bj][0], v1 = acc[ai][bj][m][1] + bv[bj][1];
;                     unsigned q[8];
; #pragma unroll
;                     for (int j = 0; j < 4; ++j) { q[j] = (unsigned)fmaxf(__builtin_rintf(sigmoidf_(v0[j]) * 255.f), 1.f); q[4 + j] = (unsigned)fmaxf(__builtin_rintf(sigmoidf_(v1[j]) * 255.f), 1.f); }
;                     u32x2 w; w.x = q[0] | (q[1] << 8) | (q[2] << 16) | (q[3] << 24); w.y = q[4] | (q[5] << 8) | (q[6] << 16) | (q[7] << 24);
;                     *(u32x2*)(rowp + bj * HALF) = w; } }
.LBB0_811:
	v_lshl_or_b32 v162, s9, 8, v170
	v_ashrrev_i32_e32 v163, 31, v162
	v_lshl_add_u64 v[36:37], v[162:163], 2, s[78:79]
	global_load_dwordx4 v[52:55], v[36:37], off
	global_load_dwordx4 v[48:51], v[36:37], off offset:16
	v_lshl_add_u32 v174, s8, 8, v168
	v_mov_b64_e32 v[164:165], s[34:35]
	v_mad_i64_i32 v[32:33], s[2:3], v174, s55, v[164:165]
	v_lshl_add_u64 v[166:167], v[32:33], 0, v[162:163]
	global_load_dwordx4 v[32:35], v[36:37], off offset:528
	s_nop 0
	global_load_dwordx4 v[36:39], v[36:37], off offset:512
	s_waitcnt vmcnt(0)
	v_add_f32_e32 v140, v140, v52
	v_add_f32_e32 v136, v136, v48
	v_mul_f32_e32 v140, 0xbfb8aa3b, v140
	v_add_f32_e32 v141, v141, v53
	v_add_f32_e32 v142, v142, v54
	v_mul_f32_e32 v136, 0xbfb8aa3b, v136
	v_exp_f32_e32 v140, v140
	v_mul_f32_e32 v141, 0xbfb8aa3b, v141
	v_mul_f32_e32 v142, 0xbfb8aa3b, v142
	v_exp_f32_e32 v136, v136
	v_exp_f32_e32 v141, v141
	v_exp_f32_e32 v142, v142
	v_add_f32_e32 v137, v137, v49
	v_mul_f32_e32 v137, 0xbfb8aa3b, v137
	v_add_f32_e32 v140, 1.0, v140
	v_exp_f32_e32 v137, v137
	v_add_f32_e32 v136, 1.0, v136
	v_add_f32_e32 v141, 1.0, v141
	v_add_f32_e32 v142, 1.0, v142
	v_add_f32_e32 v137, 1.0, v137
	v_rcp_f32_e32 v140, v140
	v_rcp_f32_e32 v136, v136
	s_nop 0
	v_mul_f32_e32 v136, 0x437f0000, v136
	v_rcp_f32_e32 v141, v141
	v_rndne_f32_e32 v136, v136
	v_mul_f32_e32 v141, 0x437f0000, v141
	v_max_f32_e32 v136, 1.0, v136
	v_rndne_f32_e32 v141, v141
	v_add_f32_e32 v138, v138, v50
	v_rcp_f32_e32 v137, v137
	v_cvt_u32_f32_e32 v175, v136
	v_max_f32_e32 v136, 1.0, v141
	v_mul_f32_e32 v138, 0xbfb8aa3b, v138
	v_exp_f32_e32 v138, v138
	s_nop 0
	v_add_f32_e32 v138, 1.0, v138
	v_rcp_f32_e32 v141, v142
	v_add_f32_e32 v143, v143, v55
	v_mul_f32_e32 v143, 0xbfb8aa3b, v143
	v_exp_f32_e32 v143, v143
	v_rcp_f32_e32 v138, v138
	v_add_f32_e32 v142, 1.0, v143
	v_add_f32_e32 v139, v139, v51
	v_mul_f32_e32 v139, 0xbfb8aa3b, v139
	v_exp_f32_e32 v139, v139
	s_nop 0
	v_add_f32_e32 v139, 1.0, v139
	v_rcp_f32_e32 v142, v142
	v_mul_f32_e32 v140, 0x437f0000, v140
	v_add_f32_e32 v132, v132, v36
	v_rndne_f32_e32 v140, v140
	v_mul_f32_e32 v141, 0x437f0000, v141
	v_mul_f32_e32 v142, 0x437f0000, v142
	v_mul_f32_e32 v132, 0xbfb8aa3b, v132
	v_max_f32_e32 v140, 1.0, v140
	v_rndne_f32_e32 v141, v141
	v_rndne_f32_e32 v142, v142
	v_exp_f32_e32 v132, v132
	v_cvt_u32_f32_e32 v140, v140
	v_mul_f32_e32 v137, 0x437f0000, v137
	v_cvt_u32_f32_e32 v136, v136
	v_max_f32_e32 v141, 1.0, v141
	v_max_f32_e32 v142, 1.0, v142
	v_rcp_f32_e32 v139, v139
	v_rndne_f32_e32 v137, v137
	v_cvt_u32_f32_sdwa v141, v141 dst_sel:WORD_1 dst_unused:UNUSED_PAD src0_sel:DWORD
	v_mul_f32_e32 v138, 0x437f0000, v138
	v_cvt_u32_f32_sdwa v142, v142 dst_sel:BYTE_3 dst_unused:UNUSED_PAD src0_sel:DWORD
	v_mul_f32_e32 v139, 0x437f0000, v139
	v_max_f32_e32 v137, 1.0, v137
	v_rndne_f32_e32 v138, v138
	v_rndne_f32_e32 v139, v139
	v_cvt_u32_f32_e32 v137, v137
	v_max_f32_e32 v138, 1.0, v138
	v_max_f32_e32 v139, 1.0, v139
	v_add_f32_e32 v132, 1.0, v132
	v_cvt_u32_f32_sdwa v138, v138 dst_sel:WORD_1 dst_unused:UNUSED_PAD src0_sel:DWORD
	v_cvt_u32_f32_sdwa v139, v139 dst_sel:BYTE_3 dst_unused:UNUSED_PAD src0_sel:DWORD
	v_lshl_or_b32 v136, v136, 8, v140
	v_or3_b32 v136, v136, v141, v142
	v_lshl_or_b32 v137, v137, 8, v175
	v_or3_b32 v137, v137, v138, v139
	global_store_dwordx2 v[166:167], v[136:137], off
	v_add_f32_e32 v128, v128, v32
	v_mul_f32_e32 v128, 0xbfb8aa3b, v128
	v_exp_f32_e32 v128, v128
	s_nop 0
	v_add_f32_e32 v128, 1.0, v128
	v_rcp_f32_e32 v132, v132
	v_add_f32_e32 v133, v133, v37
	v_mul_f32_e32 v133, 0xbfb8aa3b, v133
	v_exp_f32_e32 v133, v133
	s_nop 0
	v_add_f32_e32 v133, 1.0, v133
	v_rcp_f32_e32 v128, v128
	s_nop 0
	v_mul_f32_e32 v128, 0x437f0000, v128
	v_rndne_f32_e32 v128, v128
	v_max_f32_e32 v128, 1.0, v128
	v_cvt_u32_f32_e32 v138, v128
	v_add_f32_e32 v129, v129, v33
	v_mul_f32_e32 v129, 0xbfb8aa3b, v129
	v_exp_f32_e32 v129, v129
	s_nop 0
	v_add_f32_e32 v129, 1.0, v129
	v_rcp_f32_e32 v128, v133
	v_add_f32_e32 v134, v134, v38
	v_mul_f32_e32 v134, 0xbfb8aa3b, v134
	v_exp_f32_e32 v134, v134
	v_rcp_f32_e32 v129, v129
	v_add_f32_e32 v133, 1.0, v134
	v_add_f32_e32 v130, v130, v34
	v_mul_f32_e32 v130, 0xbfb8aa3b, v130
	v_exp_f32_e32 v130, v130
	s_nop 0
	v_add_f32_e32 v130, 1.0, v130
	v_rcp_f32_e32 v133, v133
	v_add_f32_e32 v135, v135, v39
	v_mul_f32_e32 v135, 0xbfb8aa3b, v135
	v_exp_f32_e32 v135, v135
	v_rcp_f32_e32 v130, v130
	v_add_f32_e32 v134, 1.0, v135
	v_add_f32_e32 v131, v131, v35
	v_mul_f32_e32 v131, 0xbfb8aa3b, v131
	v_exp_f32_e32 v131, v131
	s_nop 0
	v_add_f32_e32 v131, 1.0, v131
	v_rcp_f32_e32 v134, v134
	v_mul_f32_e32 v129, 0x437f0000, v129
	v_rndne_f32_e32 v129, v129
	v_mul_f32_e32 v130, 0x437f0000, v130
	v_rcp_f32_e32 v131, v131
	s_nop 0
	v_mul_f32_e32 v131, 0x437f0000, v131
	v_add_f32_e32 v124, v124, v52
	v_max_f32_e32 v129, 1.0, v129
	v_rndne_f32_e32 v130, v130
	v_rndne_f32_e32 v131, v131
	v_mul_f32_e32 v124, 0xbfb8aa3b, v124
	v_cvt_u32_f32_e32 v129, v129
	v_max_f32_e32 v130, 1.0, v130
	v_max_f32_e32 v131, 1.0, v131
	v_exp_f32_e32 v124, v124
	v_cvt_u32_f32_sdwa v130, v130 dst_sel:WORD_1 dst_unused:UNUSED_PAD src0_sel:DWORD
	v_cvt_u32_f32_sdwa v131, v131 dst_sel:BYTE_3 dst_unused:UNUSED_PAD src0_sel:DWORD
	v_mul_f32_e32 v132, 0x437f0000, v132
	v_mul_f32_e32 v128, 0x437f0000, v128
	v_rndne_f32_e32 v132, v132
	v_rndne_f32_e32 v128, v128
	v_lshl_or_b32 v129, v129, 8, v138
	v_add_f32_e32 v124, 1.0, v124
	v_max_f32_e32 v132, 1.0, v132
	v_max_f32_e32 v128, 1.0, v128
	v_mul_f32_e32 v133, 0x437f0000, v133
	v_mul_f32_e32 v134, 0x437f0000, v134
	v_or3_b32 v129, v129, v130, v131
	v_cvt_u32_f32_e32 v132, v132
	v_cvt_u32_f32_e32 v128, v128
	v_rndne_f32_e32 v133, v133
; __device__ __forceinline__ float sigmoidf_(float x) { return 1.0f / (1.0f + __expf(-x)); }
;     __device__ __forceinline__ void operator()(const f32x4 (&acc)[2][2][4][2], const Unit& u, int wr, int wc, int fr, int fq) const {
;     ...
;             for (int m = 0; m < 4; ++m) { unsigned char* rowp = O + (size_t)(row0 + ai * HALF + m * 16) * GP8 + col0;
; #pragma unroll
;                 for (int bj = 0; bj < 2; ++bj) { const f32x4 v0 = acc[ai][bj][m][0] + bv[bj][0], v1 = acc[ai][bj][m][1] + bv[bj][1];
;                     unsigned q[8];
; #pragma unroll
;                     for (int j = 0; j < 4; ++j) { q[j] = (unsigned)fmaxf(__builtin_rintf(sigmoidf_(v0[j]) * 255.f), 1.f); q[4 + j] = (unsigned)fmaxf(__builtin_rintf(sigmoidf_(v1[j]) * 255.f), 1.f); }
;                     u32x2 w; w.x = q[0] | (q[1] << 8) | (q[2] << 16) | (q[3] << 24); w.y = q[4] | (q[5] << 8) | (q[6] << 16) | (q[7] << 24);
;                     *(u32x2*)(rowp + bj * HALF) = w; } }
	v_rndne_f32_e32 v134, v134
	v_max_f32_e32 v133, 1.0, v133
	v_max_f32_e32 v134, 1.0, v134
	v_cvt_u32_f32_sdwa v133, v133 dst_sel:WORD_1 dst_unused:UNUSED_PAD src0_sel:DWORD
	v_cvt_u32_f32_sdwa v134, v134 dst_sel:BYTE_3 dst_unused:UNUSED_PAD src0_sel:DWORD
	v_lshl_or_b32 v128, v128, 8, v132
	v_add_f32_e32 v120, v120, v48
	v_mul_f32_e32 v120, 0xbfb8aa3b, v120
	v_or3_b32 v128, v128, v133, v134
	v_exp_f32_e32 v120, v120
	s_nop 0
	v_add_f32_e32 v120, 1.0, v120
	v_rcp_f32_e32 v124, v124
	v_add_f32_e32 v125, v125, v53
	v_mul_f32_e32 v125, 0xbfb8aa3b, v125
	v_exp_f32_e32 v125, v125
	s_nop 0
	v_add_f32_e32 v125, 1.0, v125
	v_rcp_f32_e32 v120, v120
	s_nop 0
	v_mul_f32_e32 v120, 0x437f0000, v120
	v_rndne_f32_e32 v120, v120
	v_max_f32_e32 v120, 1.0, v120
	v_cvt_u32_f32_e32 v132, v120
	v_add_f32_e32 v121, v121, v49
	v_mul_f32_e32 v121, 0xbfb8aa3b, v121
	v_exp_f32_e32 v121, v121
	s_nop 0
	v_add_f32_e32 v121, 1.0, v121
	v_rcp_f32_e32 v120, v125
	v_add_f32_e32 v126, v126, v54
	v_mul_f32_e32 v126, 0xbfb8aa3b, v126
	v_exp_f32_e32 v126, v126
	v_rcp_f32_e32 v121, v121
	v_add_f32_e32 v125, 1.0, v126
	v_add_f32_e32 v122, v122, v50
	v_mul_f32_e32 v122, 0xbfb8aa3b, v122
	v_exp_f32_e32 v122, v122
	s_nop 0
	v_add_f32_e32 v122, 1.0, v122
	v_rcp_f32_e32 v125, v125
	v_add_f32_e32 v127, v127, v55
	v_mul_f32_e32 v127, 0xbfb8aa3b, v127
	v_exp_f32_e32 v127, v127
	v_rcp_f32_e32 v122, v122
	v_add_f32_e32 v126, 1.0, v127
	v_add_f32_e32 v123, v123, v51
	v_mul_f32_e32 v123, 0xbfb8aa3b, v123
	v_exp_f32_e32 v123, v123
	s_nop 0
	v_add_f32_e32 v123, 1.0, v123
	v_rcp_f32_e32 v126, v126
	v_mul_f32_e32 v124, 0x437f0000, v124
	v_mul_f32_e32 v120, 0x437f0000, v120
	v_add_f32_e32 v116, v116, v36
	v_rndne_f32_e32 v124, v124
	v_rndne_f32_e32 v120, v120
	v_mul_f32_e32 v125, 0x437f0000, v125
	v_mul_f32_e32 v126, 0x437f0000, v126
	v_mul_f32_e32 v116, 0xbfb8aa3b, v116
	v_max_f32_e32 v124, 1.0, v124
	v_max_f32_e32 v120, 1.0, v120
	v_rndne_f32_e32 v125, v125
	v_rndne_f32_e32 v126, v126
	v_exp_f32_e32 v116, v116
	v_cvt_u32_f32_e32 v124, v124
	v_cvt_u32_f32_e32 v120, v120
	v_mul_f32_e32 v121, 0x437f0000, v121
	v_max_f32_e32 v125, 1.0, v125
	v_max_f32_e32 v126, 1.0, v126
	v_rcp_f32_e32 v123, v123
	v_rndne_f32_e32 v121, v121
	v_cvt_u32_f32_sdwa v125, v125 dst_sel:WORD_1 dst_unused:UNUSED_PAD src0_sel:DWORD
	v_mul_f32_e32 v122, 0x437f0000, v122
	v_cvt_u32_f32_sdwa v126, v126 dst_sel:BYTE_3 dst_unused:UNUSED_PAD src0_sel:DWORD
	v_mul_f32_e32 v123, 0x437f0000, v123
	v_max_f32_e32 v121, 1.0, v121
	v_rndne_f32_e32 v122, v122
	v_rndne_f32_e32 v123, v123
	v_cvt_u32_f32_e32 v121, v121
	v_max_f32_e32 v122, 1.0, v122
	v_max_f32_e32 v123, 1.0, v123
	v_add_f32_e32 v116, 1.0, v116
	v_cvt_u32_f32_sdwa v122, v122 dst_sel:WORD_1 dst_unused:UNUSED_PAD src0_sel:DWORD
	v_cvt_u32_f32_sdwa v123, v123 dst_sel:BYTE_3 dst_unused:UNUSED_PAD src0_sel:DWORD
	v_lshl_or_b32 v120, v120, 8, v124
	v_or3_b32 v120, v120, v125, v126
	global_store_dwordx2 v[166:167], v[128:129], off offset:128
	v_or_b32_e32 v128, 16, v174
	v_mad_i64_i32 v[128:129], s[2:3], v128, s55, v[164:165]
	v_lshl_or_b32 v121, v121, 8, v132
	v_lshl_add_u64 v[128:129], v[128:129], 0, v[162:163]
	v_or3_b32 v121, v121, v122, v123
	global_store_dwordx2 v[128:129], v[120:121], off
	v_add_f32_e32 v112, v112, v32
	v_mul_f32_e32 v112, 0xbfb8aa3b, v112
	v_exp_f32_e32 v112, v112
	s_nop 0
	v_add_f32_e32 v112, 1.0, v112
	v_rcp_f32_e32 v116, v116
	v_add_f32_e32 v117, v117, v37
	v_mul_f32_e32 v117, 0xbfb8aa3b, v117
	v_exp_f32_e32 v117, v117
	s_nop 0
	v_add_f32_e32 v117, 1.0, v117
	v_rcp_f32_e32 v112, v112
	s_nop 0
	v_mul_f32_e32 v112, 0x437f0000, v112
	v_rndne_f32_e32 v112, v112
	v_max_f32_e32 v112, 1.0, v112
	v_cvt_u32_f32_e32 v122, v112
	v_add_f32_e32 v113, v113, v33
	v_mul_f32_e32 v113, 0xbfb8aa3b, v113
	v_exp_f32_e32 v113, v113
	s_nop 0
	v_add_f32_e32 v113, 1.0, v113
	v_rcp_f32_e32 v112, v117
	v_add_f32_e32 v118, v118, v38
	v_mul_f32_e32 v118, 0xbfb8aa3b, v118
	v_exp_f32_e32 v118, v118
	v_rcp_f32_e32 v113, v113
	v_add_f32_e32 v117, 1.0, v118
	v_add_f32_e32 v114, v114, v34
	v_mul_f32_e32 v114, 0xbfb8aa3b, v114
	v_exp_f32_e32 v114, v114
	s_nop 0
	v_add_f32_e32 v114, 1.0, v114
	v_rcp_f32_e32 v117, v117
	v_add_f32_e32 v119, v119, v39
	v_mul_f32_e32 v119, 0xbfb8aa3b, v119
	v_exp_f32_e32 v119, v119
	v_rcp_f32_e32 v114, v114
	v_add_f32_e32 v118, 1.0, v119
	v_add_f32_e32 v115, v115, v35
	v_mul_f32_e32 v115, 0xbfb8aa3b, v115
	v_exp_f32_e32 v115, v115
	s_nop 0
	v_add_f32_e32 v115, 1.0, v115
	v_rcp_f32_e32 v118, v118
	v_mul_f32_e32 v113, 0x437f0000, v113
	v_rndne_f32_e32 v113, v113
	v_mul_f32_e32 v114, 0x437f0000, v114
	v_rcp_f32_e32 v115, v115
	s_nop 0
	v_mul_f32_e32 v115, 0x437f0000, v115
	v_add_f32_e32 v108, v108, v52
	v_max_f32_e32 v113, 1.0, v113
	v_rndne_f32_e32 v114, v114
	v_rndne_f32_e32 v115, v115
	v_mul_f32_e32 v108, 0xbfb8aa3b, v108
	v_cvt_u32_f32_e32 v113, v113
	v_max_f32_e32 v114, 1.0, v114
	v_max_f32_e32 v115, 1.0, v115
	v_exp_f32_e32 v108, v108
	v_cvt_u32_f32_sdwa v114, v114 dst_sel:WORD_1 dst_unused:UNUSED_PAD src0_sel:DWORD
	v_cvt_u32_f32_sdwa v115, v115 dst_sel:BYTE_3 dst_unused:UNUSED_PAD src0_sel:DWORD
	v_mul_f32_e32 v116, 0x437f0000, v116
	v_mul_f32_e32 v112, 0x437f0000, v112
	v_rndne_f32_e32 v116, v116
	v_rndne_f32_e32 v112, v112
	v_lshl_or_b32 v113, v113, 8, v122
	v_add_f32_e32 v108, 1.0, v108
	v_max_f32_e32 v116, 1.0, v116
	v_max_f32_e32 v112, 1.0, v112
	v_mul_f32_e32 v117, 0x437f0000, v117
	v_mul_f32_e32 v118, 0x437f0000, v118
	v_or3_b32 v113, v113, v114, v115
	v_cvt_u32_f32_e32 v116, v116
	v_cvt_u32_f32_e32 v112, v112
	v_rndne_f32_e32 v117, v117
	v_rndne_f32_e32 v118, v118
	v_max_f32_e32 v117, 1.0, v117
	v_max_f32_e32 v118, 1.0, v118
; __device__ __forceinline__ float sigmoidf_(float x) { return 1.0f / (1.0f + __expf(-x)); }
;     __device__ __forceinline__ void operator()(const f32x4 (&acc)[2][2][4][2], const Unit& u, int wr, int wc, int fr, int fq) const {
;     ...
;             for (int m = 0; m < 4; ++m) { unsigned char* rowp = O + (size_t)(row0 + ai * HALF + m * 16) * GP8 + col0;
; #pragma unroll
;                 for (int bj = 0; bj < 2; ++bj) { const f32x4 v0 = acc[ai][bj][m][0] + bv[bj][0], v1 = acc[ai][bj][m][1] + bv[bj][1];
;                     unsigned q[8];
; #pragma unroll
;                     for (int j = 0; j < 4; ++j) { q[j] = (unsigned)fmaxf(__builtin_rintf(sigmoidf_(v0[j]) * 255.f), 1.f); q[4 + j] = (unsigned)fmaxf(__builtin_rintf(sigmoidf_(v1[j]) * 255.f), 1.f); }
;                     u32x2 w; w.x = q[0] | (q[1] << 8) | (q[2] << 16) | (q[3] << 24); w.y = q[4] | (q[5] << 8) | (q[6] << 16) | (q[7] << 24);
;                     *(u32x2*)(rowp + bj * HALF) = w; } }
	v_cvt_u32_f32_sdwa v117, v117 dst_sel:WORD_1 dst_unused:UNUSED_PAD src0_sel:DWORD
	v_cvt_u32_f32_sdwa v118, v118 dst_sel:BYTE_3 dst_unused:UNUSED_PAD src0_sel:DWORD
	v_lshl_or_b32 v112, v112, 8, v116
	v_add_f32_e32 v104, v104, v48
	v_mul_f32_e32 v104, 0xbfb8aa3b, v104
	v_or3_b32 v112, v112, v117, v118
	v_exp_f32_e32 v104, v104
	s_nop 0
	v_add_f32_e32 v104, 1.0, v104
	v_rcp_f32_e32 v108, v108
	v_add_f32_e32 v109, v109, v53
	v_mul_f32_e32 v109, 0xbfb8aa3b, v109
	v_exp_f32_e32 v109, v109
	s_nop 0
	v_add_f32_e32 v109, 1.0, v109
	v_rcp_f32_e32 v104, v104
	s_nop 0
	v_mul_f32_e32 v104, 0x437f0000, v104
	v_rndne_f32_e32 v104, v104
	v_max_f32_e32 v104, 1.0, v104
	v_cvt_u32_f32_e32 v116, v104
	v_add_f32_e32 v105, v105, v49
	v_mul_f32_e32 v105, 0xbfb8aa3b, v105
	v_exp_f32_e32 v105, v105
	s_nop 0
	v_add_f32_e32 v105, 1.0, v105
	v_rcp_f32_e32 v104, v109
	v_add_f32_e32 v110, v110, v54
	v_mul_f32_e32 v110, 0xbfb8aa3b, v110
	v_exp_f32_e32 v110, v110
	v_rcp_f32_e32 v105, v105
	v_add_f32_e32 v109, 1.0, v110
	v_add_f32_e32 v106, v106, v50
	v_mul_f32_e32 v106, 0xbfb8aa3b, v106
	v_exp_f32_e32 v106, v106
	s_nop 0
	v_add_f32_e32 v106, 1.0, v106
	v_rcp_f32_e32 v109, v109
	v_add_f32_e32 v111, v111, v55
	v_mul_f32_e32 v111, 0xbfb8aa3b, v111
	v_exp_f32_e32 v111, v111
	v_rcp_f32_e32 v106, v106
	v_add_f32_e32 v110, 1.0, v111
	v_add_f32_e32 v107, v107, v51
	v_mul_f32_e32 v107, 0xbfb8aa3b, v107
	v_exp_f32_e32 v107, v107
	s_nop 0
	v_add_f32_e32 v107, 1.0, v107
	v_rcp_f32_e32 v110, v110
	v_mul_f32_e32 v108, 0x437f0000, v108
	v_mul_f32_e32 v104, 0x437f0000, v104
	v_add_f32_e32 v100, v100, v36
	v_rndne_f32_e32 v108, v108
	v_rndne_f32_e32 v104, v104
	v_mul_f32_e32 v109, 0x437f0000, v109
	v_mul_f32_e32 v110, 0x437f0000, v110
	v_mul_f32_e32 v100, 0xbfb8aa3b, v100
	v_max_f32_e32 v108, 1.0, v108
	v_max_f32_e32 v104, 1.0, v104
	v_rndne_f32_e32 v109, v109
	v_rndne_f32_e32 v110, v110
	v_exp_f32_e32 v100, v100
	v_cvt_u32_f32_e32 v108, v108
	v_cvt_u32_f32_e32 v104, v104
	v_mul_f32_e32 v105, 0x437f0000, v105
	v_max_f32_e32 v109, 1.0, v109
	v_max_f32_e32 v110, 1.0, v110
	v_rcp_f32_e32 v107, v107
	v_rndne_f32_e32 v105, v105
	v_cvt_u32_f32_sdwa v109, v109 dst_sel:WORD_1 dst_unused:UNUSED_PAD src0_sel:DWORD
	v_mul_f32_e32 v106, 0x437f0000, v106
	v_cvt_u32_f32_sdwa v110, v110 dst_sel:BYTE_3 dst_unused:UNUSED_PAD src0_sel:DWORD
	v_mul_f32_e32 v107, 0x437f0000, v107
	v_max_f32_e32 v105, 1.0, v105
	v_rndne_f32_e32 v106, v106
	v_rndne_f32_e32 v107, v107
	v_cvt_u32_f32_e32 v105, v105
	v_max_f32_e32 v106, 1.0, v106
	v_max_f32_e32 v107, 1.0, v107
	v_add_f32_e32 v100, 1.0, v100
	v_cvt_u32_f32_sdwa v106, v106 dst_sel:WORD_1 dst_unused:UNUSED_PAD src0_sel:DWORD
	v_cvt_u32_f32_sdwa v107, v107 dst_sel:BYTE_3 dst_unused:UNUSED_PAD src0_sel:DWORD
	v_lshl_or_b32 v104, v104, 8, v108
	v_or3_b32 v104, v104, v109, v110
	global_store_dwordx2 v[128:129], v[112:113], off offset:128
	v_or_b32_e32 v112, 32, v174
	v_mad_i64_i32 v[112:113], s[2:3], v112, s55, v[164:165]
	v_lshl_or_b32 v105, v105, 8, v116
	v_lshl_add_u64 v[112:113], v[112:113], 0, v[162:163]
	v_or3_b32 v105, v105, v106, v107
	global_store_dwordx2 v[112:113], v[104:105], off
	v_add_f32_e32 v96, v96, v32
	v_mul_f32_e32 v96, 0xbfb8aa3b, v96
	v_exp_f32_e32 v96, v96
	s_nop 0
	v_add_f32_e32 v96, 1.0, v96
	v_rcp_f32_e32 v100, v100
	v_add_f32_e32 v101, v101, v37
	v_mul_f32_e32 v101, 0xbfb8aa3b, v101
	v_exp_f32_e32 v101, v101
	s_nop 0
	v_add_f32_e32 v101, 1.0, v101
	v_rcp_f32_e32 v96, v96
	s_nop 0
	v_mul_f32_e32 v96, 0x437f0000, v96
	v_rndne_f32_e32 v96, v96
	v_max_f32_e32 v96, 1.0, v96
	v_cvt_u32_f32_e32 v106, v96
	v_add_f32_e32 v97, v97, v33
	v_mul_f32_e32 v97, 0xbfb8aa3b, v97
	v_exp_f32_e32 v97, v97
	s_nop 0
	v_add_f32_e32 v97, 1.0, v97
	v_rcp_f32_e32 v96, v101
	v_add_f32_e32 v102, v102, v38
	v_mul_f32_e32 v102, 0xbfb8aa3b, v102
	v_exp_f32_e32 v102, v102
	v_rcp_f32_e32 v97, v97
	v_add_f32_e32 v101, 1.0, v102
	v_add_f32_e32 v98, v98, v34
	v_mul_f32_e32 v98, 0xbfb8aa3b, v98
	v_exp_f32_e32 v98, v98
	s_nop 0
	v_add_f32_e32 v98, 1.0, v98
	v_rcp_f32_e32 v101, v101
	v_add_f32_e32 v103, v103, v39
	v_mul_f32_e32 v103, 0xbfb8aa3b, v103
	v_exp_f32_e32 v103, v103
	v_rcp_f32_e32 v98, v98
	v_add_f32_e32 v102, 1.0, v103
	v_add_f32_e32 v99, v99, v35
	v_mul_f32_e32 v99, 0xbfb8aa3b, v99
	v_exp_f32_e32 v99, v99
	s_nop 0
	v_add_f32_e32 v99, 1.0, v99
	v_rcp_f32_e32 v102, v102
	v_mul_f32_e32 v97, 0x437f0000, v97
	v_rndne_f32_e32 v97, v97
	v_mul_f32_e32 v98, 0x437f0000, v98
	v_rcp_f32_e32 v99, v99
	s_nop 0
	v_mul_f32_e32 v99, 0x437f0000, v99
	v_add_f32_e32 v92, v92, v52
	v_max_f32_e32 v97, 1.0, v97
	v_rndne_f32_e32 v98, v98
	v_rndne_f32_e32 v99, v99
	v_mul_f32_e32 v92, 0xbfb8aa3b, v92
	v_cvt_u32_f32_e32 v97, v97
	v_max_f32_e32 v98, 1.0, v98
	v_max_f32_e32 v99, 1.0, v99
	v_exp_f32_e32 v92, v92
	v_cvt_u32_f32_sdwa v98, v98 dst_sel:WORD_1 dst_unused:UNUSED_PAD src0_sel:DWORD
	v_cvt_u32_f32_sdwa v99, v99 dst_sel:BYTE_3 dst_unused:UNUSED_PAD src0_sel:DWORD
	v_mul_f32_e32 v100, 0x437f0000, v100
	v_mul_f32_e32 v96, 0x437f0000, v96
	v_rndne_f32_e32 v100, v100
	v_rndne_f32_e32 v96, v96
	v_lshl_or_b32 v97, v97, 8, v106
	v_add_f32_e32 v92, 1.0, v92
	v_max_f32_e32 v100, 1.0, v100
	v_max_f32_e32 v96, 1.0, v96
	v_mul_f32_e32 v101, 0x437f0000, v101
	v_mul_f32_e32 v102, 0x437f0000, v102
	v_or3_b32 v97, v97, v98, v99
	v_cvt_u32_f32_e32 v100, v100
	v_cvt_u32_f32_e32 v96, v96
	v_rndne_f32_e32 v101, v101
	v_rndne_f32_e32 v102, v102
	v_max_f32_e32 v101, 1.0, v101
	v_max_f32_e32 v102, 1.0, v102
	v_cvt_u32_f32_sdwa v101, v101 dst_sel:WORD_1 dst_unused:UNUSED_PAD src0_sel:DWORD
	v_cvt_u32_f32_sdwa v102, v102 dst_sel:BYTE_3 dst_unused:UNUSED_PAD src0_sel:DWORD
	v_lshl_or_b32 v96, v96, 8, v100
; __device__ __forceinline__ float sigmoidf_(float x) { return 1.0f / (1.0f + __expf(-x)); }
;     __device__ __forceinline__ void operator()(const f32x4 (&acc)[2][2][4][2], const Unit& u, int wr, int wc, int fr, int fq) const {
;     ...
;             for (int m = 0; m < 4; ++m) { unsigned char* rowp = O + (size_t)(row0 + ai * HALF + m * 16) * GP8 + col0;
; #pragma unroll
;                 for (int bj = 0; bj < 2; ++bj) { const f32x4 v0 = acc[ai][bj][m][0] + bv[bj][0], v1 = acc[ai][bj][m][1] + bv[bj][1];
;                     unsigned q[8];
; #pragma unroll
;                     for (int j = 0; j < 4; ++j) { q[j] = (unsigned)fmaxf(__builtin_rintf(sigmoidf_(v0[j]) * 255.f), 1.f); q[4 + j] = (unsigned)fmaxf(__builtin_rintf(sigmoidf_(v1[j]) * 255.f), 1.f); }
;                     u32x2 w; w.x = q[0] | (q[1] << 8) | (q[2] << 16) | (q[3] << 24); w.y = q[4] | (q[5] << 8) | (q[6] << 16) | (q[7] << 24);
;                     *(u32x2*)(rowp + bj * HALF) = w; } }
	v_add_f32_e32 v88, v88, v48
	v_mul_f32_e32 v88, 0xbfb8aa3b, v88
	v_or3_b32 v96, v96, v101, v102
	v_exp_f32_e32 v88, v88
	s_nop 0
	v_add_f32_e32 v88, 1.0, v88
	v_rcp_f32_e32 v92, v92
	v_add_f32_e32 v93, v93, v53
	v_mul_f32_e32 v93, 0xbfb8aa3b, v93
	v_exp_f32_e32 v93, v93
	s_nop 0
	v_add_f32_e32 v93, 1.0, v93
	v_rcp_f32_e32 v88, v88
	s_nop 0
	v_mul_f32_e32 v88, 0x437f0000, v88
	v_rndne_f32_e32 v88, v88
	v_max_f32_e32 v88, 1.0, v88
	v_cvt_u32_f32_e32 v100, v88
	v_add_f32_e32 v89, v89, v49
	v_mul_f32_e32 v89, 0xbfb8aa3b, v89
	v_exp_f32_e32 v89, v89
	s_nop 0
	v_add_f32_e32 v89, 1.0, v89
	v_rcp_f32_e32 v88, v93
	v_add_f32_e32 v94, v94, v54
	v_mul_f32_e32 v94, 0xbfb8aa3b, v94
	v_exp_f32_e32 v94, v94
	v_rcp_f32_e32 v89, v89
	v_add_f32_e32 v93, 1.0, v94
	v_add_f32_e32 v90, v90, v50
	v_mul_f32_e32 v90, 0xbfb8aa3b, v90
	v_exp_f32_e32 v90, v90
	s_nop 0
	v_add_f32_e32 v90, 1.0, v90
	v_rcp_f32_e32 v93, v93
	v_add_f32_e32 v95, v95, v55
	v_mul_f32_e32 v95, 0xbfb8aa3b, v95
	v_exp_f32_e32 v95, v95
	v_rcp_f32_e32 v90, v90
	v_add_f32_e32 v94, 1.0, v95
	v_add_f32_e32 v91, v91, v51
	v_mul_f32_e32 v91, 0xbfb8aa3b, v91
	v_exp_f32_e32 v91, v91
	s_nop 0
	v_add_f32_e32 v91, 1.0, v91
	v_rcp_f32_e32 v94, v94
	v_mul_f32_e32 v92, 0x437f0000, v92
	v_mul_f32_e32 v88, 0x437f0000, v88
	v_add_f32_e32 v84, v84, v36
	v_rndne_f32_e32 v92, v92
	v_rndne_f32_e32 v88, v88
	v_mul_f32_e32 v93, 0x437f0000, v93
	v_mul_f32_e32 v94, 0x437f0000, v94
	v_mul_f32_e32 v84, 0xbfb8aa3b, v84
	v_max_f32_e32 v92, 1.0, v92
	v_max_f32_e32 v88, 1.0, v88
	v_rndne_f32_e32 v93, v93
	v_rndne_f32_e32 v94, v94
	v_exp_f32_e32 v84, v84
	v_cvt_u32_f32_e32 v92, v92
	v_cvt_u32_f32_e32 v88, v88
	v_mul_f32_e32 v89, 0x437f0000, v89
	v_max_f32_e32 v93, 1.0, v93
	v_max_f32_e32 v94, 1.0, v94
	v_rcp_f32_e32 v91, v91
	v_rndne_f32_e32 v89, v89
	v_cvt_u32_f32_sdwa v93, v93 dst_sel:WORD_1 dst_unused:UNUSED_PAD src0_sel:DWORD
	v_mul_f32_e32 v90, 0x437f0000, v90
	v_cvt_u32_f32_sdwa v94, v94 dst_sel:BYTE_3 dst_unused:UNUSED_PAD src0_sel:DWORD
	v_mul_f32_e32 v91, 0x437f0000, v91
	v_max_f32_e32 v89, 1.0, v89
	v_rndne_f32_e32 v90, v90
	v_rndne_f32_e32 v91, v91
	v_cvt_u32_f32_e32 v89, v89
	v_max_f32_e32 v90, 1.0, v90
	v_max_f32_e32 v91, 1.0, v91
	v_add_f32_e32 v84, 1.0, v84
	v_cvt_u32_f32_sdwa v90, v90 dst_sel:WORD_1 dst_unused:UNUSED_PAD src0_sel:DWORD
	v_cvt_u32_f32_sdwa v91, v91 dst_sel:BYTE_3 dst_unused:UNUSED_PAD src0_sel:DWORD
	v_lshl_or_b32 v88, v88, 8, v92
	v_or3_b32 v88, v88, v93, v94
	global_store_dwordx2 v[112:113], v[96:97], off offset:128
	v_or_b32_e32 v96, 48, v174
	v_mad_i64_i32 v[96:97], s[2:3], v96, s55, v[164:165]
	v_lshl_or_b32 v89, v89, 8, v100
	v_lshl_add_u64 v[96:97], v[96:97], 0, v[162:163]
	v_or3_b32 v89, v89, v90, v91
	global_store_dwordx2 v[96:97], v[88:89], off
	v_add_f32_e32 v80, v80, v32
	v_mul_f32_e32 v80, 0xbfb8aa3b, v80
	v_exp_f32_e32 v80, v80
	s_nop 0
	v_add_f32_e32 v80, 1.0, v80
	v_rcp_f32_e32 v84, v84
	v_add_f32_e32 v85, v85, v37
	v_mul_f32_e32 v85, 0xbfb8aa3b, v85
	v_exp_f32_e32 v85, v85
	s_nop 0
	v_add_f32_e32 v85, 1.0, v85
	v_rcp_f32_e32 v80, v80
	s_nop 0
	v_mul_f32_e32 v80, 0x437f0000, v80
	v_rndne_f32_e32 v80, v80
	v_max_f32_e32 v80, 1.0, v80
	v_cvt_u32_f32_e32 v90, v80
	v_add_f32_e32 v81, v81, v33
	v_mul_f32_e32 v81, 0xbfb8aa3b, v81
	v_exp_f32_e32 v81, v81
	s_nop 0
	v_add_f32_e32 v81, 1.0, v81
	v_rcp_f32_e32 v80, v85
	v_add_f32_e32 v86, v86, v38
	v_mul_f32_e32 v86, 0xbfb8aa3b, v86
	v_exp_f32_e32 v86, v86
	v_rcp_f32_e32 v81, v81
	v_add_f32_e32 v85, 1.0, v86
	v_add_f32_e32 v82, v82, v34
	v_mul_f32_e32 v82, 0xbfb8aa3b, v82
	v_exp_f32_e32 v82, v82
	s_nop 0
	v_add_f32_e32 v82, 1.0, v82
	v_rcp_f32_e32 v85, v85
	v_add_f32_e32 v87, v87, v39
	v_mul_f32_e32 v87, 0xbfb8aa3b, v87
	v_exp_f32_e32 v87, v87
	v_rcp_f32_e32 v82, v82
	v_add_f32_e32 v86, 1.0, v87
	v_add_f32_e32 v83, v83, v35
	v_mul_f32_e32 v83, 0xbfb8aa3b, v83
	v_exp_f32_e32 v83, v83
	s_nop 0
	v_add_f32_e32 v83, 1.0, v83
	v_rcp_f32_e32 v86, v86
	v_mul_f32_e32 v81, 0x437f0000, v81
	v_rndne_f32_e32 v81, v81
	v_mul_f32_e32 v82, 0x437f0000, v82
	v_rcp_f32_e32 v83, v83
	s_nop 0
	v_mul_f32_e32 v83, 0x437f0000, v83
	v_add_f32_e32 v76, v76, v52
	v_max_f32_e32 v81, 1.0, v81
	v_rndne_f32_e32 v82, v82
	v_rndne_f32_e32 v83, v83
	v_mul_f32_e32 v76, 0xbfb8aa3b, v76
	v_cvt_u32_f32_e32 v81, v81
	v_max_f32_e32 v82, 1.0, v82
	v_max_f32_e32 v83, 1.0, v83
	v_exp_f32_e32 v76, v76
	v_cvt_u32_f32_sdwa v82, v82 dst_sel:WORD_1 dst_unused:UNUSED_PAD src0_sel:DWORD
	v_cvt_u32_f32_sdwa v83, v83 dst_sel:BYTE_3 dst_unused:UNUSED_PAD src0_sel:DWORD
	v_mul_f32_e32 v84, 0x437f0000, v84
	v_mul_f32_e32 v80, 0x437f0000, v80
	v_rndne_f32_e32 v84, v84
	v_rndne_f32_e32 v80, v80
	v_lshl_or_b32 v81, v81, 8, v90
	v_add_f32_e32 v76, 1.0, v76
	v_max_f32_e32 v84, 1.0, v84
	v_max_f32_e32 v80, 1.0, v80
	v_mul_f32_e32 v85, 0x437f0000, v85
	v_mul_f32_e32 v86, 0x437f0000, v86
	v_or3_b32 v81, v81, v82, v83
	v_cvt_u32_f32_e32 v84, v84
	v_cvt_u32_f32_e32 v80, v80
	v_rndne_f32_e32 v85, v85
	v_rndne_f32_e32 v86, v86
	v_max_f32_e32 v85, 1.0, v85
	v_max_f32_e32 v86, 1.0, v86
	v_cvt_u32_f32_sdwa v85, v85 dst_sel:WORD_1 dst_unused:UNUSED_PAD src0_sel:DWORD
	v_cvt_u32_f32_sdwa v86, v86 dst_sel:BYTE_3 dst_unused:UNUSED_PAD src0_sel:DWORD
	v_lshl_or_b32 v80, v80, 8, v84
	v_add_f32_e32 v72, v72, v48
	v_mul_f32_e32 v72, 0xbfb8aa3b, v72
	v_or3_b32 v80, v80, v85, v86
	v_exp_f32_e32 v72, v72
	s_nop 0
	v_add_f32_e32 v72, 1.0, v72
	v_rcp_f32_e32 v76, v76
	v_add_f32_e32 v77, v77, v53
	v_mul_f32_e32 v77, 0xbfb8aa3b, v77
	v_exp_f32_e32 v77, v77
	s_nop 0
	v_add_f32_e32 v77, 1.0, v77
	v_rcp_f32_e32 v72, v72
	s_nop 0
	v_mul_f32_e32 v72, 0x437f0000, v72
	v_rndne_f32_e32 v72, v72
	v_max_f32_e32 v72, 1.0, v72
; __device__ __forceinline__ float sigmoidf_(float x) { return 1.0f / (1.0f + __expf(-x)); }
;     __device__ __forceinline__ void operator()(const f32x4 (&acc)[2][2][4][2], const Unit& u, int wr, int wc, int fr, int fq) const {
;     ...
;             for (int m = 0; m < 4; ++m) { unsigned char* rowp = O + (size_t)(row0 + ai * HALF + m * 16) * GP8 + col0;
; #pragma unroll
;                 for (int bj = 0; bj < 2; ++bj) { const f32x4 v0 = acc[ai][bj][m][0] + bv[bj][0], v1 = acc[ai][bj][m][1] + bv[bj][1];
;                     unsigned q[8];
; #pragma unroll
;                     for (int j = 0; j < 4; ++j) { q[j] = (unsigned)fmaxf(__builtin_rintf(sigmoidf_(v0[j]) * 255.f), 1.f); q[4 + j] = (unsigned)fmaxf(__builtin_rintf(sigmoidf_(v1[j]) * 255.f), 1.f); }
;                     u32x2 w; w.x = q[0] | (q[1] << 8) | (q[2] << 16) | (q[3] << 24); w.y = q[4] | (q[5] << 8) | (q[6] << 16) | (q[7] << 24);
;                     *(u32x2*)(rowp + bj * HALF) = w; } }
	v_cvt_u32_f32_e32 v84, v72
	v_add_f32_e32 v73, v73, v49
	v_mul_f32_e32 v73, 0xbfb8aa3b, v73
	v_exp_f32_e32 v73, v73
	s_nop 0
	v_add_f32_e32 v73, 1.0, v73
	v_rcp_f32_e32 v72, v77
	v_add_f32_e32 v78, v78, v54
	v_mul_f32_e32 v78, 0xbfb8aa3b, v78
	v_exp_f32_e32 v78, v78
	v_rcp_f32_e32 v73, v73
	v_add_f32_e32 v77, 1.0, v78
	v_add_f32_e32 v74, v74, v50
	v_mul_f32_e32 v74, 0xbfb8aa3b, v74
	v_exp_f32_e32 v74, v74
	s_nop 0
	v_add_f32_e32 v74, 1.0, v74
	v_rcp_f32_e32 v77, v77
	v_add_f32_e32 v79, v79, v55
	v_mul_f32_e32 v79, 0xbfb8aa3b, v79
	v_exp_f32_e32 v79, v79
	v_rcp_f32_e32 v74, v74
	v_add_f32_e32 v78, 1.0, v79
	v_add_f32_e32 v75, v75, v51
	v_mul_f32_e32 v75, 0xbfb8aa3b, v75
	v_exp_f32_e32 v75, v75
	s_nop 0
	v_add_f32_e32 v75, 1.0, v75
	v_rcp_f32_e32 v78, v78
	v_mul_f32_e32 v76, 0x437f0000, v76
	v_mul_f32_e32 v72, 0x437f0000, v72
	v_add_f32_e32 v68, v68, v36
	v_rndne_f32_e32 v76, v76
	v_rndne_f32_e32 v72, v72
	v_mul_f32_e32 v77, 0x437f0000, v77
	v_mul_f32_e32 v78, 0x437f0000, v78
	v_mul_f32_e32 v68, 0xbfb8aa3b, v68
	v_max_f32_e32 v76, 1.0, v76
	v_max_f32_e32 v72, 1.0, v72
	v_rndne_f32_e32 v77, v77
	v_rndne_f32_e32 v78, v78
	v_exp_f32_e32 v68, v68
	v_cvt_u32_f32_e32 v76, v76
	v_cvt_u32_f32_e32 v72, v72
	v_mul_f32_e32 v73, 0x437f0000, v73
	v_max_f32_e32 v77, 1.0, v77
	v_max_f32_e32 v78, 1.0, v78
	v_rcp_f32_e32 v75, v75
	v_rndne_f32_e32 v73, v73
	v_cvt_u32_f32_sdwa v77, v77 dst_sel:WORD_1 dst_unused:UNUSED_PAD src0_sel:DWORD
	v_mul_f32_e32 v74, 0x437f0000, v74
	v_cvt_u32_f32_sdwa v78, v78 dst_sel:BYTE_3 dst_unused:UNUSED_PAD src0_sel:DWORD
	v_mul_f32_e32 v75, 0x437f0000, v75
	v_max_f32_e32 v73, 1.0, v73
	v_rndne_f32_e32 v74, v74
	v_rndne_f32_e32 v75, v75
	v_cvt_u32_f32_e32 v73, v73
	v_max_f32_e32 v74, 1.0, v74
	v_max_f32_e32 v75, 1.0, v75
	v_add_f32_e32 v68, 1.0, v68
	v_cvt_u32_f32_sdwa v74, v74 dst_sel:WORD_1 dst_unused:UNUSED_PAD src0_sel:DWORD
	v_cvt_u32_f32_sdwa v75, v75 dst_sel:BYTE_3 dst_unused:UNUSED_PAD src0_sel:DWORD
	v_lshl_or_b32 v72, v72, 8, v76
	v_or3_b32 v72, v72, v77, v78
	global_store_dwordx2 v[96:97], v[80:81], off offset:128
	v_add_u32_e32 v80, 0x80, v174
	v_mad_i64_i32 v[80:81], s[2:3], v80, s55, v[164:165]
	v_lshl_or_b32 v73, v73, 8, v84
	v_lshl_add_u64 v[80:81], v[80:81], 0, v[162:163]
	v_or3_b32 v73, v73, v74, v75
	global_store_dwordx2 v[80:81], v[72:73], off
	v_add_f32_e32 v64, v64, v32
	v_mul_f32_e32 v64, 0xbfb8aa3b, v64
	v_exp_f32_e32 v64, v64
	s_nop 0
	v_add_f32_e32 v64, 1.0, v64
	v_rcp_f32_e32 v68, v68
	v_add_f32_e32 v69, v69, v37
	v_mul_f32_e32 v69, 0xbfb8aa3b, v69
	v_exp_f32_e32 v69, v69
	s_nop 0
	v_add_f32_e32 v69, 1.0, v69
	v_rcp_f32_e32 v64, v64
	s_nop 0
	v_mul_f32_e32 v64, 0x437f0000, v64
	v_rndne_f32_e32 v64, v64
	v_max_f32_e32 v64, 1.0, v64
	v_cvt_u32_f32_e32 v74, v64
	v_add_f32_e32 v65, v65, v33
	v_mul_f32_e32 v65, 0xbfb8aa3b, v65
	v_exp_f32_e32 v65, v65
	s_nop 0
	v_add_f32_e32 v65, 1.0, v65
	v_rcp_f32_e32 v64, v69
	v_add_f32_e32 v70, v70, v38
	v_mul_f32_e32 v70, 0xbfb8aa3b, v70
	v_exp_f32_e32 v70, v70
	v_rcp_f32_e32 v65, v65
	v_add_f32_e32 v69, 1.0, v70
	v_add_f32_e32 v66, v66, v34
	v_mul_f32_e32 v66, 0xbfb8aa3b, v66
	v_exp_f32_e32 v66, v66
	s_nop 0
	v_add_f32_e32 v66, 1.0, v66
	v_rcp_f32_e32 v69, v69
	v_add_f32_e32 v71, v71, v39
	v_mul_f32_e32 v71, 0xbfb8aa3b, v71
	v_exp_f32_e32 v71, v71
	v_rcp_f32_e32 v66, v66
	v_add_f32_e32 v70, 1.0, v71
	v_add_f32_e32 v67, v67, v35
	v_mul_f32_e32 v67, 0xbfb8aa3b, v67
	v_exp_f32_e32 v67, v67
	s_nop 0
	v_add_f32_e32 v67, 1.0, v67
	v_rcp_f32_e32 v70, v70
	v_mul_f32_e32 v65, 0x437f0000, v65
	v_rndne_f32_e32 v65, v65
	v_mul_f32_e32 v66, 0x437f0000, v66
	v_rcp_f32_e32 v67, v67
	s_nop 0
	v_mul_f32_e32 v67, 0x437f0000, v67
	v_add_f32_e32 v60, v60, v52
	v_max_f32_e32 v65, 1.0, v65
	v_rndne_f32_e32 v66, v66
	v_rndne_f32_e32 v67, v67
	v_mul_f32_e32 v60, 0xbfb8aa3b, v60
	v_cvt_u32_f32_e32 v65, v65
	v_max_f32_e32 v66, 1.0, v66
	v_max_f32_e32 v67, 1.0, v67
	v_exp_f32_e32 v60, v60
	v_cvt_u32_f32_sdwa v66, v66 dst_sel:WORD_1 dst_unused:UNUSED_PAD src0_sel:DWORD
	v_cvt_u32_f32_sdwa v67, v67 dst_sel:BYTE_3 dst_unused:UNUSED_PAD src0_sel:DWORD
	v_mul_f32_e32 v68, 0x437f0000, v68
	v_mul_f32_e32 v64, 0x437f0000, v64
	v_rndne_f32_e32 v68, v68
	v_rndne_f32_e32 v64, v64
	v_lshl_or_b32 v65, v65, 8, v74
	v_add_f32_e32 v60, 1.0, v60
	v_max_f32_e32 v68, 1.0, v68
	v_max_f32_e32 v64, 1.0, v64
	v_mul_f32_e32 v69, 0x437f0000, v69
	v_mul_f32_e32 v70, 0x437f0000, v70
	v_or3_b32 v65, v65, v66, v67
	v_cvt_u32_f32_e32 v68, v68
	v_cvt_u32_f32_e32 v64, v64
	v_rndne_f32_e32 v69, v69
	v_rndne_f32_e32 v70, v70
	v_max_f32_e32 v69, 1.0, v69
	v_max_f32_e32 v70, 1.0, v70
	v_cvt_u32_f32_sdwa v69, v69 dst_sel:WORD_1 dst_unused:UNUSED_PAD src0_sel:DWORD
	v_cvt_u32_f32_sdwa v70, v70 dst_sel:BYTE_3 dst_unused:UNUSED_PAD src0_sel:DWORD
	v_lshl_or_b32 v64, v64, 8, v68
	v_add_f32_e32 v56, v56, v48
	v_mul_f32_e32 v56, 0xbfb8aa3b, v56
	v_or3_b32 v64, v64, v69, v70
	v_exp_f32_e32 v56, v56
	s_nop 0
	v_add_f32_e32 v56, 1.0, v56
	v_rcp_f32_e32 v60, v60
	v_add_f32_e32 v61, v61, v53
	v_mul_f32_e32 v61, 0xbfb8aa3b, v61
	v_exp_f32_e32 v61, v61
	s_nop 0
	v_add_f32_e32 v61, 1.0, v61
	v_rcp_f32_e32 v56, v56
	s_nop 0
	v_mul_f32_e32 v56, 0x437f0000, v56
	v_rndne_f32_e32 v56, v56
	v_max_f32_e32 v56, 1.0, v56
	v_cvt_u32_f32_e32 v68, v56
	v_add_f32_e32 v57, v57, v49
	v_mul_f32_e32 v57, 0xbfb8aa3b, v57
	v_exp_f32_e32 v57, v57
	s_nop 0
	v_add_f32_e32 v57, 1.0, v57
	v_rcp_f32_e32 v56, v61
	v_add_f32_e32 v62, v62, v54
	v_mul_f32_e32 v62, 0xbfb8aa3b, v62
	v_exp_f32_e32 v62, v62
	v_rcp_f32_e32 v57, v57
	v_add_f32_e32 v61, 1.0, v62
	v_add_f32_e32 v58, v58, v50
	v_mul_f32_e32 v58, 0xbfb8aa3b, v58
	v_exp_f32_e32 v58, v58
	s_nop 0
	v_add_f32_e32 v58, 1.0, v58
; __device__ __forceinline__ float sigmoidf_(float x) { return 1.0f / (1.0f + __expf(-x)); }
;     __device__ __forceinline__ void operator()(const f32x4 (&acc)[2][2][4][2], const Unit& u, int wr, int wc, int fr, int fq) const {
;     ...
;             for (int m = 0; m < 4; ++m) { unsigned char* rowp = O + (size_t)(row0 + ai * HALF + m * 16) * GP8 + col0;
; #pragma unroll
;                 for (int bj = 0; bj < 2; ++bj) { const f32x4 v0 = acc[ai][bj][m][0] + bv[bj][0], v1 = acc[ai][bj][m][1] + bv[bj][1];
;                     unsigned q[8];
; #pragma unroll
;                     for (int j = 0; j < 4; ++j) { q[j] = (unsigned)fmaxf(__builtin_rintf(sigmoidf_(v0[j]) * 255.f), 1.f); q[4 + j] = (unsigned)fmaxf(__builtin_rintf(sigmoidf_(v1[j]) * 255.f), 1.f); }
;                     u32x2 w; w.x = q[0] | (q[1] << 8) | (q[2] << 16) | (q[3] << 24); w.y = q[4] | (q[5] << 8) | (q[6] << 16) | (q[7] << 24);
;                     *(u32x2*)(rowp + bj * HALF) = w; } }
	v_rcp_f32_e32 v61, v61
	v_add_f32_e32 v63, v63, v55
	v_mul_f32_e32 v63, 0xbfb8aa3b, v63
	v_exp_f32_e32 v63, v63
	v_rcp_f32_e32 v58, v58
	v_add_f32_e32 v62, 1.0, v63
	v_add_f32_e32 v59, v59, v51
	v_mul_f32_e32 v59, 0xbfb8aa3b, v59
	v_exp_f32_e32 v59, v59
	s_nop 0
	v_add_f32_e32 v59, 1.0, v59
	v_rcp_f32_e32 v62, v62
	v_mul_f32_e32 v60, 0x437f0000, v60
	v_mul_f32_e32 v56, 0x437f0000, v56
	v_add_f32_e32 v44, v44, v36
	v_rndne_f32_e32 v60, v60
	v_rndne_f32_e32 v56, v56
	v_mul_f32_e32 v61, 0x437f0000, v61
	v_mul_f32_e32 v62, 0x437f0000, v62
	v_mul_f32_e32 v44, 0xbfb8aa3b, v44
	v_max_f32_e32 v60, 1.0, v60
	v_max_f32_e32 v56, 1.0, v56
	v_rndne_f32_e32 v61, v61
	v_rndne_f32_e32 v62, v62
	v_exp_f32_e32 v44, v44
	v_cvt_u32_f32_e32 v60, v60
	v_cvt_u32_f32_e32 v56, v56
	v_mul_f32_e32 v57, 0x437f0000, v57
	v_max_f32_e32 v61, 1.0, v61
	v_max_f32_e32 v62, 1.0, v62
	v_rcp_f32_e32 v59, v59
	v_rndne_f32_e32 v57, v57
	v_cvt_u32_f32_sdwa v61, v61 dst_sel:WORD_1 dst_unused:UNUSED_PAD src0_sel:DWORD
	v_mul_f32_e32 v58, 0x437f0000, v58
	v_cvt_u32_f32_sdwa v62, v62 dst_sel:BYTE_3 dst_unused:UNUSED_PAD src0_sel:DWORD
	v_mul_f32_e32 v59, 0x437f0000, v59
	v_max_f32_e32 v57, 1.0, v57
	v_rndne_f32_e32 v58, v58
	v_rndne_f32_e32 v59, v59
	v_cvt_u32_f32_e32 v57, v57
	v_max_f32_e32 v58, 1.0, v58
	v_max_f32_e32 v59, 1.0, v59
	v_add_f32_e32 v44, 1.0, v44
	v_cvt_u32_f32_sdwa v58, v58 dst_sel:WORD_1 dst_unused:UNUSED_PAD src0_sel:DWORD
	v_cvt_u32_f32_sdwa v59, v59 dst_sel:BYTE_3 dst_unused:UNUSED_PAD src0_sel:DWORD
	v_lshl_or_b32 v56, v56, 8, v60
	v_or3_b32 v56, v56, v61, v62
	global_store_dwordx2 v[80:81], v[64:65], off offset:128
	v_add_u32_e32 v64, 0x90, v174
	v_mad_i64_i32 v[64:65], s[2:3], v64, s55, v[164:165]
	v_lshl_or_b32 v57, v57, 8, v68
	v_lshl_add_u64 v[64:65], v[64:65], 0, v[162:163]
	v_or3_b32 v57, v57, v58, v59
	global_store_dwordx2 v[64:65], v[56:57], off
	v_add_f32_e32 v40, v40, v32
	v_mul_f32_e32 v40, 0xbfb8aa3b, v40
	v_exp_f32_e32 v40, v40
	s_nop 0
	v_add_f32_e32 v40, 1.0, v40
	v_rcp_f32_e32 v44, v44
	v_add_f32_e32 v45, v45, v37
	v_mul_f32_e32 v45, 0xbfb8aa3b, v45
	v_exp_f32_e32 v45, v45
	s_nop 0
	v_add_f32_e32 v45, 1.0, v45
	v_rcp_f32_e32 v40, v40
	s_nop 0
	v_mul_f32_e32 v40, 0x437f0000, v40
	v_rndne_f32_e32 v40, v40
	v_max_f32_e32 v40, 1.0, v40
	v_cvt_u32_f32_e32 v58, v40
	v_add_f32_e32 v41, v41, v33
	v_mul_f32_e32 v41, 0xbfb8aa3b, v41
	v_exp_f32_e32 v41, v41
	s_nop 0
	v_add_f32_e32 v41, 1.0, v41
	v_rcp_f32_e32 v40, v45
	v_add_f32_e32 v46, v46, v38
	v_mul_f32_e32 v46, 0xbfb8aa3b, v46
	v_exp_f32_e32 v46, v46
	v_rcp_f32_e32 v41, v41
	v_add_f32_e32 v45, 1.0, v46
	v_add_f32_e32 v42, v42, v34
	v_mul_f32_e32 v42, 0xbfb8aa3b, v42
	v_exp_f32_e32 v42, v42
	s_nop 0
	v_add_f32_e32 v42, 1.0, v42
	v_rcp_f32_e32 v45, v45
	v_add_f32_e32 v47, v47, v39
	v_mul_f32_e32 v47, 0xbfb8aa3b, v47
	v_exp_f32_e32 v47, v47
	v_rcp_f32_e32 v42, v42
	v_add_f32_e32 v46, 1.0, v47
	v_add_f32_e32 v43, v43, v35
	v_mul_f32_e32 v43, 0xbfb8aa3b, v43
	v_exp_f32_e32 v43, v43
	s_nop 0
	v_add_f32_e32 v43, 1.0, v43
	v_rcp_f32_e32 v46, v46
	v_mul_f32_e32 v41, 0x437f0000, v41
	v_rndne_f32_e32 v41, v41
	v_mul_f32_e32 v42, 0x437f0000, v42
	v_rcp_f32_e32 v43, v43
	s_nop 0
	v_mul_f32_e32 v43, 0x437f0000, v43
	v_add_f32_e32 v28, v28, v52
	v_max_f32_e32 v41, 1.0, v41
	v_rndne_f32_e32 v42, v42
	v_rndne_f32_e32 v43, v43
	v_mul_f32_e32 v28, 0xbfb8aa3b, v28
	v_cvt_u32_f32_e32 v41, v41
	v_max_f32_e32 v42, 1.0, v42
	v_max_f32_e32 v43, 1.0, v43
	v_exp_f32_e32 v28, v28
	v_cvt_u32_f32_sdwa v42, v42 dst_sel:WORD_1 dst_unused:UNUSED_PAD src0_sel:DWORD
	v_cvt_u32_f32_sdwa v43, v43 dst_sel:BYTE_3 dst_unused:UNUSED_PAD src0_sel:DWORD
	v_mul_f32_e32 v44, 0x437f0000, v44
	v_mul_f32_e32 v40, 0x437f0000, v40
	v_rndne_f32_e32 v44, v44
	v_rndne_f32_e32 v40, v40
	v_lshl_or_b32 v41, v41, 8, v58
	v_add_f32_e32 v28, 1.0, v28
	v_max_f32_e32 v44, 1.0, v44
	v_max_f32_e32 v40, 1.0, v40
	v_mul_f32_e32 v45, 0x437f0000, v45
	v_mul_f32_e32 v46, 0x437f0000, v46
	v_or3_b32 v41, v41, v42, v43
	v_cvt_u32_f32_e32 v44, v44
	v_cvt_u32_f32_e32 v40, v40
	v_rndne_f32_e32 v45, v45
	v_rndne_f32_e32 v46, v46
	v_max_f32_e32 v45, 1.0, v45
	v_max_f32_e32 v46, 1.0, v46
	v_cvt_u32_f32_sdwa v45, v45 dst_sel:WORD_1 dst_unused:UNUSED_PAD src0_sel:DWORD
	v_cvt_u32_f32_sdwa v46, v46 dst_sel:BYTE_3 dst_unused:UNUSED_PAD src0_sel:DWORD
	v_lshl_or_b32 v40, v40, 8, v44
	v_add_f32_e32 v24, v24, v48
	v_mul_f32_e32 v24, 0xbfb8aa3b, v24
	v_or3_b32 v40, v40, v45, v46
	v_exp_f32_e32 v24, v24
	s_nop 0
	v_add_f32_e32 v24, 1.0, v24
	v_rcp_f32_e32 v28, v28
	v_add_f32_e32 v29, v29, v53
	v_mul_f32_e32 v29, 0xbfb8aa3b, v29
	v_exp_f32_e32 v29, v29
	s_nop 0
	v_add_f32_e32 v29, 1.0, v29
	v_rcp_f32_e32 v24, v24
	s_nop 0
	v_mul_f32_e32 v24, 0x437f0000, v24
	v_rndne_f32_e32 v24, v24
	v_max_f32_e32 v24, 1.0, v24
	v_cvt_u32_f32_e32 v44, v24
	v_add_f32_e32 v25, v25, v49
	v_mul_f32_e32 v25, 0xbfb8aa3b, v25
	v_exp_f32_e32 v25, v25
	s_nop 0
	v_add_f32_e32 v25, 1.0, v25
	v_rcp_f32_e32 v24, v29
	v_add_f32_e32 v30, v30, v54
	v_mul_f32_e32 v30, 0xbfb8aa3b, v30
	v_exp_f32_e32 v30, v30
	v_rcp_f32_e32 v25, v25
	v_add_f32_e32 v29, 1.0, v30
	v_add_f32_e32 v26, v26, v50
	v_mul_f32_e32 v26, 0xbfb8aa3b, v26
	v_exp_f32_e32 v26, v26
	s_nop 0
	v_add_f32_e32 v26, 1.0, v26
	v_rcp_f32_e32 v29, v29
	v_add_f32_e32 v31, v31, v55
	v_mul_f32_e32 v31, 0xbfb8aa3b, v31
	v_exp_f32_e32 v31, v31
	v_rcp_f32_e32 v26, v26
	v_add_f32_e32 v30, 1.0, v31
	v_add_f32_e32 v27, v27, v51
	v_mul_f32_e32 v27, 0xbfb8aa3b, v27
	v_exp_f32_e32 v27, v27
	s_nop 0
	v_add_f32_e32 v27, 1.0, v27
	v_rcp_f32_e32 v30, v30
	v_mul_f32_e32 v28, 0x437f0000, v28
	v_mul_f32_e32 v24, 0x437f0000, v24
	v_add_f32_e32 v20, v20, v36
	v_rndne_f32_e32 v28, v28
; __device__ __forceinline__ float sigmoidf_(float x) { return 1.0f / (1.0f + __expf(-x)); }
;     __device__ __forceinline__ void operator()(const f32x4 (&acc)[2][2][4][2], const Unit& u, int wr, int wc, int fr, int fq) const {
;     ...
;             for (int m = 0; m < 4; ++m) { unsigned char* rowp = O + (size_t)(row0 + ai * HALF + m * 16) * GP8 + col0;
; #pragma unroll
;                 for (int bj = 0; bj < 2; ++bj) { const f32x4 v0 = acc[ai][bj][m][0] + bv[bj][0], v1 = acc[ai][bj][m][1] + bv[bj][1];
;                     unsigned q[8];
; #pragma unroll
;                     for (int j = 0; j < 4; ++j) { q[j] = (unsigned)fmaxf(__builtin_rintf(sigmoidf_(v0[j]) * 255.f), 1.f); q[4 + j] = (unsigned)fmaxf(__builtin_rintf(sigmoidf_(v1[j]) * 255.f), 1.f); }
;                     u32x2 w; w.x = q[0] | (q[1] << 8) | (q[2] << 16) | (q[3] << 24); w.y = q[4] | (q[5] << 8) | (q[6] << 16) | (q[7] << 24);
;                     *(u32x2*)(rowp + bj * HALF) = w; } }
	v_rndne_f32_e32 v24, v24
	v_mul_f32_e32 v29, 0x437f0000, v29
	v_mul_f32_e32 v30, 0x437f0000, v30
	v_mul_f32_e32 v20, 0xbfb8aa3b, v20
	v_max_f32_e32 v28, 1.0, v28
	v_max_f32_e32 v24, 1.0, v24
	v_rndne_f32_e32 v29, v29
	v_rndne_f32_e32 v30, v30
	v_exp_f32_e32 v20, v20
	v_cvt_u32_f32_e32 v28, v28
	v_cvt_u32_f32_e32 v24, v24
	v_mul_f32_e32 v25, 0x437f0000, v25
	v_max_f32_e32 v29, 1.0, v29
	v_max_f32_e32 v30, 1.0, v30
	v_rcp_f32_e32 v27, v27
	v_rndne_f32_e32 v25, v25
	v_cvt_u32_f32_sdwa v29, v29 dst_sel:WORD_1 dst_unused:UNUSED_PAD src0_sel:DWORD
	v_mul_f32_e32 v26, 0x437f0000, v26
	v_cvt_u32_f32_sdwa v30, v30 dst_sel:BYTE_3 dst_unused:UNUSED_PAD src0_sel:DWORD
	v_mul_f32_e32 v27, 0x437f0000, v27
	v_max_f32_e32 v25, 1.0, v25
	v_rndne_f32_e32 v26, v26
	v_rndne_f32_e32 v27, v27
	v_cvt_u32_f32_e32 v25, v25
	v_max_f32_e32 v26, 1.0, v26
	v_max_f32_e32 v27, 1.0, v27
	v_add_f32_e32 v20, 1.0, v20
	v_cvt_u32_f32_sdwa v26, v26 dst_sel:WORD_1 dst_unused:UNUSED_PAD src0_sel:DWORD
	v_cvt_u32_f32_sdwa v27, v27 dst_sel:BYTE_3 dst_unused:UNUSED_PAD src0_sel:DWORD
	v_lshl_or_b32 v24, v24, 8, v28
	v_or3_b32 v24, v24, v29, v30
	global_store_dwordx2 v[64:65], v[40:41], off offset:128
	v_add_u32_e32 v40, 0xa0, v174
	v_mad_i64_i32 v[40:41], s[2:3], v40, s55, v[164:165]
	v_lshl_or_b32 v25, v25, 8, v44
	v_lshl_add_u64 v[40:41], v[40:41], 0, v[162:163]
	v_or3_b32 v25, v25, v26, v27
	global_store_dwordx2 v[40:41], v[24:25], off
	v_add_f32_e32 v16, v16, v32
	v_mul_f32_e32 v16, 0xbfb8aa3b, v16
	v_exp_f32_e32 v16, v16
	s_nop 0
	v_add_f32_e32 v16, 1.0, v16
	v_rcp_f32_e32 v20, v20
	v_add_f32_e32 v21, v21, v37
	v_mul_f32_e32 v21, 0xbfb8aa3b, v21
	v_exp_f32_e32 v21, v21
	s_nop 0
	v_add_f32_e32 v21, 1.0, v21
	v_rcp_f32_e32 v16, v16
	s_nop 0
	v_mul_f32_e32 v16, 0x437f0000, v16
	v_rndne_f32_e32 v16, v16
	v_max_f32_e32 v16, 1.0, v16
	v_cvt_u32_f32_e32 v26, v16
	v_add_f32_e32 v17, v17, v33
	v_mul_f32_e32 v17, 0xbfb8aa3b, v17
	v_exp_f32_e32 v17, v17
	s_nop 0
	v_add_f32_e32 v17, 1.0, v17
	v_rcp_f32_e32 v16, v21
	v_add_f32_e32 v22, v22, v38
	v_mul_f32_e32 v22, 0xbfb8aa3b, v22
	v_exp_f32_e32 v22, v22
	v_rcp_f32_e32 v17, v17
	v_add_f32_e32 v21, 1.0, v22
	v_add_f32_e32 v18, v18, v34
	v_mul_f32_e32 v18, 0xbfb8aa3b, v18
	v_exp_f32_e32 v18, v18
	s_nop 0
	v_add_f32_e32 v18, 1.0, v18
	v_rcp_f32_e32 v21, v21
	v_add_f32_e32 v23, v23, v39
	v_mul_f32_e32 v23, 0xbfb8aa3b, v23
	v_exp_f32_e32 v23, v23
	v_rcp_f32_e32 v18, v18
	v_add_f32_e32 v22, 1.0, v23
	v_add_f32_e32 v19, v19, v35
	v_mul_f32_e32 v19, 0xbfb8aa3b, v19
	v_exp_f32_e32 v19, v19
	s_nop 0
	v_add_f32_e32 v19, 1.0, v19
	v_rcp_f32_e32 v22, v22
	v_mul_f32_e32 v17, 0x437f0000, v17
	v_rndne_f32_e32 v17, v17
	v_mul_f32_e32 v18, 0x437f0000, v18
	v_rcp_f32_e32 v19, v19
	s_nop 0
	v_mul_f32_e32 v19, 0x437f0000, v19
	v_add_f32_e32 v12, v12, v52
	v_max_f32_e32 v17, 1.0, v17
	v_rndne_f32_e32 v18, v18
	v_rndne_f32_e32 v19, v19
	v_mul_f32_e32 v12, 0xbfb8aa3b, v12
	v_cvt_u32_f32_e32 v17, v17
	v_max_f32_e32 v18, 1.0, v18
	v_max_f32_e32 v19, 1.0, v19
	v_exp_f32_e32 v12, v12
	v_cvt_u32_f32_sdwa v18, v18 dst_sel:WORD_1 dst_unused:UNUSED_PAD src0_sel:DWORD
	v_cvt_u32_f32_sdwa v19, v19 dst_sel:BYTE_3 dst_unused:UNUSED_PAD src0_sel:DWORD
	v_mul_f32_e32 v20, 0x437f0000, v20
	v_mul_f32_e32 v16, 0x437f0000, v16
	v_rndne_f32_e32 v20, v20
	v_rndne_f32_e32 v16, v16
	v_lshl_or_b32 v17, v17, 8, v26
	v_add_f32_e32 v12, 1.0, v12
	v_max_f32_e32 v20, 1.0, v20
	v_max_f32_e32 v16, 1.0, v16
	v_mul_f32_e32 v21, 0x437f0000, v21
	v_mul_f32_e32 v22, 0x437f0000, v22
	v_or3_b32 v17, v17, v18, v19
	v_cvt_u32_f32_e32 v20, v20
	v_cvt_u32_f32_e32 v16, v16
	v_rndne_f32_e32 v21, v21
	v_rndne_f32_e32 v22, v22
	v_max_f32_e32 v21, 1.0, v21
	v_max_f32_e32 v22, 1.0, v22
	v_cvt_u32_f32_sdwa v21, v21 dst_sel:WORD_1 dst_unused:UNUSED_PAD src0_sel:DWORD
	v_cvt_u32_f32_sdwa v22, v22 dst_sel:BYTE_3 dst_unused:UNUSED_PAD src0_sel:DWORD
	v_lshl_or_b32 v16, v16, 8, v20
	v_add_f32_e32 v8, v8, v48
	v_mul_f32_e32 v8, 0xbfb8aa3b, v8
	v_or3_b32 v16, v16, v21, v22
	v_exp_f32_e32 v8, v8
	s_nop 0
	v_add_f32_e32 v8, 1.0, v8
	v_rcp_f32_e32 v12, v12
	v_add_f32_e32 v13, v13, v53
	v_mul_f32_e32 v13, 0xbfb8aa3b, v13
	v_exp_f32_e32 v13, v13
	s_nop 0
	v_add_f32_e32 v13, 1.0, v13
	v_rcp_f32_e32 v8, v8
	s_nop 0
	v_mul_f32_e32 v8, 0x437f0000, v8
	v_rndne_f32_e32 v8, v8
	v_max_f32_e32 v8, 1.0, v8
	v_cvt_u32_f32_e32 v20, v8
	v_add_f32_e32 v9, v9, v49
	v_mul_f32_e32 v9, 0xbfb8aa3b, v9
	v_exp_f32_e32 v9, v9
	s_nop 0
	v_add_f32_e32 v9, 1.0, v9
	v_rcp_f32_e32 v8, v13
	v_add_f32_e32 v14, v14, v54
; __device__ __forceinline__ float sigmoidf_(float x) { return 1.0f / (1.0f + __expf(-x)); }
; #define PG8_BAR __builtin_amdgcn_s_barrier()
;     __device__ __forceinline__ void operator()(const f32x4 (&acc)[2][2][4][2], const Unit& u, int wr, int wc, int fr, int fq) const {
;     ...
;             for (int m = 0; m < 4; ++m) { unsigned char* rowp = O + (size_t)(row0 + ai * HALF + m * 16) * GP8 + col0;
; #pragma unroll
;                 for (int bj = 0; bj < 2; ++bj) { const f32x4 v0 = acc[ai][bj][m][0] + bv[bj][0], v1 = acc[ai][bj][m][1] + bv[bj][1];
;                     unsigned q[8];
; #pragma unroll
;                     for (int j = 0; j < 4; ++j) { q[j] = (unsigned)fmaxf(__builtin_rintf(sigmoidf_(v0[j]) * 255.f), 1.f); q[4 + j] = (unsigned)fmaxf(__builtin_rintf(sigmoidf_(v1[j]) * 255.f), 1.f); }
;                     u32x2 w; w.x = q[0] | (q[1] << 8) | (q[2] << 16) | (q[3] << 24); w.y = q[4] | (q[5] << 8) | (q[6] << 16) | (q[7] << 24);
;                     *(u32x2*)(rowp + bj * HALF) = w; } }
; template <class Epi, class Sched, bool ALIGN_EPI = true>
; __device__ __forceinline__ void gemm_phase(LAS unsigned char* lds, const Gemm g, const Sched& S, const Epi& E) {
;     ...
;         if constexpr (ALIGN_EPI) { if (wr == 0) PG8_BAR; }
;         E(acc, cur, wr, wc, fr, fq);
;         if (!has_next) break;
; #pragma unroll
;         for (int a = 0; a < 2; ++a)
; #pragma unroll
;             for (int b = 0; b < 2; ++b)
; #pragma unroll
;                 for (int m = 0; m < 4; ++m)
; #pragma unroll
;                     for (int n = 0; n < 2; ++n) acc[a][b][m][n] = (f32x4){0.f, 0.f, 0.f, 0.f};
;         cur = nxt; cA = nA; cB = nB; ++ui;
;         if constexpr (ALIGN_EPI) { if (wr == 1) PG8_BAR; }
	v_mul_f32_e32 v14, 0xbfb8aa3b, v14
	v_exp_f32_e32 v14, v14
	v_rcp_f32_e32 v9, v9
	v_add_f32_e32 v13, 1.0, v14
	v_add_f32_e32 v10, v10, v50
	v_mul_f32_e32 v10, 0xbfb8aa3b, v10
	v_exp_f32_e32 v10, v10
	s_nop 0
	v_add_f32_e32 v10, 1.0, v10
	v_rcp_f32_e32 v13, v13
	v_add_f32_e32 v15, v15, v55
	v_mul_f32_e32 v15, 0xbfb8aa3b, v15
	v_exp_f32_e32 v15, v15
	v_rcp_f32_e32 v10, v10
	v_add_f32_e32 v14, 1.0, v15
	v_add_f32_e32 v11, v11, v51
	v_mul_f32_e32 v11, 0xbfb8aa3b, v11
	v_exp_f32_e32 v11, v11
	s_nop 0
	v_add_f32_e32 v11, 1.0, v11
	v_rcp_f32_e32 v14, v14
	v_mul_f32_e32 v12, 0x437f0000, v12
	v_mul_f32_e32 v8, 0x437f0000, v8
	v_add_f32_e32 v4, v4, v36
	v_rndne_f32_e32 v12, v12
	v_rndne_f32_e32 v8, v8
	v_mul_f32_e32 v13, 0x437f0000, v13
	v_mul_f32_e32 v14, 0x437f0000, v14
	v_mul_f32_e32 v4, 0xbfb8aa3b, v4
	v_max_f32_e32 v12, 1.0, v12
	v_max_f32_e32 v8, 1.0, v8
	v_rndne_f32_e32 v13, v13
	v_rndne_f32_e32 v14, v14
	v_exp_f32_e32 v4, v4
	v_cvt_u32_f32_e32 v12, v12
	v_cvt_u32_f32_e32 v8, v8
	v_mul_f32_e32 v9, 0x437f0000, v9
	v_max_f32_e32 v13, 1.0, v13
	v_max_f32_e32 v14, 1.0, v14
	v_rcp_f32_e32 v11, v11
	v_rndne_f32_e32 v9, v9
	v_cvt_u32_f32_sdwa v13, v13 dst_sel:WORD_1 dst_unused:UNUSED_PAD src0_sel:DWORD
	v_mul_f32_e32 v10, 0x437f0000, v10
	v_cvt_u32_f32_sdwa v14, v14 dst_sel:BYTE_3 dst_unused:UNUSED_PAD src0_sel:DWORD
	v_mul_f32_e32 v11, 0x437f0000, v11
	v_max_f32_e32 v9, 1.0, v9
	v_rndne_f32_e32 v10, v10
	v_rndne_f32_e32 v11, v11
	v_cvt_u32_f32_e32 v9, v9
	v_max_f32_e32 v10, 1.0, v10
	v_max_f32_e32 v11, 1.0, v11
	v_add_f32_e32 v4, 1.0, v4
	v_cvt_u32_f32_sdwa v10, v10 dst_sel:WORD_1 dst_unused:UNUSED_PAD src0_sel:DWORD
	v_cvt_u32_f32_sdwa v11, v11 dst_sel:BYTE_3 dst_unused:UNUSED_PAD src0_sel:DWORD
	v_lshl_or_b32 v8, v8, 8, v12
	v_or3_b32 v8, v8, v13, v14
	global_store_dwordx2 v[40:41], v[16:17], off offset:128
	v_add_u32_e32 v16, 0xb0, v174
	v_mad_i64_i32 v[16:17], s[2:3], v16, s55, v[164:165]
	v_lshl_or_b32 v9, v9, 8, v20
	v_lshl_add_u64 v[16:17], v[16:17], 0, v[162:163]
	v_or3_b32 v9, v9, v10, v11
	global_store_dwordx2 v[16:17], v[8:9], off
	v_add_f32_e32 v0, v0, v32
	v_mul_f32_e32 v0, 0xbfb8aa3b, v0
	v_exp_f32_e32 v0, v0
	s_nop 0
	v_add_f32_e32 v0, 1.0, v0
	v_rcp_f32_e32 v4, v4
	v_add_f32_e32 v5, v5, v37
	v_mul_f32_e32 v5, 0xbfb8aa3b, v5
	v_exp_f32_e32 v5, v5
	s_nop 0
	v_add_f32_e32 v5, 1.0, v5
	v_rcp_f32_e32 v0, v0
	s_nop 0
	v_mul_f32_e32 v0, 0x437f0000, v0
	v_rndne_f32_e32 v0, v0
	v_max_f32_e32 v0, 1.0, v0
	v_cvt_u32_f32_e32 v10, v0
	v_add_f32_e32 v1, v1, v33
	v_mul_f32_e32 v1, 0xbfb8aa3b, v1
	v_exp_f32_e32 v1, v1
	s_nop 0
	v_add_f32_e32 v1, 1.0, v1
	v_rcp_f32_e32 v0, v5
	v_add_f32_e32 v6, v6, v38
	v_mul_f32_e32 v6, 0xbfb8aa3b, v6
	v_exp_f32_e32 v6, v6
	v_rcp_f32_e32 v1, v1
	v_add_f32_e32 v5, 1.0, v6
	v_add_f32_e32 v2, v2, v34
	v_mul_f32_e32 v2, 0xbfb8aa3b, v2
	v_exp_f32_e32 v2, v2
	s_nop 0
	v_add_f32_e32 v2, 1.0, v2
	v_rcp_f32_e32 v5, v5
	v_add_f32_e32 v7, v7, v39
	v_mul_f32_e32 v7, 0xbfb8aa3b, v7
	v_exp_f32_e32 v7, v7
	v_rcp_f32_e32 v2, v2
	v_add_f32_e32 v6, 1.0, v7
	v_add_f32_e32 v3, v3, v35
	v_mul_f32_e32 v3, 0xbfb8aa3b, v3
	v_exp_f32_e32 v3, v3
	s_nop 0
	v_add_f32_e32 v3, 1.0, v3
	v_rcp_f32_e32 v6, v6
	v_mul_f32_e32 v4, 0x437f0000, v4
	v_mul_f32_e32 v0, 0x437f0000, v0
	v_mul_f32_e32 v1, 0x437f0000, v1
	v_rcp_f32_e32 v3, v3
	v_rndne_f32_e32 v4, v4
	v_rndne_f32_e32 v0, v0
	v_rndne_f32_e32 v1, v1
	v_mul_f32_e32 v5, 0x437f0000, v5
	v_mul_f32_e32 v2, 0x437f0000, v2
	v_mul_f32_e32 v6, 0x437f0000, v6
	v_mul_f32_e32 v3, 0x437f0000, v3
	v_max_f32_e32 v4, 1.0, v4
	v_max_f32_e32 v0, 1.0, v0
	v_max_f32_e32 v1, 1.0, v1
	v_rndne_f32_e32 v5, v5
	v_rndne_f32_e32 v2, v2
	v_rndne_f32_e32 v6, v6
	v_rndne_f32_e32 v3, v3
	v_cvt_u32_f32_e32 v4, v4
	v_cvt_u32_f32_e32 v0, v0
	v_cvt_u32_f32_e32 v1, v1
	v_max_f32_e32 v5, 1.0, v5
	v_max_f32_e32 v2, 1.0, v2
	v_max_f32_e32 v6, 1.0, v6
	v_max_f32_e32 v3, 1.0, v3
	v_cvt_u32_f32_sdwa v5, v5 dst_sel:WORD_1 dst_unused:UNUSED_PAD src0_sel:DWORD
	v_cvt_u32_f32_sdwa v2, v2 dst_sel:WORD_1 dst_unused:UNUSED_PAD src0_sel:DWORD
	v_cvt_u32_f32_sdwa v6, v6 dst_sel:BYTE_3 dst_unused:UNUSED_PAD src0_sel:DWORD
	v_cvt_u32_f32_sdwa v3, v3 dst_sel:BYTE_3 dst_unused:UNUSED_PAD src0_sel:DWORD
	v_lshl_or_b32 v0, v0, 8, v4
	v_lshl_or_b32 v1, v1, 8, v10
	v_or3_b32 v0, v0, v5, v6
	v_or3_b32 v1, v1, v2, v3
	s_andn2_b64 vcc, exec, s[0:1]
	s_mov_b64 s[0:1], -1
	global_store_dwordx2 v[16:17], v[0:1], off offset:128
	s_cbranch_vccnz .LBB0_804
	s_andn2_b64 vcc, exec, s[10:11]
	s_cbranch_vccnz .LBB0_803
	s_barrier
	s_branch .LBB0_803

; __device__ __forceinline__ float ub0(unsigned w) { return (float)(w & 0xffu); }
; __device__ __forceinline__ float ub1(unsigned w) { return (float)((w >> 8) & 0xffu); }
; __device__ __forceinline__ float ub2(unsigned w) { return (float)((w >> 16) & 0xffu); }
; __device__ __forceinline__ float ub3(unsigned w) { return (float)(w >> 24); }
;     __device__ __forceinline__ void mid(f32x4 (&acc)[2][2][4][2], const Unit& u, int wr, int wc, int fr, int fq, int t) const {
;         const int offx = (t == 8) ? 0 : 2048;
;         const unsigned char* gp0 = gates + (size_t)(u.pm * BM + wr * 64 + fr) * GP8 + u.pn * BM + wc * 32 + 8 * fq + offx;
; #pragma unroll
;         for (int ai = 0; ai < 2; ++ai) {
;             u32x2 gx[4][2], gy[4][2];
; #pragma unroll
;             for (int m = 0; m < 4; ++m)
; #pragma unroll
;                 for (int bj = 0; bj < 2; ++bj) { const unsigned char* gp = gp0 + (size_t)(ai * HALF + m * 16) * GP8 + bj * HALF; gx[m][bj] = *(const u32x2*)gp; gy[m][bj] = *(const u32x2*)(gp + 2048); }
; #pragma unroll
;             for (int m = 0; m < 4; ++m)
; #pragma unroll
;                 for (int bj = 0; bj < 2; ++bj) { const u32x2 x = gx[m][bj], y = gy[m][bj];
;                     f32x4 r0, r1;
;                     r0[0] = __fdividef(ub0(x.x), ub0(y.x)); r0[1] = __fdividef(ub1(x.x), ub1(y.x)); r0[2] = __fdividef(ub2(x.x), ub2(y.x)); r0[3] = __fdividef(ub3(x.x), ub3(y.x));
;                     r1[0] = __fdividef(ub0(x.y), ub0(y.y)); r1[1] = __fdividef(ub1(x.y), ub1(y.y)); r1[2] = __fdividef(ub2(x.y), ub2(y.y)); r1[3] = __fdividef(ub3(x.y), ub3(y.y));
;                     acc[ai][bj][m][0] *= r0; acc[ai][bj][m][1] *= r1; }
;             asm volatile("" ::: "memory"); }
.LBB0_959:
	s_andn2_b64 vcc, exec, s[4:5]
	s_cbranch_vccnz .LBB0_961
	s_cmpk_eq_i32 s44, 0x300
	s_cselect_b32 s12, 0, 0x800
	v_lshl_add_u64 v[2:3], v[158:159], 0, s[12:13]
	global_load_dwordx2 v[198:199], v[2:3], off
	global_load_dwordx2 v[200:201], v[2:3], off offset:2048
	global_load_dwordx2 v[188:189], v[2:3], off offset:2176
	global_load_dwordx2 v[190:191], v[2:3], off offset:128
	v_add_co_u32_e32 v164, vcc, 0x44000, v2
	s_waitcnt vmcnt(0)
	v_cvt_f32_ubyte2_e32 v1, v198
	v_addc_co_u32_e32 v165, vcc, 0, v3, vcc
	v_add_co_u32_e32 v166, vcc, 0x88000, v2
	global_load_dwordx2 v[186:187], v[164:165], off
	global_load_dwordx2 v[184:185], v[164:165], off offset:2048
	global_load_dwordx2 v[180:181], v[164:165], off offset:2176
	global_load_dwordx2 v[182:183], v[164:165], off offset:128
	v_addc_co_u32_e32 v167, vcc, 0, v3, vcc
	v_add_co_u32_e32 v202, vcc, 0xcc000, v2
	global_load_dwordx2 v[178:179], v[166:167], off
	global_load_dwordx2 v[176:177], v[166:167], off offset:2048
	global_load_dwordx2 v[172:173], v[166:167], off offset:2176
	global_load_dwordx2 v[174:175], v[166:167], off offset:128
	v_addc_co_u32_e32 v203, vcc, 0, v3, vcc
	global_load_dwordx2 v[170:171], v[202:203], off
	global_load_dwordx2 v[168:169], v[202:203], off offset:2048
	global_load_dwordx2 v[164:165], v[202:203], off offset:2176
	global_load_dwordx2 v[166:167], v[202:203], off offset:128
	v_cvt_f32_ubyte3_e32 v204, v198
	v_cvt_f32_ubyte0_e32 v202, v198
	v_cvt_f32_ubyte1_e32 v198, v198
	v_cvt_f32_ubyte2_e32 v206, v200
	v_cvt_f32_ubyte3_e32 v205, v200
	v_cvt_f32_ubyte0_e32 v207, v200
	v_cvt_f32_ubyte1_e32 v200, v200
	v_rcp_f32_e32 v203, v200
	s_nop 0
	v_mul_f32_e32 v203, v198, v203
	v_rcp_f32_e32 v198, v207
	s_nop 0
	v_mul_f32_e32 v202, v202, v198
	v_rcp_f32_e32 v198, v205
	s_nop 0
	v_mul_f32_e32 v205, v204, v198
	v_cvt_f32_ubyte2_e32 v208, v199
	v_cvt_f32_ubyte3_e32 v209, v199
	v_rcp_f32_e32 v198, v206
	s_nop 0
	v_mul_f32_e32 v204, v1, v198
	v_cvt_f32_ubyte0_e32 v1, v199
	v_cvt_f32_ubyte1_e32 v198, v199
	v_cvt_f32_ubyte1_e32 v199, v201
	v_cvt_f32_ubyte2_e32 v207, v201
	v_cvt_f32_ubyte3_e32 v210, v201
	v_cvt_f32_ubyte0_e32 v201, v201
	v_rcp_f32_e32 v200, v199
	s_nop 0
	v_mul_f32_e32 v199, v198, v200
	v_pk_mul_f32 v[128:129], v[128:129], v[202:203]
	v_rcp_f32_e32 v198, v201
	s_nop 0
	v_mul_f32_e32 v198, v1, v198
	v_pk_mul_f32 v[124:125], v[124:125], v[198:199]
	v_rcp_f32_e32 v1, v210
	s_nop 0
	v_mul_f32_e32 v201, v209, v1
	v_cvt_f32_ubyte0_e32 v198, v190
	v_rcp_f32_e32 v1, v207
	s_nop 0
	v_mul_f32_e32 v200, v208, v1
	v_pk_mul_f32 v[126:127], v[126:127], v[200:201]
	v_cvt_f32_ubyte2_e32 v1, v190
	v_cvt_f32_ubyte3_e32 v200, v190
	v_cvt_f32_ubyte1_e32 v190, v190
	v_cvt_f32_ubyte1_e32 v199, v188
	v_pk_mul_f32 v[130:131], v[130:131], v[204:205]
	v_cvt_f32_ubyte2_e32 v203, v188
	v_cvt_f32_ubyte3_e32 v204, v188
	v_cvt_f32_ubyte0_e32 v188, v188
	v_rcp_f32_e32 v201, v199
	s_nop 0
	v_mul_f32_e32 v199, v190, v201
	v_rcp_f32_e32 v190, v188
	s_nop 0
	v_mul_f32_e32 v198, v198, v190
	v_cvt_f32_ubyte0_e32 v207, v189
	v_rcp_f32_e32 v188, v204
	s_nop 0
	v_mul_f32_e32 v201, v200, v188
	v_cvt_f32_ubyte2_e32 v205, v189
	v_rcp_f32_e32 v188, v203
	s_nop 0
	v_mul_f32_e32 v200, v1, v188
	v_cvt_f32_ubyte2_e32 v1, v191
	v_cvt_f32_ubyte3_e32 v190, v191
	v_cvt_f32_ubyte0_e32 v188, v191
	v_cvt_f32_ubyte1_e32 v191, v191
	v_cvt_f32_ubyte1_e32 v202, v189
	v_cvt_f32_ubyte3_e32 v206, v189
	v_pk_mul_f32 v[120:121], v[120:121], v[198:199]
	v_pk_mul_f32 v[122:123], v[122:123], v[200:201]
	v_rcp_f32_e32 v189, v202
	s_nop 0
	v_mul_f32_e32 v189, v191, v189
	s_waitcnt vmcnt(10)
	v_cvt_f32_ubyte2_e32 v199, v184
	v_rcp_f32_e32 v191, v207
	s_nop 0
	v_mul_f32_e32 v188, v188, v191
	v_pk_mul_f32 v[116:117], v[116:117], v[188:189]
	v_rcp_f32_e32 v191, v206
	s_nop 0
	v_mul_f32_e32 v191, v190, v191
	v_cvt_f32_ubyte0_e32 v188, v186
	v_rcp_f32_e32 v190, v205
	s_nop 0
	v_mul_f32_e32 v190, v1, v190
	v_pk_mul_f32 v[118:119], v[118:119], v[190:191]
	v_cvt_f32_ubyte2_e32 v1, v186
	v_cvt_f32_ubyte3_e32 v190, v186
	v_cvt_f32_ubyte1_e32 v186, v186
	v_cvt_f32_ubyte1_e32 v189, v184
	v_cvt_f32_ubyte3_e32 v200, v184
	v_cvt_f32_ubyte0_e32 v184, v184
	v_rcp_f32_e32 v191, v189
	s_nop 0
	v_mul_f32_e32 v189, v186, v191
	v_rcp_f32_e32 v186, v184
	s_nop 0
	v_mul_f32_e32 v188, v188, v186
	v_cvt_f32_ubyte0_e32 v203, v185
	v_rcp_f32_e32 v184, v200
	s_nop 0
	v_mul_f32_e32 v191, v190, v184
	v_cvt_f32_ubyte2_e32 v201, v185
	v_rcp_f32_e32 v184, v199
	s_nop 0
	v_mul_f32_e32 v190, v1, v184
	v_cvt_f32_ubyte2_e32 v1, v187
	v_cvt_f32_ubyte3_e32 v186, v187
	v_cvt_f32_ubyte0_e32 v184, v187
	v_cvt_f32_ubyte1_e32 v187, v187
	v_cvt_f32_ubyte1_e32 v198, v185
	v_cvt_f32_ubyte3_e32 v202, v185
	v_pk_mul_f32 v[112:113], v[112:113], v[188:189]
	v_pk_mul_f32 v[114:115], v[114:115], v[190:191]
	v_rcp_f32_e32 v185, v198
	s_nop 0
	v_mul_f32_e32 v185, v187, v185
	s_waitcnt vmcnt(9)
	v_cvt_f32_ubyte2_e32 v189, v180
	v_rcp_f32_e32 v187, v203
	s_nop 0
	v_mul_f32_e32 v184, v184, v187
	v_pk_mul_f32 v[108:109], v[108:109], v[184:185]
	v_rcp_f32_e32 v187, v202
	s_nop 0
	v_mul_f32_e32 v187, v186, v187
	s_waitcnt vmcnt(8)
	v_cvt_f32_ubyte0_e32 v184, v182
	v_rcp_f32_e32 v186, v201
	s_nop 0
	v_mul_f32_e32 v186, v1, v186
	v_pk_mul_f32 v[110:111], v[110:111], v[186:187]
	v_cvt_f32_ubyte2_e32 v1, v182
	v_cvt_f32_ubyte3_e32 v186, v182
	v_cvt_f32_ubyte1_e32 v182, v182
	v_cvt_f32_ubyte1_e32 v185, v180
	v_cvt_f32_ubyte3_e32 v190, v180
	v_cvt_f32_ubyte0_e32 v180, v180
	v_rcp_f32_e32 v187, v185
	s_nop 0
	v_mul_f32_e32 v185, v182, v187
	v_rcp_f32_e32 v182, v180
	s_nop 0
	v_mul_f32_e32 v184, v184, v182
	v_cvt_f32_ubyte0_e32 v199, v181
	v_rcp_f32_e32 v180, v190
	s_nop 0
	v_mul_f32_e32 v187, v186, v180
	v_cvt_f32_ubyte2_e32 v191, v181
	v_rcp_f32_e32 v180, v189
	s_nop 0
	v_mul_f32_e32 v186, v1, v180
	v_cvt_f32_ubyte2_e32 v1, v183
	v_cvt_f32_ubyte3_e32 v182, v183
	v_cvt_f32_ubyte0_e32 v180, v183
	v_cvt_f32_ubyte1_e32 v183, v183
	v_cvt_f32_ubyte1_e32 v188, v181
	v_cvt_f32_ubyte3_e32 v198, v181
	v_pk_mul_f32 v[104:105], v[104:105], v[184:185]
	v_pk_mul_f32 v[106:107], v[106:107], v[186:187]
	v_rcp_f32_e32 v181, v188
	s_nop 0
	v_mul_f32_e32 v181, v183, v181
	s_waitcnt vmcnt(6)
; __device__ __forceinline__ float ub0(unsigned w) { return (float)(w & 0xffu); }
; __device__ __forceinline__ float ub1(unsigned w) { return (float)((w >> 8) & 0xffu); }
; __device__ __forceinline__ float ub2(unsigned w) { return (float)((w >> 16) & 0xffu); }
; __device__ __forceinline__ float ub3(unsigned w) { return (float)(w >> 24); }
;     __device__ __forceinline__ void mid(f32x4 (&acc)[2][2][4][2], const Unit& u, int wr, int wc, int fr, int fq, int t) const {
;         const int offx = (t == 8) ? 0 : 2048;
;         const unsigned char* gp0 = gates + (size_t)(u.pm * BM + wr * 64 + fr) * GP8 + u.pn * BM + wc * 32 + 8 * fq + offx;
; #pragma unroll
;         for (int ai = 0; ai < 2; ++ai) {
;             u32x2 gx[4][2], gy[4][2];
; #pragma unroll
;             for (int m = 0; m < 4; ++m)
; #pragma unroll
;                 for (int bj = 0; bj < 2; ++bj) { const unsigned char* gp = gp0 + (size_t)(ai * HALF + m * 16) * GP8 + bj * HALF; gx[m][bj] = *(const u32x2*)gp; gy[m][bj] = *(const u32x2*)(gp + 2048); }
; #pragma unroll
;             for (int m = 0; m < 4; ++m)
; #pragma unroll
;                 for (int bj = 0; bj < 2; ++bj) { const u32x2 x = gx[m][bj], y = gy[m][bj];
;                     f32x4 r0, r1;
;                     r0[0] = __fdividef(ub0(x.x), ub0(y.x)); r0[1] = __fdividef(ub1(x.x), ub1(y.x)); r0[2] = __fdividef(ub2(x.x), ub2(y.x)); r0[3] = __fdividef(ub3(x.x), ub3(y.x));
;                     r1[0] = __fdividef(ub0(x.y), ub0(y.y)); r1[1] = __fdividef(ub1(x.y), ub1(y.y)); r1[2] = __fdividef(ub2(x.y), ub2(y.y)); r1[3] = __fdividef(ub3(x.y), ub3(y.y));
;                     acc[ai][bj][m][0] *= r0; acc[ai][bj][m][1] *= r1; }
;             asm volatile("" ::: "memory"); }
	v_cvt_f32_ubyte2_e32 v185, v176
	v_rcp_f32_e32 v183, v199
	s_nop 0
	v_mul_f32_e32 v180, v180, v183
	v_pk_mul_f32 v[100:101], v[100:101], v[180:181]
	v_rcp_f32_e32 v183, v198
	s_nop 0
	v_mul_f32_e32 v183, v182, v183
	v_cvt_f32_ubyte0_e32 v180, v178
	v_rcp_f32_e32 v182, v191
	s_nop 0
	v_mul_f32_e32 v182, v1, v182
	v_pk_mul_f32 v[102:103], v[102:103], v[182:183]
	v_cvt_f32_ubyte2_e32 v1, v178
	v_cvt_f32_ubyte3_e32 v182, v178
	v_cvt_f32_ubyte1_e32 v178, v178
	v_cvt_f32_ubyte1_e32 v181, v176
	v_cvt_f32_ubyte3_e32 v186, v176
	v_cvt_f32_ubyte0_e32 v176, v176
	v_rcp_f32_e32 v183, v181
	s_nop 0
	v_mul_f32_e32 v181, v178, v183
	v_rcp_f32_e32 v178, v176
	s_nop 0
	v_mul_f32_e32 v180, v180, v178
	v_cvt_f32_ubyte0_e32 v189, v177
	v_rcp_f32_e32 v176, v186
	s_nop 0
	v_mul_f32_e32 v183, v182, v176
	v_cvt_f32_ubyte2_e32 v187, v177
	v_rcp_f32_e32 v176, v185
	s_nop 0
	v_mul_f32_e32 v182, v1, v176
	v_cvt_f32_ubyte2_e32 v1, v179
	v_cvt_f32_ubyte3_e32 v178, v179
	v_cvt_f32_ubyte0_e32 v176, v179
	v_cvt_f32_ubyte1_e32 v179, v179
	v_cvt_f32_ubyte1_e32 v184, v177
	v_cvt_f32_ubyte3_e32 v188, v177
	v_pk_mul_f32 v[96:97], v[96:97], v[180:181]
	v_pk_mul_f32 v[98:99], v[98:99], v[182:183]
	v_rcp_f32_e32 v177, v184
	s_nop 0
	v_mul_f32_e32 v177, v179, v177
	s_waitcnt vmcnt(5)
	v_cvt_f32_ubyte2_e32 v181, v172
	v_rcp_f32_e32 v179, v189
	s_nop 0
	v_mul_f32_e32 v176, v176, v179
	v_pk_mul_f32 v[92:93], v[92:93], v[176:177]
	v_rcp_f32_e32 v179, v188
	s_nop 0
	v_mul_f32_e32 v179, v178, v179
	s_waitcnt vmcnt(4)
	v_cvt_f32_ubyte0_e32 v176, v174
	v_rcp_f32_e32 v178, v187
	s_nop 0
	v_mul_f32_e32 v178, v1, v178
	v_pk_mul_f32 v[94:95], v[94:95], v[178:179]
	v_cvt_f32_ubyte2_e32 v1, v174
	v_cvt_f32_ubyte3_e32 v178, v174
	v_cvt_f32_ubyte1_e32 v174, v174
	v_cvt_f32_ubyte1_e32 v177, v172
	v_cvt_f32_ubyte3_e32 v182, v172
	v_cvt_f32_ubyte0_e32 v172, v172
	v_rcp_f32_e32 v179, v177
	s_nop 0
	v_mul_f32_e32 v177, v174, v179
	v_rcp_f32_e32 v174, v172
	s_nop 0
	v_mul_f32_e32 v176, v176, v174
	v_cvt_f32_ubyte0_e32 v185, v173
	v_rcp_f32_e32 v172, v182
	s_nop 0
	v_mul_f32_e32 v179, v178, v172
	v_cvt_f32_ubyte2_e32 v183, v173
	v_rcp_f32_e32 v172, v181
	s_nop 0
	v_mul_f32_e32 v178, v1, v172
	v_cvt_f32_ubyte2_e32 v1, v175
	v_cvt_f32_ubyte3_e32 v174, v175
	v_cvt_f32_ubyte0_e32 v172, v175
	v_cvt_f32_ubyte1_e32 v175, v175
	v_cvt_f32_ubyte1_e32 v180, v173
	v_cvt_f32_ubyte3_e32 v184, v173
	v_pk_mul_f32 v[88:89], v[88:89], v[176:177]
	v_pk_mul_f32 v[90:91], v[90:91], v[178:179]
	v_rcp_f32_e32 v173, v180
	s_nop 0
	v_mul_f32_e32 v173, v175, v173
	s_waitcnt vmcnt(2)
	v_cvt_f32_ubyte2_e32 v177, v168
	v_rcp_f32_e32 v175, v185
	s_nop 0
	v_mul_f32_e32 v172, v172, v175
	v_pk_mul_f32 v[84:85], v[84:85], v[172:173]
	v_rcp_f32_e32 v175, v184
	s_nop 0
	v_mul_f32_e32 v175, v174, v175
	v_cvt_f32_ubyte0_e32 v172, v170
	v_rcp_f32_e32 v174, v183
	s_nop 0
	v_mul_f32_e32 v174, v1, v174
	v_pk_mul_f32 v[86:87], v[86:87], v[174:175]
	v_cvt_f32_ubyte2_e32 v1, v170
	v_cvt_f32_ubyte3_e32 v174, v170
	v_cvt_f32_ubyte1_e32 v170, v170
	v_cvt_f32_ubyte1_e32 v173, v168
	v_cvt_f32_ubyte3_e32 v178, v168
	v_cvt_f32_ubyte0_e32 v168, v168
	v_rcp_f32_e32 v175, v173
	s_nop 0
	v_mul_f32_e32 v173, v170, v175
	v_rcp_f32_e32 v170, v168
	s_nop 0
	v_mul_f32_e32 v172, v172, v170
	v_cvt_f32_ubyte0_e32 v181, v169
	v_rcp_f32_e32 v168, v178
	s_nop 0
	v_mul_f32_e32 v175, v174, v168
	v_cvt_f32_ubyte2_e32 v179, v169
	v_rcp_f32_e32 v168, v177
	s_nop 0
	v_mul_f32_e32 v174, v1, v168
	v_cvt_f32_ubyte2_e32 v1, v171
	v_cvt_f32_ubyte3_e32 v170, v171
	v_cvt_f32_ubyte0_e32 v168, v171
	v_cvt_f32_ubyte1_e32 v171, v171
	v_cvt_f32_ubyte1_e32 v176, v169
	v_cvt_f32_ubyte3_e32 v180, v169
	v_pk_mul_f32 v[80:81], v[80:81], v[172:173]
	v_pk_mul_f32 v[82:83], v[82:83], v[174:175]
	v_rcp_f32_e32 v169, v176
	s_nop 0
	v_mul_f32_e32 v169, v171, v169
	s_waitcnt vmcnt(1)
	v_cvt_f32_ubyte2_e32 v173, v164
	v_rcp_f32_e32 v171, v181
	s_nop 0
	v_mul_f32_e32 v168, v168, v171
	v_pk_mul_f32 v[76:77], v[76:77], v[168:169]
	v_rcp_f32_e32 v171, v180
	s_nop 0
	v_mul_f32_e32 v171, v170, v171
	s_waitcnt vmcnt(0)
	v_cvt_f32_ubyte0_e32 v168, v166
	v_rcp_f32_e32 v170, v179
	s_nop 0
	v_mul_f32_e32 v170, v1, v170
	v_pk_mul_f32 v[78:79], v[78:79], v[170:171]
	v_cvt_f32_ubyte2_e32 v1, v166
	v_cvt_f32_ubyte3_e32 v170, v166
	v_cvt_f32_ubyte1_e32 v166, v166
	v_cvt_f32_ubyte1_e32 v169, v164
	v_cvt_f32_ubyte3_e32 v174, v164
	v_cvt_f32_ubyte0_e32 v164, v164
	v_cvt_f32_ubyte0_e32 v178, v165
	v_rcp_f32_e32 v171, v169
	s_nop 0
	v_mul_f32_e32 v169, v166, v171
	v_rcp_f32_e32 v166, v164
	s_nop 0
	v_mul_f32_e32 v168, v168, v166
	v_cvt_f32_ubyte3_e32 v177, v165
	v_rcp_f32_e32 v164, v174
	s_nop 0
	v_mul_f32_e32 v171, v170, v164
	v_pk_mul_f32 v[72:73], v[72:73], v[168:169]
	v_rcp_f32_e32 v164, v173
	s_nop 0
	v_mul_f32_e32 v170, v1, v164
	v_cvt_f32_ubyte2_e32 v1, v167
	v_cvt_f32_ubyte3_e32 v172, v167
	v_cvt_f32_ubyte0_e32 v166, v167
	v_cvt_f32_ubyte1_e32 v167, v167
	v_cvt_f32_ubyte1_e32 v173, v165
	v_cvt_f32_ubyte2_e32 v176, v165
	v_add_co_u32_e64 v164, s[4:5], s59, v2
	s_nop 0
	v_addc_co_u32_e64 v165, s[4:5], 0, v3, s[4:5]
	global_load_dwordx2 v[190:191], v[164:165], off
	global_load_dwordx2 v[198:199], v[164:165], off offset:2048
	v_rcp_f32_e32 v174, v173
	s_nop 0
	v_mul_f32_e32 v167, v167, v174
	global_load_dwordx2 v[186:187], v[164:165], off offset:2176
	global_load_dwordx2 v[188:189], v[164:165], off offset:128
	v_rcp_f32_e32 v173, v178
	s_nop 0
	v_mul_f32_e32 v166, v166, v173
	v_pk_mul_f32 v[74:75], v[74:75], v[170:171]
	v_rcp_f32_e32 v173, v177
	s_nop 0
	v_mul_f32_e32 v173, v172, v173
	v_pk_mul_f32 v[68:69], v[68:69], v[166:167]
	v_rcp_f32_e32 v172, v176
	s_nop 0
	v_mul_f32_e32 v172, v1, v172
	v_add_co_u32_e32 v164, vcc, s60, v2
	v_pk_mul_f32 v[70:71], v[70:71], v[172:173]
	s_nop 0
	v_addc_co_u32_e32 v165, vcc, 0, v3, vcc
	global_load_dwordx2 v[184:185], v[164:165], off
	global_load_dwordx2 v[182:183], v[164:165], off offset:2048
	global_load_dwordx2 v[178:179], v[164:165], off offset:2176
	global_load_dwordx2 v[180:181], v[164:165], off offset:128
	v_add_co_u32_e32 v164, vcc, s61, v2
	s_waitcnt vmcnt(7)
; __device__ __forceinline__ float ub0(unsigned w) { return (float)(w & 0xffu); }
; __device__ __forceinline__ float ub1(unsigned w) { return (float)((w >> 8) & 0xffu); }
; __device__ __forceinline__ float ub2(unsigned w) { return (float)((w >> 16) & 0xffu); }
; __device__ __forceinline__ float ub3(unsigned w) { return (float)(w >> 24); }
;     __device__ __forceinline__ void mid(f32x4 (&acc)[2][2][4][2], const Unit& u, int wr, int wc, int fr, int fq, int t) const {
;         const int offx = (t == 8) ? 0 : 2048;
;         const unsigned char* gp0 = gates + (size_t)(u.pm * BM + wr * 64 + fr) * GP8 + u.pn * BM + wc * 32 + 8 * fq + offx;
; #pragma unroll
;         for (int ai = 0; ai < 2; ++ai) {
;             u32x2 gx[4][2], gy[4][2];
; #pragma unroll
;             for (int m = 0; m < 4; ++m)
; #pragma unroll
;                 for (int bj = 0; bj < 2; ++bj) { const unsigned char* gp = gp0 + (size_t)(ai * HALF + m * 16) * GP8 + bj * HALF; gx[m][bj] = *(const u32x2*)gp; gy[m][bj] = *(const u32x2*)(gp + 2048); }
; #pragma unroll
;             for (int m = 0; m < 4; ++m)
; #pragma unroll
;                 for (int bj = 0; bj < 2; ++bj) { const u32x2 x = gx[m][bj], y = gy[m][bj];
;                     f32x4 r0, r1;
;                     r0[0] = __fdividef(ub0(x.x), ub0(y.x)); r0[1] = __fdividef(ub1(x.x), ub1(y.x)); r0[2] = __fdividef(ub2(x.x), ub2(y.x)); r0[3] = __fdividef(ub3(x.x), ub3(y.x));
;                     r1[0] = __fdividef(ub0(x.y), ub0(y.y)); r1[1] = __fdividef(ub1(x.y), ub1(y.y)); r1[2] = __fdividef(ub2(x.y), ub2(y.y)); r1[3] = __fdividef(ub3(x.y), ub3(y.y));
;                     acc[ai][bj][m][0] *= r0; acc[ai][bj][m][1] *= r1; }
;             asm volatile("" ::: "memory"); }
	v_cvt_f32_ubyte2_e32 v1, v190
	v_cvt_f32_ubyte3_e32 v202, v190
	v_cvt_f32_ubyte0_e32 v200, v190
	v_cvt_f32_ubyte1_e32 v190, v190
	s_waitcnt vmcnt(6)
	v_cvt_f32_ubyte1_e32 v201, v198
	v_addc_co_u32_e32 v165, vcc, 0, v3, vcc
	global_load_dwordx2 v[176:177], v[164:165], off
	global_load_dwordx2 v[174:175], v[164:165], off offset:2048
	global_load_dwordx2 v[170:171], v[164:165], off offset:2176
	global_load_dwordx2 v[172:173], v[164:165], off offset:128
	v_add_co_u32_e32 v164, vcc, s62, v2
	s_nop 0
	v_addc_co_u32_e32 v165, vcc, 0, v3, vcc
	v_cvt_f32_ubyte2_e32 v205, v198
	v_cvt_f32_ubyte3_e32 v206, v198
	v_cvt_f32_ubyte0_e32 v198, v198
	v_rcp_f32_e32 v203, v201
	s_nop 0
	v_mul_f32_e32 v201, v190, v203
	global_load_dwordx2 v[168:169], v[164:165], off
	global_load_dwordx2 v[166:167], v[164:165], off offset:2048
	global_load_dwordx2 v[2:3], v[164:165], off offset:2176
	s_nop 0
	global_load_dwordx2 v[164:165], v[164:165], off offset:128
	v_rcp_f32_e32 v190, v198
	s_nop 0
	v_mul_f32_e32 v200, v200, v190
	v_pk_mul_f32 v[64:65], v[64:65], v[200:201]
	v_rcp_f32_e32 v190, v206
	s_nop 0
	v_mul_f32_e32 v203, v202, v190
	v_cvt_f32_ubyte2_e32 v207, v199
	v_rcp_f32_e32 v190, v205
	s_nop 0
	v_mul_f32_e32 v202, v1, v190
	v_cvt_f32_ubyte2_e32 v1, v191
	v_cvt_f32_ubyte3_e32 v198, v191
	v_cvt_f32_ubyte0_e32 v190, v191
	v_cvt_f32_ubyte1_e32 v191, v191
	v_cvt_f32_ubyte1_e32 v204, v199
	v_cvt_f32_ubyte3_e32 v208, v199
	v_cvt_f32_ubyte0_e32 v199, v199
	v_pk_mul_f32 v[66:67], v[66:67], v[202:203]
	v_rcp_f32_e32 v205, v204
	s_nop 0
	v_mul_f32_e32 v191, v191, v205
	s_waitcnt vmcnt(13)
	v_cvt_f32_ubyte2_e32 v201, v186
	v_rcp_f32_e32 v204, v199
	s_nop 0
	v_mul_f32_e32 v190, v190, v204
	v_pk_mul_f32 v[60:61], v[60:61], v[190:191]
	v_rcp_f32_e32 v199, v208
	s_nop 0
	v_mul_f32_e32 v199, v198, v199
	s_waitcnt vmcnt(12)
	v_cvt_f32_ubyte0_e32 v190, v188
	v_rcp_f32_e32 v198, v207
	s_nop 0
	v_mul_f32_e32 v198, v1, v198
	v_pk_mul_f32 v[62:63], v[62:63], v[198:199]
	v_cvt_f32_ubyte2_e32 v1, v188
	v_cvt_f32_ubyte3_e32 v198, v188
	v_cvt_f32_ubyte1_e32 v188, v188
	v_cvt_f32_ubyte1_e32 v191, v186
	v_cvt_f32_ubyte3_e32 v202, v186
	v_cvt_f32_ubyte0_e32 v186, v186
	v_rcp_f32_e32 v199, v191
	s_nop 0
	v_mul_f32_e32 v191, v188, v199
	v_rcp_f32_e32 v188, v186
	s_nop 0
	v_mul_f32_e32 v190, v190, v188
	v_cvt_f32_ubyte0_e32 v205, v187
	v_rcp_f32_e32 v186, v202
	s_nop 0
	v_mul_f32_e32 v199, v198, v186
	v_cvt_f32_ubyte2_e32 v203, v187
	v_rcp_f32_e32 v186, v201
	s_nop 0
	v_mul_f32_e32 v198, v1, v186
	v_cvt_f32_ubyte2_e32 v1, v189
	v_cvt_f32_ubyte3_e32 v188, v189
	v_cvt_f32_ubyte0_e32 v186, v189
	v_cvt_f32_ubyte1_e32 v189, v189
	v_cvt_f32_ubyte1_e32 v200, v187
	v_cvt_f32_ubyte3_e32 v204, v187
	v_pk_mul_f32 v[56:57], v[56:57], v[190:191]
	v_pk_mul_f32 v[58:59], v[58:59], v[198:199]
	v_rcp_f32_e32 v187, v200
	s_nop 0
	v_mul_f32_e32 v187, v189, v187
	s_waitcnt vmcnt(10)
	v_cvt_f32_ubyte2_e32 v191, v182
	v_rcp_f32_e32 v189, v205
	s_nop 0
	v_mul_f32_e32 v186, v186, v189
	v_pk_mul_f32 v[52:53], v[52:53], v[186:187]
	v_rcp_f32_e32 v189, v204
	s_nop 0
	v_mul_f32_e32 v189, v188, v189
	v_cvt_f32_ubyte0_e32 v186, v184
	v_rcp_f32_e32 v188, v203
	s_nop 0
	v_mul_f32_e32 v188, v1, v188
	v_pk_mul_f32 v[54:55], v[54:55], v[188:189]
	v_cvt_f32_ubyte2_e32 v1, v184
	v_cvt_f32_ubyte3_e32 v188, v184
	v_cvt_f32_ubyte1_e32 v184, v184
	v_cvt_f32_ubyte1_e32 v187, v182
	v_cvt_f32_ubyte3_e32 v198, v182
	v_cvt_f32_ubyte0_e32 v182, v182
	v_rcp_f32_e32 v189, v187
	s_nop 0
	v_mul_f32_e32 v187, v184, v189
	v_rcp_f32_e32 v184, v182
	s_nop 0
	v_mul_f32_e32 v186, v186, v184
	v_cvt_f32_ubyte0_e32 v201, v183
	v_rcp_f32_e32 v182, v198
	s_nop 0
	v_mul_f32_e32 v189, v188, v182
	v_cvt_f32_ubyte2_e32 v199, v183
	v_rcp_f32_e32 v182, v191
	s_nop 0
	v_mul_f32_e32 v188, v1, v182
	v_cvt_f32_ubyte2_e32 v1, v185
	v_cvt_f32_ubyte3_e32 v184, v185
	v_cvt_f32_ubyte0_e32 v182, v185
	v_cvt_f32_ubyte1_e32 v185, v185
	v_cvt_f32_ubyte1_e32 v190, v183
	v_cvt_f32_ubyte3_e32 v200, v183
	v_pk_mul_f32 v[48:49], v[48:49], v[186:187]
	v_pk_mul_f32 v[50:51], v[50:51], v[188:189]
	v_rcp_f32_e32 v183, v190
	s_nop 0
	v_mul_f32_e32 v183, v185, v183
	s_waitcnt vmcnt(9)
	v_cvt_f32_ubyte2_e32 v187, v178
	v_rcp_f32_e32 v185, v201
	s_nop 0
	v_mul_f32_e32 v182, v182, v185
	v_pk_mul_f32 v[44:45], v[44:45], v[182:183]
	v_rcp_f32_e32 v185, v200
	s_nop 0
	v_mul_f32_e32 v185, v184, v185
	s_waitcnt vmcnt(8)
	v_cvt_f32_ubyte0_e32 v182, v180
	v_rcp_f32_e32 v184, v199
	s_nop 0
	v_mul_f32_e32 v184, v1, v184
	v_pk_mul_f32 v[46:47], v[46:47], v[184:185]
	v_cvt_f32_ubyte2_e32 v1, v180
	v_cvt_f32_ubyte3_e32 v184, v180
	v_cvt_f32_ubyte1_e32 v180, v180
	v_cvt_f32_ubyte1_e32 v183, v178
	v_cvt_f32_ubyte3_e32 v188, v178
	v_cvt_f32_ubyte0_e32 v178, v178
	v_rcp_f32_e32 v185, v183
	s_nop 0
	v_mul_f32_e32 v183, v180, v185
	v_rcp_f32_e32 v180, v178
	s_nop 0
	v_mul_f32_e32 v182, v182, v180
	v_cvt_f32_ubyte0_e32 v191, v179
	v_rcp_f32_e32 v178, v188
	s_nop 0
	v_mul_f32_e32 v185, v184, v178
	v_cvt_f32_ubyte2_e32 v189, v179
	v_rcp_f32_e32 v178, v187
	s_nop 0
	v_mul_f32_e32 v184, v1, v178
	v_cvt_f32_ubyte2_e32 v1, v181
	v_cvt_f32_ubyte3_e32 v180, v181
	v_cvt_f32_ubyte0_e32 v178, v181
	v_cvt_f32_ubyte1_e32 v181, v181
	v_cvt_f32_ubyte1_e32 v186, v179
	v_cvt_f32_ubyte3_e32 v190, v179
	v_pk_mul_f32 v[40:41], v[40:41], v[182:183]
	v_pk_mul_f32 v[42:43], v[42:43], v[184:185]
	v_rcp_f32_e32 v179, v186
	s_nop 0
	v_mul_f32_e32 v179, v181, v179
	s_waitcnt vmcnt(6)
; __device__ __forceinline__ float ub0(unsigned w) { return (float)(w & 0xffu); }
; __device__ __forceinline__ float ub1(unsigned w) { return (float)((w >> 8) & 0xffu); }
; __device__ __forceinline__ float ub2(unsigned w) { return (float)((w >> 16) & 0xffu); }
; __device__ __forceinline__ float ub3(unsigned w) { return (float)(w >> 24); }
;     __device__ __forceinline__ void mid(f32x4 (&acc)[2][2][4][2], const Unit& u, int wr, int wc, int fr, int fq, int t) const {
;         const int offx = (t == 8) ? 0 : 2048;
;         const unsigned char* gp0 = gates + (size_t)(u.pm * BM + wr * 64 + fr) * GP8 + u.pn * BM + wc * 32 + 8 * fq + offx;
; #pragma unroll
;         for (int ai = 0; ai < 2; ++ai) {
;             u32x2 gx[4][2], gy[4][2];
; #pragma unroll
;             for (int m = 0; m < 4; ++m)
; #pragma unroll
;                 for (int bj = 0; bj < 2; ++bj) { const unsigned char* gp = gp0 + (size_t)(ai * HALF + m * 16) * GP8 + bj * HALF; gx[m][bj] = *(const u32x2*)gp; gy[m][bj] = *(const u32x2*)(gp + 2048); }
; #pragma unroll
;             for (int m = 0; m < 4; ++m)
; #pragma unroll
;                 for (int bj = 0; bj < 2; ++bj) { const u32x2 x = gx[m][bj], y = gy[m][bj];
;                     f32x4 r0, r1;
;                     r0[0] = __fdividef(ub0(x.x), ub0(y.x)); r0[1] = __fdividef(ub1(x.x), ub1(y.x)); r0[2] = __fdividef(ub2(x.x), ub2(y.x)); r0[3] = __fdividef(ub3(x.x), ub3(y.x));
;                     r1[0] = __fdividef(ub0(x.y), ub0(y.y)); r1[1] = __fdividef(ub1(x.y), ub1(y.y)); r1[2] = __fdividef(ub2(x.y), ub2(y.y)); r1[3] = __fdividef(ub3(x.y), ub3(y.y));
;                     acc[ai][bj][m][0] *= r0; acc[ai][bj][m][1] *= r1; }
;             asm volatile("" ::: "memory"); }
	v_cvt_f32_ubyte2_e32 v183, v174
	v_rcp_f32_e32 v181, v191
	s_nop 0
	v_mul_f32_e32 v178, v178, v181
	v_pk_mul_f32 v[36:37], v[36:37], v[178:179]
	v_rcp_f32_e32 v181, v190
	s_nop 0
	v_mul_f32_e32 v181, v180, v181
	v_cvt_f32_ubyte0_e32 v178, v176
	v_rcp_f32_e32 v180, v189
	s_nop 0
	v_mul_f32_e32 v180, v1, v180
	v_pk_mul_f32 v[38:39], v[38:39], v[180:181]
	v_cvt_f32_ubyte2_e32 v1, v176
	v_cvt_f32_ubyte3_e32 v180, v176
	v_cvt_f32_ubyte1_e32 v176, v176
	v_cvt_f32_ubyte1_e32 v179, v174
	v_cvt_f32_ubyte3_e32 v184, v174
	v_cvt_f32_ubyte0_e32 v174, v174
	v_rcp_f32_e32 v181, v179
	s_nop 0
	v_mul_f32_e32 v179, v176, v181
	v_rcp_f32_e32 v176, v174
	s_nop 0
	v_mul_f32_e32 v178, v178, v176
	v_cvt_f32_ubyte0_e32 v187, v175
	v_rcp_f32_e32 v174, v184
	s_nop 0
	v_mul_f32_e32 v181, v180, v174
	v_cvt_f32_ubyte2_e32 v185, v175
	v_rcp_f32_e32 v174, v183
	s_nop 0
	v_mul_f32_e32 v180, v1, v174
	v_cvt_f32_ubyte2_e32 v1, v177
	v_cvt_f32_ubyte3_e32 v176, v177
	v_cvt_f32_ubyte0_e32 v174, v177
	v_cvt_f32_ubyte1_e32 v177, v177
	v_cvt_f32_ubyte1_e32 v182, v175
	v_cvt_f32_ubyte3_e32 v186, v175
	v_pk_mul_f32 v[32:33], v[32:33], v[178:179]
	v_pk_mul_f32 v[34:35], v[34:35], v[180:181]
	v_rcp_f32_e32 v175, v182
	s_nop 0
	v_mul_f32_e32 v175, v177, v175
	s_waitcnt vmcnt(5)
	v_cvt_f32_ubyte2_e32 v179, v170
	v_rcp_f32_e32 v177, v187
	s_nop 0
	v_mul_f32_e32 v174, v174, v177
	v_pk_mul_f32 v[28:29], v[28:29], v[174:175]
	v_rcp_f32_e32 v177, v186
	s_nop 0
	v_mul_f32_e32 v177, v176, v177
	s_waitcnt vmcnt(4)
	v_cvt_f32_ubyte0_e32 v174, v172
	v_rcp_f32_e32 v176, v185
	s_nop 0
	v_mul_f32_e32 v176, v1, v176
	v_pk_mul_f32 v[30:31], v[30:31], v[176:177]
	v_cvt_f32_ubyte2_e32 v1, v172
	v_cvt_f32_ubyte3_e32 v176, v172
	v_cvt_f32_ubyte1_e32 v172, v172
	v_cvt_f32_ubyte1_e32 v175, v170
	v_cvt_f32_ubyte3_e32 v180, v170
	v_cvt_f32_ubyte0_e32 v170, v170
	v_rcp_f32_e32 v177, v175
	s_nop 0
	v_mul_f32_e32 v175, v172, v177
	v_rcp_f32_e32 v172, v170
	s_nop 0
	v_mul_f32_e32 v174, v174, v172
	v_cvt_f32_ubyte0_e32 v183, v171
	v_rcp_f32_e32 v170, v180
	s_nop 0
	v_mul_f32_e32 v177, v176, v170
	v_cvt_f32_ubyte2_e32 v181, v171
	v_rcp_f32_e32 v170, v179
	s_nop 0
	v_mul_f32_e32 v176, v1, v170
	v_cvt_f32_ubyte2_e32 v1, v173
	v_cvt_f32_ubyte3_e32 v172, v173
	v_cvt_f32_ubyte0_e32 v170, v173
	v_cvt_f32_ubyte1_e32 v173, v173
	v_cvt_f32_ubyte1_e32 v178, v171
	v_cvt_f32_ubyte3_e32 v182, v171
	v_pk_mul_f32 v[24:25], v[24:25], v[174:175]
	v_pk_mul_f32 v[26:27], v[26:27], v[176:177]
	v_rcp_f32_e32 v171, v178
	s_nop 0
	v_mul_f32_e32 v171, v173, v171
	s_waitcnt vmcnt(2)
	v_cvt_f32_ubyte2_e32 v175, v166
	v_rcp_f32_e32 v173, v183
	s_nop 0
	v_mul_f32_e32 v170, v170, v173
	v_pk_mul_f32 v[20:21], v[20:21], v[170:171]
	v_rcp_f32_e32 v173, v182
	s_nop 0
	v_mul_f32_e32 v173, v172, v173
	v_cvt_f32_ubyte0_e32 v170, v168
	v_rcp_f32_e32 v172, v181
	s_nop 0
	v_mul_f32_e32 v172, v1, v172
	v_pk_mul_f32 v[22:23], v[22:23], v[172:173]
	v_cvt_f32_ubyte2_e32 v1, v168
	v_cvt_f32_ubyte3_e32 v172, v168
	v_cvt_f32_ubyte1_e32 v168, v168
	v_cvt_f32_ubyte1_e32 v171, v166
	v_cvt_f32_ubyte3_e32 v176, v166
	v_cvt_f32_ubyte0_e32 v166, v166
	v_rcp_f32_e32 v173, v171
	s_nop 0
	v_mul_f32_e32 v171, v168, v173
	v_rcp_f32_e32 v168, v166
	s_nop 0
	v_mul_f32_e32 v170, v170, v168
	v_cvt_f32_ubyte0_e32 v179, v167
	v_rcp_f32_e32 v166, v176
	s_nop 0
	v_mul_f32_e32 v173, v172, v166
	v_cvt_f32_ubyte2_e32 v177, v167
	v_rcp_f32_e32 v166, v175
	s_nop 0
	v_mul_f32_e32 v172, v1, v166
	v_cvt_f32_ubyte2_e32 v1, v169
	v_cvt_f32_ubyte3_e32 v168, v169
	v_cvt_f32_ubyte0_e32 v166, v169
	v_cvt_f32_ubyte1_e32 v169, v169
	v_cvt_f32_ubyte1_e32 v174, v167
	v_cvt_f32_ubyte3_e32 v178, v167
	v_pk_mul_f32 v[16:17], v[16:17], v[170:171]
	v_pk_mul_f32 v[18:19], v[18:19], v[172:173]
	v_rcp_f32_e32 v167, v174
	s_nop 0
	v_mul_f32_e32 v167, v169, v167
	s_waitcnt vmcnt(1)
	v_cvt_f32_ubyte2_e32 v171, v2
	v_rcp_f32_e32 v169, v179
	s_nop 0
	v_mul_f32_e32 v166, v166, v169
	v_pk_mul_f32 v[12:13], v[12:13], v[166:167]
	v_rcp_f32_e32 v169, v178
	s_nop 0
	v_mul_f32_e32 v169, v168, v169
	s_waitcnt vmcnt(0)
	v_cvt_f32_ubyte0_e32 v166, v164
	v_rcp_f32_e32 v168, v177
	s_nop 0
	v_mul_f32_e32 v168, v1, v168
	v_pk_mul_f32 v[14:15], v[14:15], v[168:169]
	v_cvt_f32_ubyte2_e32 v1, v164
	v_cvt_f32_ubyte3_e32 v168, v164
	v_cvt_f32_ubyte1_e32 v164, v164
	v_cvt_f32_ubyte1_e32 v167, v2
	v_cvt_f32_ubyte3_e32 v172, v2
	v_cvt_f32_ubyte0_e32 v2, v2
	v_rcp_f32_e32 v169, v167
	s_nop 0
	v_mul_f32_e32 v167, v164, v169
	v_rcp_f32_e32 v164, v2
	s_nop 0
	v_mul_f32_e32 v166, v166, v164
	v_cvt_f32_ubyte0_e32 v175, v3
	v_rcp_f32_e32 v2, v172
	s_nop 0
	v_mul_f32_e32 v169, v168, v2
	v_cvt_f32_ubyte2_e32 v173, v3
	v_rcp_f32_e32 v2, v171
	s_nop 0
	v_mul_f32_e32 v168, v1, v2
	v_cvt_f32_ubyte2_e32 v1, v165
	v_cvt_f32_ubyte3_e32 v164, v165
	v_cvt_f32_ubyte0_e32 v2, v165
	v_cvt_f32_ubyte1_e32 v165, v165
	v_cvt_f32_ubyte1_e32 v170, v3
	v_cvt_f32_ubyte3_e32 v174, v3
	v_pk_mul_f32 v[10:11], v[10:11], v[168:169]
	v_pk_mul_f32 v[8:9], v[8:9], v[166:167]
	v_rcp_f32_e32 v3, v170
	s_nop 0
	v_mul_f32_e32 v3, v165, v3
	v_rcp_f32_e32 v165, v175
	s_nop 0
	v_mul_f32_e32 v2, v2, v165
	v_pk_mul_f32 v[4:5], v[4:5], v[2:3]
	v_rcp_f32_e32 v165, v174
	s_nop 0
	v_mul_f32_e32 v165, v164, v165
	v_rcp_f32_e32 v164, v173
	s_nop 0
	v_mul_f32_e32 v164, v1, v164
	v_pk_mul_f32 v[6:7], v[6:7], v[164:165]
